# stack: m2a conv load hoist; MLA exact lgkm waits + max3 tree; m5 retention/SSD ds_read prefetch rings + Sprev staging batched loads; barrier XGEN bump before inv; GEMM loop LDS-DMA saddr form
# speedup vs baseline: 1.0105x; 1.0105x over previous
; __device__ __forceinline__ unsigned xb_ld(unsigned* p)              { return __hip_atomic_load(p, __ATOMIC_RELAXED, __HIP_MEMORY_SCOPE_AGENT); }
; __device__ __forceinline__ unsigned xb_add(unsigned* p, unsigned v) { return __hip_atomic_fetch_add(p, v, __ATOMIC_RELAXED, __HIP_MEMORY_SCOPE_AGENT); }
; #define XB_SPIN(cond, bar) do { unsigned _sp = 0; while (cond) { __builtin_amdgcn_s_sleep(1); \
;     if ((++_sp & 255u) == 0u) { if (xb_ld(&(bar)[XB_TMO])) break; if (_sp > XB_SPIN_CAP) { atomicAdd(&(bar)[XB_TMO], 1u); break; } } } } while (0)
; __device__ __forceinline__ void xcd_barrier(const XcdBarrier& b) {
;     ...
;             __builtin_amdgcn_fence(__ATOMIC_RELEASE, "agent");
;             asm volatile("s_waitcnt vmcnt(0)" ::: "memory");
;             const unsigned og = xb_add(&bar[XB_TOP], 1u);
;             const unsigned tg = og / nx;
;             if (og + 1u == (tg + 1u) * nx) xb_add(&bar[XB_TOPGEN], 1u);
;             else XB_SPIN(xb_ld(&bar[XB_TOPGEN]) == tg, bar);
;             __builtin_amdgcn_fence(__ATOMIC_ACQUIRE, "agent");
;             xb_add(&bar[XB_XGEN(b.x)], 1u);
;             asm volatile("s_waitcnt vmcnt(0)" ::: "memory");
.LBB0_12:
	s_or_b64 exec, exec, s[4:5]
	s_waitcnt vmcnt(0)
	global_atomic_add v225, v197, s[2:3] offset:1024
	buffer_inv sc1
	s_waitcnt vmcnt(0)

;     __device__ bool next(int i, Unit& u) const { Unit b; if (!so.next(i / 3, b)) return false; const int br = i % 3; u.pm = br * 64 + b.pm; u.pn = br * 8 + b.pn; return true; }
; #define PG8_STAGE(bufoff, gbase, voff) do { _Pragma("unroll") for (int _i = 0; _i < 2; ++_i) \
;         __builtin_amdgcn_global_load_lds((const unsigned*)((const char*)(gbase) + (voff)[_i]), (LAS unsigned*)(lds + (bufoff) + ldsw + _i * 8192), 16, 0, 0); } while (0)
; #define PG8_LDA(dst, b, h) do { _Pragma("unroll") for (int m = 0; m < 4; ++m) _Pragma("unroll") for (int k = 0; k < 2; ++k) dst[m][k] = *(const LAS bf16x8*)(lds + PG8_SA(b, h) + aoff + m * 2048 + k * 1024); } while (0)
; #define PG8_LDB(dst, b, h) do { _Pragma("unroll") for (int n = 0; n < 2; ++n) _Pragma("unroll") for (int k = 0; k < 2; ++k) dst[n][k] = *(const LAS bf16x8*)(lds + PG8_SB(b, h) + boff + n * 2048 + k * 1024); } while (0)
; #define PG8_WAIT_V(n) asm volatile("s_waitcnt vmcnt(" #n ")" ::: "memory")
; #define PG8_WAIT_L(n) asm volatile("s_waitcnt lgkmcnt(" #n ")" ::: "memory")
; #define PG8_BAR __builtin_amdgcn_s_barrier()
; template <class Epi, class Sched>
; __device__ __forceinline__ void gemm_phase(const int tid, LAS unsigned char* lds, const Gemm g, const Sched& S, const Epi& E) {
;     ...
;         const bool has_next = S.next(ui + 1, nxt);
;         const char* nA = has_next ? (const char*)g.A + (size_t)nxt.pm * tstepA : cA; const char* nB = has_next ? (const char*)g.Bt + (size_t)nxt.pn * tstepB : cB;
;         for (int t = 0; t < nt; t += 2) {
;             const bool last = (t == nt - 2);
;             const char* a1 = cA + (size_t)(t + 1) * kstepA;
;             const char* a2 = last ? nA : cA + (size_t)(t + 2) * kstepA; const char* b2 = last ? nB : cB + (size_t)(t + 2) * kstepB;
;             const char* a3 = a2 + kstepA; const char* b3 = b2 + kstepB;
;             PG8_LDB(B0, 0, 0); PG8_LDB(B1, 0, 1); PG8_SCHED; PG8_LDA(At, 0, 0); PG8_STAGE(PG8_SA(1, 1), a1 + hstepA, voffA);
;             PG8_WAIT_V(8); PG8_WAIT_L(0); PG8_BAR; PG8_MMA(0, 0, At, B0); PG8_MMA(0, 1, At, B1); PG8_BAR; PG8_SCHED;
;             PG8_LDA(At, 0, 1); PG8_STAGE(PG8_SB(0, 0), b2, voffB); PG8_STAGE(PG8_SB(0, 1), b2 + hstepB, voffB); PG8_STAGE(PG8_SA(0, 0), a2, voffA);
;             PG8_WAIT_V(8); PG8_WAIT_L(0); PG8_BAR; PG8_MMA(1, 0, At, B0); PG8_MMA(1, 1, At, B1); PG8_BAR; PG8_SCHED;
.LBB0_135:
	s_add_u32 s24, s6, 0x4000
	s_addc_u32 s25, s7, 0
	s_cmp_eq_u32 s66, 28
	s_cselect_b32 s28, s19, s24
	s_cselect_b32 s29, s13, s25
	s_cselect_b32 s26, s63, s64
	s_cselect_b32 s27, s17, s65
	s_add_u32 s24, s28, 0x8000
	s_addc_u32 s25, s29, 0
	s_add_i32 s67, 16, 0x10000
	s_add_i32 s78, 16, 0x14000
	s_waitcnt vmcnt(0)
	v_add_u32_e32 v78, s67, v180
	v_add_u32_e32 v178, s78, v180
	ds_read_b128 v[58:61], v78
	ds_read_b128 v[62:65], v78 offset:1024
	ds_read_b128 v[74:77], v78 offset:2048
	ds_read_b128 v[78:81], v78 offset:3072
	ds_read_b128 v[174:177], v178
	ds_read_b128 v[182:185], v178 offset:1024
	ds_read_b128 v[186:189], v178 offset:2048
	ds_read_b128 v[190:193], v178 offset:3072
	s_add_i32 m0, s15, 0xc000
	ds_read_b128 v[208:211], v181
	ds_read_b128 v[212:215], v181 offset:1024
	ds_read_b128 v[216:219], v181 offset:2048
	ds_read_b128 v[220:223], v181 offset:3072
	ds_read_b128 v[236:239], v181 offset:4096
	ds_read_b128 v[244:247], v181 offset:5120
	ds_read_b128 v[248:251], v181 offset:6144
	ds_read_b128 v[204:207], v181 offset:7168
	global_load_lds_dwordx4 v172, s[6:7]
	s_add_i32 m0, s15, 0xe000
	s_nop 0
	global_load_lds_dwordx4 v170, s[6:7]
	s_waitcnt vmcnt(8)
	s_waitcnt lgkmcnt(0)
	s_barrier
	s_setprio 1
	s_waitcnt lgkmcnt(0)
	v_mfma_f32_16x16x32_bf16 v[142:145], v[58:61], v[208:211], v[142:145]
	v_mfma_f32_16x16x32_bf16 v[138:141], v[74:77], v[208:211], v[138:141]
	v_mfma_f32_16x16x32_bf16 v[126:129], v[58:61], v[216:219], v[126:129]
	v_mfma_f32_16x16x32_bf16 v[122:125], v[74:77], v[216:219], v[122:125]
	v_mfma_f32_16x16x32_bf16 v[110:113], v[58:61], v[236:239], v[110:113]
	v_mfma_f32_16x16x32_bf16 v[106:109], v[74:77], v[236:239], v[106:109]
	v_mfma_f32_16x16x32_bf16 v[94:97], v[58:61], v[248:251], v[94:97]
	v_mfma_f32_16x16x32_bf16 v[90:93], v[74:77], v[248:251], v[90:93]
	v_mfma_f32_16x16x32_bf16 v[142:145], v[62:65], v[212:215], v[142:145]
	v_mfma_f32_16x16x32_bf16 v[138:141], v[78:81], v[212:215], v[138:141]
	v_mfma_f32_16x16x32_bf16 v[126:129], v[62:65], v[220:223], v[126:129]
	v_mfma_f32_16x16x32_bf16 v[122:125], v[78:81], v[220:223], v[122:125]
	v_mfma_f32_16x16x32_bf16 v[110:113], v[62:65], v[244:247], v[110:113]
	v_mfma_f32_16x16x32_bf16 v[106:109], v[78:81], v[244:247], v[106:109]
	v_mfma_f32_16x16x32_bf16 v[94:97], v[62:65], v[204:207], v[94:97]
	v_mfma_f32_16x16x32_bf16 v[90:93], v[78:81], v[204:207], v[90:93]
	s_setprio 0
	s_setprio 1
	v_mfma_f32_16x16x32_bf16 v[134:137], v[174:177], v[208:211], v[134:137]
	v_mfma_f32_16x16x32_bf16 v[130:133], v[186:189], v[208:211], v[130:133]
	v_mfma_f32_16x16x32_bf16 v[118:121], v[174:177], v[216:219], v[118:121]
	v_mfma_f32_16x16x32_bf16 v[114:117], v[186:189], v[216:219], v[114:117]
	v_mfma_f32_16x16x32_bf16 v[102:105], v[174:177], v[236:239], v[102:105]
	v_mfma_f32_16x16x32_bf16 v[98:101], v[186:189], v[236:239], v[98:101]
	v_mfma_f32_16x16x32_bf16 v[86:89], v[174:177], v[248:251], v[86:89]
	v_mfma_f32_16x16x32_bf16 v[82:85], v[186:189], v[248:251], v[82:85]
	v_mfma_f32_16x16x32_bf16 v[134:137], v[182:185], v[212:215], v[134:137]
	v_mfma_f32_16x16x32_bf16 v[130:133], v[190:193], v[212:215], v[130:133]
	v_mfma_f32_16x16x32_bf16 v[118:121], v[182:185], v[220:223], v[118:121]
	v_mfma_f32_16x16x32_bf16 v[114:117], v[190:193], v[220:223], v[114:117]
	v_mfma_f32_16x16x32_bf16 v[102:105], v[182:185], v[244:247], v[102:105]
	v_mfma_f32_16x16x32_bf16 v[98:101], v[190:193], v[244:247], v[98:101]
	v_mfma_f32_16x16x32_bf16 v[86:89], v[182:185], v[204:207], v[86:89]
	v_mfma_f32_16x16x32_bf16 v[82:85], v[190:193], v[204:207], v[82:85]
	s_setprio 0
	s_barrier
	s_add_i32 s67, s67, s54
	s_mov_b32 m0, s67
	ds_read_b128 v[204:207], v181 offset:16384
	ds_read_b128 v[208:211], v181 offset:17408
	ds_read_b128 v[212:215], v181 offset:18432
	ds_read_b128 v[216:219], v181 offset:19456
	ds_read_b128 v[220:223], v181 offset:20480
	ds_read_b128 v[236:239], v181 offset:21504
	ds_read_b128 v[244:247], v181 offset:22528
	ds_read_b128 v[248:251], v181 offset:23552
	global_load_lds_dwordx4 v0, s[26:27]
	s_add_i32 m0, s67, 0x2000
	s_add_u32 s76, s26, 0x4000
	s_addc_u32 s77, s27, 0
	s_add_i32 s67, s78, s54
	global_load_lds_dwordx4 v150, s[26:27]
	s_mov_b32 m0, s67
	s_nop 0
	global_load_lds_dwordx4 v0, s[76:77]
	s_add_i32 m0, s67, 0x2000
	s_nop 0
	global_load_lds_dwordx4 v150, s[76:77]
	s_mov_b32 m0, s15
	s_nop 0
	global_load_lds_dwordx4 v146, s[28:29]
	v_lshl_add_u64 v[178:179], s[28:29], 0, v[148:149]
	s_mov_b32 m0, s55
	s_nop 0
	global_load_lds_dwordx4 v[178:179], off
	s_waitcnt vmcnt(8)
	s_waitcnt lgkmcnt(0)
	s_barrier
; #define PG8_STAGE(bufoff, gbase, voff) do { _Pragma("unroll") for (int _i = 0; _i < 2; ++_i) \
;         __builtin_amdgcn_global_load_lds((const unsigned*)((const char*)(gbase) + (voff)[_i]), (LAS unsigned*)(lds + (bufoff) + ldsw + _i * 8192), 16, 0, 0); } while (0)
; #define PG8_LDA(dst, b, h) do { _Pragma("unroll") for (int m = 0; m < 4; ++m) _Pragma("unroll") for (int k = 0; k < 2; ++k) dst[m][k] = *(const LAS bf16x8*)(lds + PG8_SA(b, h) + aoff + m * 2048 + k * 1024); } while (0)
; #define PG8_LDB(dst, b, h) do { _Pragma("unroll") for (int n = 0; n < 2; ++n) _Pragma("unroll") for (int k = 0; k < 2; ++k) dst[n][k] = *(const LAS bf16x8*)(lds + PG8_SB(b, h) + boff + n * 2048 + k * 1024); } while (0)
; #define PG8_MMA(ai, bj, At, Bt) do { __builtin_amdgcn_s_setprio(1); _Pragma("unroll") for (int m = 0; m < 4; ++m) _Pragma("unroll") for (int n = 0; n < 2; ++n) _Pragma("unroll") for (int k = 0; k < 2; ++k) \
;         acc[ai][bj][m][n] = __builtin_amdgcn_mfma_f32_16x16x32_bf16(Bt[n][k], At[m][k], acc[ai][bj][m][n], 0, 0, 0); __builtin_amdgcn_s_setprio(0); } while (0)
; #define PG8_WAIT_V(n) asm volatile("s_waitcnt vmcnt(" #n ")" ::: "memory")
; #define PG8_WAIT_L(n) asm volatile("s_waitcnt lgkmcnt(" #n ")" ::: "memory")
; #define PG8_BAR __builtin_amdgcn_s_barrier()
; #define PG8_SCHED __builtin_amdgcn_sched_barrier(0)
; template <class Epi, class Sched>
; __device__ __forceinline__ void gemm_phase(const int tid, LAS unsigned char* lds, const Gemm g, const Sched& S, const Epi& E) {
;     ...
;             PG8_WAIT_V(8); PG8_WAIT_L(0); PG8_BAR; PG8_MMA(1, 0, At, B0); PG8_MMA(1, 1, At, B1); PG8_BAR; PG8_SCHED;
;             PG8_LDB(B0, 1, 0); PG8_LDB(B1, 1, 1); PG8_SCHED; PG8_LDA(At, 1, 0); PG8_STAGE(PG8_SA(0, 1), a2 + hstepA, voffA);
;             PG8_WAIT_V(8); PG8_WAIT_L(0); PG8_BAR; PG8_MMA(0, 0, At, B0); PG8_MMA(0, 1, At, B1); PG8_BAR; PG8_SCHED;
	s_setprio 1
	s_waitcnt lgkmcnt(0)
	v_mfma_f32_16x16x32_bf16 v[70:73], v[58:61], v[204:207], v[70:73]
	v_mfma_f32_16x16x32_bf16 v[66:69], v[74:77], v[204:207], v[66:69]
	v_mfma_f32_16x16x32_bf16 v[46:49], v[58:61], v[212:215], v[46:49]
	v_mfma_f32_16x16x32_bf16 v[42:45], v[74:77], v[212:215], v[42:45]
	v_mfma_f32_16x16x32_bf16 v[30:33], v[58:61], v[220:223], v[30:33]
	v_mfma_f32_16x16x32_bf16 v[26:29], v[74:77], v[220:223], v[26:29]
	v_mfma_f32_16x16x32_bf16 v[14:17], v[58:61], v[244:247], v[14:17]
	v_mfma_f32_16x16x32_bf16 v[10:13], v[74:77], v[244:247], v[10:13]
	v_mfma_f32_16x16x32_bf16 v[70:73], v[62:65], v[208:211], v[70:73]
	v_mfma_f32_16x16x32_bf16 v[66:69], v[78:81], v[208:211], v[66:69]
	v_mfma_f32_16x16x32_bf16 v[46:49], v[62:65], v[216:219], v[46:49]
	v_mfma_f32_16x16x32_bf16 v[42:45], v[78:81], v[216:219], v[42:45]
	v_mfma_f32_16x16x32_bf16 v[30:33], v[62:65], v[236:239], v[30:33]
	v_mfma_f32_16x16x32_bf16 v[26:29], v[78:81], v[236:239], v[26:29]
	v_mfma_f32_16x16x32_bf16 v[14:17], v[62:65], v[248:251], v[14:17]
	v_mfma_f32_16x16x32_bf16 v[10:13], v[78:81], v[248:251], v[10:13]
	s_setprio 0
	s_setprio 1
	v_mfma_f32_16x16x32_bf16 v[54:57], v[174:177], v[204:207], v[54:57]
	v_mfma_f32_16x16x32_bf16 v[50:53], v[186:189], v[204:207], v[50:53]
	v_mfma_f32_16x16x32_bf16 v[38:41], v[174:177], v[212:215], v[38:41]
	v_mfma_f32_16x16x32_bf16 v[34:37], v[186:189], v[212:215], v[34:37]
	v_mfma_f32_16x16x32_bf16 v[22:25], v[174:177], v[220:223], v[22:25]
	v_mfma_f32_16x16x32_bf16 v[18:21], v[186:189], v[220:223], v[18:21]
	v_mfma_f32_16x16x32_bf16 v[6:9], v[174:177], v[244:247], v[6:9]
	v_mfma_f32_16x16x32_bf16 v[2:5], v[186:189], v[244:247], v[2:5]
	v_mfma_f32_16x16x32_bf16 v[54:57], v[182:185], v[208:211], v[54:57]
	v_mfma_f32_16x16x32_bf16 v[50:53], v[190:193], v[208:211], v[50:53]
	v_mfma_f32_16x16x32_bf16 v[38:41], v[182:185], v[216:219], v[38:41]
	v_mfma_f32_16x16x32_bf16 v[34:37], v[190:193], v[216:219], v[34:37]
	v_mfma_f32_16x16x32_bf16 v[22:25], v[182:185], v[236:239], v[22:25]
	v_mfma_f32_16x16x32_bf16 v[18:21], v[190:193], v[236:239], v[18:21]
	v_mfma_f32_16x16x32_bf16 v[6:9], v[182:185], v[248:251], v[6:9]
	v_mfma_f32_16x16x32_bf16 v[2:5], v[190:193], v[248:251], v[2:5]
	s_setprio 0
	s_barrier
	s_add_i32 s67, 16, 0x18000
	s_add_i32 s76, 16, 0x1c000
	v_add_u32_e32 v78, s67, v180
	v_add_u32_e32 v178, s76, v180
	ds_read_b128 v[58:61], v78
	ds_read_b128 v[62:65], v78 offset:1024
	ds_read_b128 v[74:77], v78 offset:2048
	ds_read_b128 v[78:81], v78 offset:3072
	ds_read_b128 v[174:177], v178
	ds_read_b128 v[182:185], v178 offset:1024
	ds_read_b128 v[186:189], v178 offset:2048
	ds_read_b128 v[190:193], v178 offset:3072
	s_add_u32 s28, s28, 0x4000
	s_addc_u32 s29, s29, 0
	s_mov_b32 m0, s56
	ds_read_b128 v[204:207], v181 offset:32768
	ds_read_b128 v[208:211], v181 offset:33792
	ds_read_b128 v[212:215], v181 offset:34816
	ds_read_b128 v[216:219], v181 offset:35840
	ds_read_b128 v[220:223], v181 offset:36864
	ds_read_b128 v[236:239], v181 offset:37888
	ds_read_b128 v[244:247], v181 offset:38912
	ds_read_b128 v[248:251], v181 offset:39936
	global_load_lds_dwordx4 v146, s[28:29]
	s_mov_b32 m0, s57
	s_nop 0
	global_load_lds_dwordx4 v148, s[28:29]
	s_waitcnt vmcnt(8)
	s_waitcnt lgkmcnt(0)
	s_barrier
	s_setprio 1
	s_waitcnt lgkmcnt(0)
	v_mfma_f32_16x16x32_bf16 v[142:145], v[58:61], v[204:207], v[142:145]
	v_mfma_f32_16x16x32_bf16 v[138:141], v[74:77], v[204:207], v[138:141]
	v_mfma_f32_16x16x32_bf16 v[126:129], v[58:61], v[212:215], v[126:129]
	v_mfma_f32_16x16x32_bf16 v[122:125], v[74:77], v[212:215], v[122:125]
	v_mfma_f32_16x16x32_bf16 v[110:113], v[58:61], v[220:223], v[110:113]
	v_mfma_f32_16x16x32_bf16 v[106:109], v[74:77], v[220:223], v[106:109]
	v_mfma_f32_16x16x32_bf16 v[94:97], v[58:61], v[244:247], v[94:97]
	v_mfma_f32_16x16x32_bf16 v[90:93], v[74:77], v[244:247], v[90:93]
	v_mfma_f32_16x16x32_bf16 v[142:145], v[62:65], v[208:211], v[142:145]
	v_mfma_f32_16x16x32_bf16 v[138:141], v[78:81], v[208:211], v[138:141]
	v_mfma_f32_16x16x32_bf16 v[126:129], v[62:65], v[216:219], v[126:129]
	v_mfma_f32_16x16x32_bf16 v[122:125], v[78:81], v[216:219], v[122:125]
	v_mfma_f32_16x16x32_bf16 v[110:113], v[62:65], v[236:239], v[110:113]
	v_mfma_f32_16x16x32_bf16 v[106:109], v[78:81], v[236:239], v[106:109]
	v_mfma_f32_16x16x32_bf16 v[94:97], v[62:65], v[248:251], v[94:97]
	v_mfma_f32_16x16x32_bf16 v[90:93], v[78:81], v[248:251], v[90:93]
	s_setprio 0
	s_setprio 1
	v_mfma_f32_16x16x32_bf16 v[134:137], v[174:177], v[204:207], v[134:137]
	v_mfma_f32_16x16x32_bf16 v[130:133], v[186:189], v[204:207], v[130:133]
	v_mfma_f32_16x16x32_bf16 v[118:121], v[174:177], v[212:215], v[118:121]
	v_mfma_f32_16x16x32_bf16 v[114:117], v[186:189], v[212:215], v[114:117]
	v_mfma_f32_16x16x32_bf16 v[102:105], v[174:177], v[220:223], v[102:105]
	v_mfma_f32_16x16x32_bf16 v[98:101], v[186:189], v[220:223], v[98:101]
	v_mfma_f32_16x16x32_bf16 v[86:89], v[174:177], v[244:247], v[86:89]
	v_mfma_f32_16x16x32_bf16 v[82:85], v[186:189], v[244:247], v[82:85]
	v_mfma_f32_16x16x32_bf16 v[134:137], v[182:185], v[208:211], v[134:137]
	v_mfma_f32_16x16x32_bf16 v[130:133], v[190:193], v[208:211], v[130:133]
	v_mfma_f32_16x16x32_bf16 v[118:121], v[182:185], v[216:219], v[118:121]
	v_mfma_f32_16x16x32_bf16 v[114:117], v[190:193], v[216:219], v[114:117]
	v_mfma_f32_16x16x32_bf16 v[102:105], v[182:185], v[236:239], v[102:105]
	v_mfma_f32_16x16x32_bf16 v[98:101], v[190:193], v[236:239], v[98:101]
	v_mfma_f32_16x16x32_bf16 v[86:89], v[182:185], v[248:251], v[86:89]
	v_mfma_f32_16x16x32_bf16 v[82:85], v[190:193], v[248:251], v[82:85]
	s_setprio 0
	s_barrier
; #define PG8_STAGE(bufoff, gbase, voff) do { _Pragma("unroll") for (int _i = 0; _i < 2; ++_i) \
;         __builtin_amdgcn_global_load_lds((const unsigned*)((const char*)(gbase) + (voff)[_i]), (LAS unsigned*)(lds + (bufoff) + ldsw + _i * 8192), 16, 0, 0); } while (0)
; #define PG8_LDA(dst, b, h) do { _Pragma("unroll") for (int m = 0; m < 4; ++m) _Pragma("unroll") for (int k = 0; k < 2; ++k) dst[m][k] = *(const LAS bf16x8*)(lds + PG8_SA(b, h) + aoff + m * 2048 + k * 1024); } while (0)
; #define PG8_MMA(ai, bj, At, Bt) do { __builtin_amdgcn_s_setprio(1); _Pragma("unroll") for (int m = 0; m < 4; ++m) _Pragma("unroll") for (int n = 0; n < 2; ++n) _Pragma("unroll") for (int k = 0; k < 2; ++k) \
;         acc[ai][bj][m][n] = __builtin_amdgcn_mfma_f32_16x16x32_bf16(Bt[n][k], At[m][k], acc[ai][bj][m][n], 0, 0, 0); __builtin_amdgcn_s_setprio(0); } while (0)
; #define PG8_WAIT_V(n) asm volatile("s_waitcnt vmcnt(" #n ")" ::: "memory")
; #define PG8_WAIT_L(n) asm volatile("s_waitcnt lgkmcnt(" #n ")" ::: "memory")
; #define PG8_BAR __builtin_amdgcn_s_barrier()
; #define PG8_SCHED __builtin_amdgcn_sched_barrier(0)
; template <class Epi, class Sched>
; __device__ __forceinline__ void gemm_phase(const int tid, LAS unsigned char* lds, const Gemm g, const Sched& S, const Epi& E) {
;     ...
;             PG8_LDA(At, 1, 1); PG8_STAGE(PG8_SB(1, 0), b3, voffB); PG8_STAGE(PG8_SB(1, 1), b3 + hstepB, voffB); PG8_STAGE(PG8_SA(1, 0), a3, voffA);
;             PG8_WAIT_V(8); PG8_WAIT_L(0); PG8_BAR; PG8_MMA(1, 0, At, B0); PG8_MMA(1, 1, At, B1); PG8_BAR; PG8_SCHED;
;         }
;         if (wr == 0) PG8_BAR;
	s_add_u32 s28, s26, 0x8000
	s_addc_u32 s29, s27, 0
	s_add_i32 s67, s67, s54
	s_mov_b32 m0, s67
	ds_read_b128 v[204:207], v181 offset:49152
	ds_read_b128 v[208:211], v181 offset:50176
	ds_read_b128 v[212:215], v181 offset:51200
	ds_read_b128 v[216:219], v181 offset:52224
	ds_read_b128 v[220:223], v181 offset:53248
	ds_read_b128 v[236:239], v181 offset:54272
	ds_read_b128 v[244:247], v181 offset:55296
	ds_read_b128 v[248:251], v181 offset:56320
	global_load_lds_dwordx4 v0, s[28:29]
	s_add_i32 m0, s67, 0x2000
	s_add_u32 s26, s26, 0xc000
	s_addc_u32 s27, s27, 0
	global_load_lds_dwordx4 v150, s[28:29]
	s_add_i32 s28, s76, s54
	s_mov_b32 m0, s28
	s_nop 0
	global_load_lds_dwordx4 v0, s[26:27]
	s_add_i32 m0, s28, 0x2000
	s_nop 0
	global_load_lds_dwordx4 v150, s[26:27]
	s_mov_b32 m0, s58
	s_nop 0
	global_load_lds_dwordx4 v146, s[24:25]
	v_lshl_add_u64 v[178:179], s[24:25], 0, v[148:149]
	s_mov_b32 m0, s59
	s_nop 0
	global_load_lds_dwordx4 v[178:179], off
	s_waitcnt vmcnt(8)
	s_waitcnt lgkmcnt(0)
	s_barrier
	s_setprio 1
	s_waitcnt lgkmcnt(0)
	v_mfma_f32_16x16x32_bf16 v[70:73], v[58:61], v[204:207], v[70:73]
	v_mfma_f32_16x16x32_bf16 v[66:69], v[74:77], v[204:207], v[66:69]
	v_mfma_f32_16x16x32_bf16 v[46:49], v[58:61], v[212:215], v[46:49]
	v_mfma_f32_16x16x32_bf16 v[42:45], v[74:77], v[212:215], v[42:45]
	v_mfma_f32_16x16x32_bf16 v[30:33], v[58:61], v[220:223], v[30:33]
	v_mfma_f32_16x16x32_bf16 v[26:29], v[74:77], v[220:223], v[26:29]
	v_mfma_f32_16x16x32_bf16 v[14:17], v[58:61], v[244:247], v[14:17]
	v_mfma_f32_16x16x32_bf16 v[10:13], v[74:77], v[244:247], v[10:13]
	v_mfma_f32_16x16x32_bf16 v[70:73], v[62:65], v[208:211], v[70:73]
	v_mfma_f32_16x16x32_bf16 v[66:69], v[78:81], v[208:211], v[66:69]
	v_mfma_f32_16x16x32_bf16 v[46:49], v[62:65], v[216:219], v[46:49]
	v_mfma_f32_16x16x32_bf16 v[42:45], v[78:81], v[216:219], v[42:45]
	v_mfma_f32_16x16x32_bf16 v[30:33], v[62:65], v[236:239], v[30:33]
	v_mfma_f32_16x16x32_bf16 v[26:29], v[78:81], v[236:239], v[26:29]
	v_mfma_f32_16x16x32_bf16 v[14:17], v[62:65], v[248:251], v[14:17]
	v_mfma_f32_16x16x32_bf16 v[10:13], v[78:81], v[248:251], v[10:13]
	s_setprio 0
	s_setprio 1
	v_mfma_f32_16x16x32_bf16 v[54:57], v[174:177], v[204:207], v[54:57]
	v_mfma_f32_16x16x32_bf16 v[50:53], v[186:189], v[204:207], v[50:53]
	v_mfma_f32_16x16x32_bf16 v[38:41], v[174:177], v[212:215], v[38:41]
	v_mfma_f32_16x16x32_bf16 v[34:37], v[186:189], v[212:215], v[34:37]
	v_mfma_f32_16x16x32_bf16 v[22:25], v[174:177], v[220:223], v[22:25]
	v_mfma_f32_16x16x32_bf16 v[18:21], v[186:189], v[220:223], v[18:21]
	v_mfma_f32_16x16x32_bf16 v[6:9], v[174:177], v[244:247], v[6:9]
	v_mfma_f32_16x16x32_bf16 v[2:5], v[186:189], v[244:247], v[2:5]
	v_mfma_f32_16x16x32_bf16 v[54:57], v[182:185], v[208:211], v[54:57]
	v_mfma_f32_16x16x32_bf16 v[50:53], v[190:193], v[208:211], v[50:53]
	v_mfma_f32_16x16x32_bf16 v[38:41], v[182:185], v[216:219], v[38:41]
	v_mfma_f32_16x16x32_bf16 v[34:37], v[190:193], v[216:219], v[34:37]
	v_mfma_f32_16x16x32_bf16 v[22:25], v[182:185], v[236:239], v[22:25]
	v_mfma_f32_16x16x32_bf16 v[18:21], v[190:193], v[236:239], v[18:21]
	v_mfma_f32_16x16x32_bf16 v[6:9], v[182:185], v[248:251], v[6:9]
	v_mfma_f32_16x16x32_bf16 v[2:5], v[190:193], v[248:251], v[2:5]
	s_setprio 0
	s_barrier
	s_add_i32 s66, s66, 2
	s_add_u32 s64, s64, 0x10000
	s_addc_u32 s65, s65, 0
	s_add_u32 s6, s6, 0x10000
	s_addc_u32 s7, s7, 0
	s_cmp_gt_u32 s66, 29
	s_cbranch_scc0 .LBB0_135
	s_and_b64 vcc, exec, s[10:11]
	s_cbranch_vccz .LBB0_138
	s_barrier

;     __device__ bool next(int i, Unit& u) const { Unit b; if (!so.next(i / 3, b)) return false; const int br = i % 3; u.pm = br * 64 + b.pm; u.pn = br * 8 + b.pn; return true; }
; #define PG8_STAGE(bufoff, gbase, voff) do { _Pragma("unroll") for (int _i = 0; _i < 2; ++_i) \
;         __builtin_amdgcn_global_load_lds((const unsigned*)((const char*)(gbase) + (voff)[_i]), (LAS unsigned*)(lds + (bufoff) + ldsw + _i * 8192), 16, 0, 0); } while (0)
; #define PG8_LDA(dst, b, h) do { _Pragma("unroll") for (int m = 0; m < 4; ++m) _Pragma("unroll") for (int k = 0; k < 2; ++k) dst[m][k] = *(const LAS bf16x8*)(lds + PG8_SA(b, h) + aoff + m * 2048 + k * 1024); } while (0)
; #define PG8_LDB(dst, b, h) do { _Pragma("unroll") for (int n = 0; n < 2; ++n) _Pragma("unroll") for (int k = 0; k < 2; ++k) dst[n][k] = *(const LAS bf16x8*)(lds + PG8_SB(b, h) + boff + n * 2048 + k * 1024); } while (0)
; #define PG8_WAIT_V(n) asm volatile("s_waitcnt vmcnt(" #n ")" ::: "memory")
; #define PG8_WAIT_L(n) asm volatile("s_waitcnt lgkmcnt(" #n ")" ::: "memory")
; #define PG8_BAR __builtin_amdgcn_s_barrier()
; template <class Epi, class Sched>
; __device__ __forceinline__ void gemm_phase(const int tid, LAS unsigned char* lds, const Gemm g, const Sched& S, const Epi& E) {
;     ...
;         const bool has_next = S.next(ui + 1, nxt);
;         const char* nA = has_next ? (const char*)g.A + (size_t)nxt.pm * tstepA : cA; const char* nB = has_next ? (const char*)g.Bt + (size_t)nxt.pn * tstepB : cB;
;         for (int t = 0; t < nt; t += 2) {
;             const bool last = (t == nt - 2);
;             const char* a1 = cA + (size_t)(t + 1) * kstepA;
;             const char* a2 = last ? nA : cA + (size_t)(t + 2) * kstepA; const char* b2 = last ? nB : cB + (size_t)(t + 2) * kstepB;
;             const char* a3 = a2 + kstepA; const char* b3 = b2 + kstepB;
;             PG8_LDB(B0, 0, 0); PG8_LDB(B1, 0, 1); PG8_SCHED; PG8_LDA(At, 0, 0); PG8_STAGE(PG8_SA(1, 1), a1 + hstepA, voffA);
;             PG8_WAIT_V(8); PG8_WAIT_L(0); PG8_BAR; PG8_MMA(0, 0, At, B0); PG8_MMA(0, 1, At, B1); PG8_BAR; PG8_SCHED;
;             PG8_LDA(At, 0, 1); PG8_STAGE(PG8_SB(0, 0), b2, voffB); PG8_STAGE(PG8_SB(0, 1), b2 + hstepB, voffB); PG8_STAGE(PG8_SA(0, 0), a2, voffA);
;             PG8_WAIT_V(8); PG8_WAIT_L(0); PG8_BAR; PG8_MMA(1, 0, At, B0); PG8_MMA(1, 1, At, B1); PG8_BAR; PG8_SCHED;
.LBB0_404:
	s_add_u32 s18, s6, 0xffe00080
	s_addc_u32 s19, s7, -1
	s_add_i32 s61, 16, 0x10000
	s_cmp_eq_u32 s60, 8
	s_cselect_b32 s21, s13, s19
	s_cselect_b32 s20, s57, s18
	s_cselect_b32 s19, s15, s59
	s_cselect_b32 s18, s14, s58
	s_add_i32 s64, 16, 0x14000
	v_add_u32_e32 v156, s61, v141
	v_add_u32_e32 v172, s64, v141
	ds_read_b128 v[144:147], v156
	ds_read_b128 v[148:151], v156 offset:1024
	ds_read_b128 v[152:155], v156 offset:2048
	ds_read_b128 v[156:159], v156 offset:3072
	ds_read_b128 v[160:163], v172
	ds_read_b128 v[164:167], v172 offset:1024
	ds_read_b128 v[168:171], v172 offset:2048
	ds_read_b128 v[172:175], v172 offset:3072
	s_add_i32 m0, s9, 0xc000
	ds_read_b128 v[176:179], v143
	ds_read_b128 v[180:183], v143 offset:1024
	ds_read_b128 v[184:187], v143 offset:2048
	ds_read_b128 v[188:191], v143 offset:3072
	ds_read_b128 v[204:207], v143 offset:4096
	ds_read_b128 v[208:211], v143 offset:5120
	ds_read_b128 v[212:215], v143 offset:6144
	ds_read_b128 v[216:219], v143 offset:7168
	global_load_lds_dwordx4 v138, s[6:7]
	s_add_i32 m0, s9, 0xe000
	s_nop 0
	global_load_lds_dwordx4 v136, s[6:7]
	s_waitcnt vmcnt(8)
	s_waitcnt lgkmcnt(0)
	s_barrier
	s_setprio 1
	s_waitcnt lgkmcnt(0)
	v_mfma_f32_16x16x32_bf16 v[126:129], v[144:147], v[176:179], v[126:129]
	v_mfma_f32_16x16x32_bf16 v[122:125], v[152:155], v[176:179], v[122:125]
	v_mfma_f32_16x16x32_bf16 v[118:121], v[144:147], v[184:187], v[118:121]
	v_mfma_f32_16x16x32_bf16 v[114:117], v[152:155], v[184:187], v[114:117]
	v_mfma_f32_16x16x32_bf16 v[102:105], v[144:147], v[204:207], v[102:105]
	v_mfma_f32_16x16x32_bf16 v[98:101], v[152:155], v[204:207], v[98:101]
	v_mfma_f32_16x16x32_bf16 v[86:89], v[144:147], v[212:215], v[86:89]
	v_mfma_f32_16x16x32_bf16 v[82:85], v[152:155], v[212:215], v[82:85]
	v_mfma_f32_16x16x32_bf16 v[126:129], v[148:151], v[180:183], v[126:129]
	v_mfma_f32_16x16x32_bf16 v[122:125], v[156:159], v[180:183], v[122:125]
	v_mfma_f32_16x16x32_bf16 v[118:121], v[148:151], v[188:191], v[118:121]
	v_mfma_f32_16x16x32_bf16 v[114:117], v[156:159], v[188:191], v[114:117]
	v_mfma_f32_16x16x32_bf16 v[102:105], v[148:151], v[208:211], v[102:105]
	v_mfma_f32_16x16x32_bf16 v[98:101], v[156:159], v[208:211], v[98:101]
	v_mfma_f32_16x16x32_bf16 v[86:89], v[148:151], v[216:219], v[86:89]
	v_mfma_f32_16x16x32_bf16 v[82:85], v[156:159], v[216:219], v[82:85]
	s_setprio 0
	s_setprio 1
	v_mfma_f32_16x16x32_bf16 v[110:113], v[160:163], v[176:179], v[110:113]
	v_mfma_f32_16x16x32_bf16 v[106:109], v[168:171], v[176:179], v[106:109]
	v_mfma_f32_16x16x32_bf16 v[94:97], v[160:163], v[184:187], v[94:97]
	v_mfma_f32_16x16x32_bf16 v[90:93], v[168:171], v[184:187], v[90:93]
	v_mfma_f32_16x16x32_bf16 v[78:81], v[160:163], v[204:207], v[78:81]
	v_mfma_f32_16x16x32_bf16 v[74:77], v[168:171], v[204:207], v[74:77]
	v_mfma_f32_16x16x32_bf16 v[70:73], v[160:163], v[212:215], v[70:73]
	v_mfma_f32_16x16x32_bf16 v[66:69], v[168:171], v[212:215], v[66:69]
	v_mfma_f32_16x16x32_bf16 v[110:113], v[164:167], v[180:183], v[110:113]
	v_mfma_f32_16x16x32_bf16 v[106:109], v[172:175], v[180:183], v[106:109]
	v_mfma_f32_16x16x32_bf16 v[94:97], v[164:167], v[188:191], v[94:97]
	v_mfma_f32_16x16x32_bf16 v[90:93], v[172:175], v[188:191], v[90:93]
	v_mfma_f32_16x16x32_bf16 v[78:81], v[164:167], v[208:211], v[78:81]
	v_mfma_f32_16x16x32_bf16 v[74:77], v[172:175], v[208:211], v[74:77]
	v_mfma_f32_16x16x32_bf16 v[70:73], v[164:167], v[216:219], v[70:73]
	v_mfma_f32_16x16x32_bf16 v[66:69], v[172:175], v[216:219], v[66:69]
	s_setprio 0
	s_barrier
	s_add_i32 s61, s61, s28
	s_mov_b32 m0, s61
	ds_read_b128 v[176:179], v143 offset:16384
	ds_read_b128 v[180:183], v143 offset:17408
	ds_read_b128 v[184:187], v143 offset:18432
	ds_read_b128 v[188:191], v143 offset:19456
	ds_read_b128 v[204:207], v143 offset:20480
	ds_read_b128 v[208:211], v143 offset:21504
	ds_read_b128 v[212:215], v143 offset:22528
	ds_read_b128 v[216:219], v143 offset:23552
	global_load_lds_dwordx4 v134, s[18:19]
	s_add_i32 m0, s61, 0x2000
	s_add_u32 s62, s18, 0x4000
	s_addc_u32 s63, s19, 0
	s_add_i32 s61, s64, s28
	global_load_lds_dwordx4 v130, s[18:19]
	s_mov_b32 m0, s61
	v_lshl_add_u64 v[220:221], s[20:21], 0, v[132:133]
	global_load_lds_dwordx4 v134, s[62:63]
	s_add_i32 m0, s61, 0x2000
	s_nop 0
	global_load_lds_dwordx4 v130, s[62:63]
	v_lshl_add_u64 v[192:193], s[20:21], 0, v[0:1]
	s_mov_b32 m0, s9
	s_nop 0
	global_load_lds_dwordx4 v[192:193], off
	s_mov_b32 m0, s30
	s_nop 0
	global_load_lds_dwordx4 v[220:221], off
	s_waitcnt vmcnt(8)
	s_waitcnt lgkmcnt(0)
	s_barrier
; #define PG8_STAGE(bufoff, gbase, voff) do { _Pragma("unroll") for (int _i = 0; _i < 2; ++_i) \
;         __builtin_amdgcn_global_load_lds((const unsigned*)((const char*)(gbase) + (voff)[_i]), (LAS unsigned*)(lds + (bufoff) + ldsw + _i * 8192), 16, 0, 0); } while (0)
; #define PG8_LDA(dst, b, h) do { _Pragma("unroll") for (int m = 0; m < 4; ++m) _Pragma("unroll") for (int k = 0; k < 2; ++k) dst[m][k] = *(const LAS bf16x8*)(lds + PG8_SA(b, h) + aoff + m * 2048 + k * 1024); } while (0)
; #define PG8_LDB(dst, b, h) do { _Pragma("unroll") for (int n = 0; n < 2; ++n) _Pragma("unroll") for (int k = 0; k < 2; ++k) dst[n][k] = *(const LAS bf16x8*)(lds + PG8_SB(b, h) + boff + n * 2048 + k * 1024); } while (0)
; #define PG8_MMA(ai, bj, At, Bt) do { __builtin_amdgcn_s_setprio(1); _Pragma("unroll") for (int m = 0; m < 4; ++m) _Pragma("unroll") for (int n = 0; n < 2; ++n) _Pragma("unroll") for (int k = 0; k < 2; ++k) \
;         acc[ai][bj][m][n] = __builtin_amdgcn_mfma_f32_16x16x32_bf16(Bt[n][k], At[m][k], acc[ai][bj][m][n], 0, 0, 0); __builtin_amdgcn_s_setprio(0); } while (0)
; #define PG8_WAIT_V(n) asm volatile("s_waitcnt vmcnt(" #n ")" ::: "memory")
; #define PG8_WAIT_L(n) asm volatile("s_waitcnt lgkmcnt(" #n ")" ::: "memory")
; #define PG8_BAR __builtin_amdgcn_s_barrier()
; #define PG8_SCHED __builtin_amdgcn_sched_barrier(0)
; template <class Epi, class Sched>
; __device__ __forceinline__ void gemm_phase(const int tid, LAS unsigned char* lds, const Gemm g, const Sched& S, const Epi& E) {
;     ...
;             PG8_WAIT_V(8); PG8_WAIT_L(0); PG8_BAR; PG8_MMA(1, 0, At, B0); PG8_MMA(1, 1, At, B1); PG8_BAR; PG8_SCHED;
;             PG8_LDB(B0, 1, 0); PG8_LDB(B1, 1, 1); PG8_SCHED; PG8_LDA(At, 1, 0); PG8_STAGE(PG8_SA(0, 1), a2 + hstepA, voffA);
;             PG8_WAIT_V(8); PG8_WAIT_L(0); PG8_BAR; PG8_MMA(0, 0, At, B0); PG8_MMA(0, 1, At, B1); PG8_BAR; PG8_SCHED;
	s_setprio 1
	s_waitcnt lgkmcnt(0)
	v_mfma_f32_16x16x32_bf16 v[62:65], v[144:147], v[176:179], v[62:65]
	v_mfma_f32_16x16x32_bf16 v[58:61], v[152:155], v[176:179], v[58:61]
	v_mfma_f32_16x16x32_bf16 v[54:57], v[144:147], v[184:187], v[54:57]
	v_mfma_f32_16x16x32_bf16 v[50:53], v[152:155], v[184:187], v[50:53]
	v_mfma_f32_16x16x32_bf16 v[38:41], v[144:147], v[204:207], v[38:41]
	v_mfma_f32_16x16x32_bf16 v[34:37], v[152:155], v[204:207], v[34:37]
	v_mfma_f32_16x16x32_bf16 v[22:25], v[144:147], v[212:215], v[22:25]
	v_mfma_f32_16x16x32_bf16 v[18:21], v[152:155], v[212:215], v[18:21]
	v_mfma_f32_16x16x32_bf16 v[62:65], v[148:151], v[180:183], v[62:65]
	v_mfma_f32_16x16x32_bf16 v[58:61], v[156:159], v[180:183], v[58:61]
	v_mfma_f32_16x16x32_bf16 v[54:57], v[148:151], v[188:191], v[54:57]
	v_mfma_f32_16x16x32_bf16 v[50:53], v[156:159], v[188:191], v[50:53]
	v_mfma_f32_16x16x32_bf16 v[38:41], v[148:151], v[208:211], v[38:41]
	v_mfma_f32_16x16x32_bf16 v[34:37], v[156:159], v[208:211], v[34:37]
	v_mfma_f32_16x16x32_bf16 v[22:25], v[148:151], v[216:219], v[22:25]
	v_mfma_f32_16x16x32_bf16 v[18:21], v[156:159], v[216:219], v[18:21]
	s_setprio 0
	s_setprio 1
	v_mfma_f32_16x16x32_bf16 v[46:49], v[160:163], v[176:179], v[46:49]
	v_mfma_f32_16x16x32_bf16 v[42:45], v[168:171], v[176:179], v[42:45]
	v_mfma_f32_16x16x32_bf16 v[30:33], v[160:163], v[184:187], v[30:33]
	v_mfma_f32_16x16x32_bf16 v[26:29], v[168:171], v[184:187], v[26:29]
	v_mfma_f32_16x16x32_bf16 v[14:17], v[160:163], v[204:207], v[14:17]
	v_mfma_f32_16x16x32_bf16 v[10:13], v[168:171], v[204:207], v[10:13]
	v_mfma_f32_16x16x32_bf16 v[6:9], v[160:163], v[212:215], v[6:9]
	v_mfma_f32_16x16x32_bf16 v[2:5], v[168:171], v[212:215], v[2:5]
	v_mfma_f32_16x16x32_bf16 v[46:49], v[164:167], v[180:183], v[46:49]
	v_mfma_f32_16x16x32_bf16 v[42:45], v[172:175], v[180:183], v[42:45]
	v_mfma_f32_16x16x32_bf16 v[30:33], v[164:167], v[188:191], v[30:33]
	v_mfma_f32_16x16x32_bf16 v[26:29], v[172:175], v[188:191], v[26:29]
	v_mfma_f32_16x16x32_bf16 v[14:17], v[164:167], v[208:211], v[14:17]
	v_mfma_f32_16x16x32_bf16 v[10:13], v[172:175], v[208:211], v[10:13]
	v_mfma_f32_16x16x32_bf16 v[6:9], v[164:167], v[216:219], v[6:9]
	v_mfma_f32_16x16x32_bf16 v[2:5], v[172:175], v[216:219], v[2:5]
	s_setprio 0
	s_barrier
	s_add_i32 s61, 16, 0x18000
	s_add_i32 s62, 16, 0x1c000
	v_add_u32_e32 v156, s61, v141
	v_add_u32_e32 v172, s62, v141
	ds_read_b128 v[144:147], v156
	ds_read_b128 v[148:151], v156 offset:1024
	ds_read_b128 v[152:155], v156 offset:2048
	ds_read_b128 v[156:159], v156 offset:3072
	ds_read_b128 v[160:163], v172
	ds_read_b128 v[164:167], v172 offset:1024
	ds_read_b128 v[168:171], v172 offset:2048
	ds_read_b128 v[172:175], v172 offset:3072
	s_add_u32 s20, s20, 0x200000
	s_addc_u32 s21, s21, 0
	s_mov_b32 m0, s31
	ds_read_b128 v[176:179], v143 offset:32768
	ds_read_b128 v[180:183], v143 offset:33792
	ds_read_b128 v[184:187], v143 offset:34816
	ds_read_b128 v[188:191], v143 offset:35840
	ds_read_b128 v[204:207], v143 offset:36864
	ds_read_b128 v[208:211], v143 offset:37888
	ds_read_b128 v[212:215], v143 offset:38912
	ds_read_b128 v[216:219], v143 offset:39936
	global_load_lds_dwordx4 v0, s[20:21]
	s_mov_b32 m0, s34
	s_nop 0
	global_load_lds_dwordx4 v132, s[20:21]
	s_waitcnt vmcnt(8)
	s_waitcnt lgkmcnt(0)
	s_barrier
	s_setprio 1
	s_waitcnt lgkmcnt(0)
	v_mfma_f32_16x16x32_bf16 v[126:129], v[144:147], v[176:179], v[126:129]
	v_mfma_f32_16x16x32_bf16 v[122:125], v[152:155], v[176:179], v[122:125]
	v_mfma_f32_16x16x32_bf16 v[118:121], v[144:147], v[184:187], v[118:121]
	v_mfma_f32_16x16x32_bf16 v[114:117], v[152:155], v[184:187], v[114:117]
	v_mfma_f32_16x16x32_bf16 v[102:105], v[144:147], v[204:207], v[102:105]
	v_mfma_f32_16x16x32_bf16 v[98:101], v[152:155], v[204:207], v[98:101]
	v_mfma_f32_16x16x32_bf16 v[86:89], v[144:147], v[212:215], v[86:89]
	v_mfma_f32_16x16x32_bf16 v[82:85], v[152:155], v[212:215], v[82:85]
	v_mfma_f32_16x16x32_bf16 v[126:129], v[148:151], v[180:183], v[126:129]
	v_mfma_f32_16x16x32_bf16 v[122:125], v[156:159], v[180:183], v[122:125]
	v_mfma_f32_16x16x32_bf16 v[118:121], v[148:151], v[188:191], v[118:121]
	v_mfma_f32_16x16x32_bf16 v[114:117], v[156:159], v[188:191], v[114:117]
	v_mfma_f32_16x16x32_bf16 v[102:105], v[148:151], v[208:211], v[102:105]
	v_mfma_f32_16x16x32_bf16 v[98:101], v[156:159], v[208:211], v[98:101]
	v_mfma_f32_16x16x32_bf16 v[86:89], v[148:151], v[216:219], v[86:89]
	v_mfma_f32_16x16x32_bf16 v[82:85], v[156:159], v[216:219], v[82:85]
	s_setprio 0
	s_setprio 1
	v_mfma_f32_16x16x32_bf16 v[110:113], v[160:163], v[176:179], v[110:113]
	v_mfma_f32_16x16x32_bf16 v[106:109], v[168:171], v[176:179], v[106:109]
	v_mfma_f32_16x16x32_bf16 v[94:97], v[160:163], v[184:187], v[94:97]
	v_mfma_f32_16x16x32_bf16 v[90:93], v[168:171], v[184:187], v[90:93]
	v_mfma_f32_16x16x32_bf16 v[78:81], v[160:163], v[204:207], v[78:81]
	v_mfma_f32_16x16x32_bf16 v[74:77], v[168:171], v[204:207], v[74:77]
	v_mfma_f32_16x16x32_bf16 v[70:73], v[160:163], v[212:215], v[70:73]
	v_mfma_f32_16x16x32_bf16 v[66:69], v[168:171], v[212:215], v[66:69]
	v_mfma_f32_16x16x32_bf16 v[110:113], v[164:167], v[180:183], v[110:113]
	v_mfma_f32_16x16x32_bf16 v[106:109], v[172:175], v[180:183], v[106:109]
	v_mfma_f32_16x16x32_bf16 v[94:97], v[164:167], v[188:191], v[94:97]
	v_mfma_f32_16x16x32_bf16 v[90:93], v[172:175], v[188:191], v[90:93]
	v_mfma_f32_16x16x32_bf16 v[78:81], v[164:167], v[208:211], v[78:81]
	v_mfma_f32_16x16x32_bf16 v[74:77], v[172:175], v[208:211], v[74:77]
	v_mfma_f32_16x16x32_bf16 v[70:73], v[164:167], v[216:219], v[70:73]
	v_mfma_f32_16x16x32_bf16 v[66:69], v[172:175], v[216:219], v[66:69]
	s_setprio 0
	s_barrier
; #define PG8_STAGE(bufoff, gbase, voff) do { _Pragma("unroll") for (int _i = 0; _i < 2; ++_i) \
;         __builtin_amdgcn_global_load_lds((const unsigned*)((const char*)(gbase) + (voff)[_i]), (LAS unsigned*)(lds + (bufoff) + ldsw + _i * 8192), 16, 0, 0); } while (0)
; #define PG8_LDA(dst, b, h) do { _Pragma("unroll") for (int m = 0; m < 4; ++m) _Pragma("unroll") for (int k = 0; k < 2; ++k) dst[m][k] = *(const LAS bf16x8*)(lds + PG8_SA(b, h) + aoff + m * 2048 + k * 1024); } while (0)
; #define PG8_MMA(ai, bj, At, Bt) do { __builtin_amdgcn_s_setprio(1); _Pragma("unroll") for (int m = 0; m < 4; ++m) _Pragma("unroll") for (int n = 0; n < 2; ++n) _Pragma("unroll") for (int k = 0; k < 2; ++k) \
;         acc[ai][bj][m][n] = __builtin_amdgcn_mfma_f32_16x16x32_bf16(Bt[n][k], At[m][k], acc[ai][bj][m][n], 0, 0, 0); __builtin_amdgcn_s_setprio(0); } while (0)
; #define PG8_WAIT_V(n) asm volatile("s_waitcnt vmcnt(" #n ")" ::: "memory")
; #define PG8_WAIT_L(n) asm volatile("s_waitcnt lgkmcnt(" #n ")" ::: "memory")
; #define PG8_BAR __builtin_amdgcn_s_barrier()
; #define PG8_SCHED __builtin_amdgcn_sched_barrier(0)
; template <class Epi, class Sched>
; __device__ __forceinline__ void gemm_phase(const int tid, LAS unsigned char* lds, const Gemm g, const Sched& S, const Epi& E) {
;     ...
;             PG8_LDA(At, 1, 1); PG8_STAGE(PG8_SB(1, 0), b3, voffB); PG8_STAGE(PG8_SB(1, 1), b3 + hstepB, voffB); PG8_STAGE(PG8_SA(1, 0), a3, voffA);
;             PG8_WAIT_V(8); PG8_WAIT_L(0); PG8_BAR; PG8_MMA(1, 0, At, B0); PG8_MMA(1, 1, At, B1); PG8_BAR; PG8_SCHED;
;         }
;         if (wr == 0) PG8_BAR;
	s_add_u32 s20, s18, 0x8000
	s_addc_u32 s21, s19, 0
	s_add_i32 s61, s61, s28
	s_mov_b32 m0, s61
	ds_read_b128 v[176:179], v143 offset:49152
	ds_read_b128 v[180:183], v143 offset:50176
	ds_read_b128 v[184:187], v143 offset:51200
	ds_read_b128 v[188:191], v143 offset:52224
	ds_read_b128 v[204:207], v143 offset:53248
	ds_read_b128 v[208:211], v143 offset:54272
	ds_read_b128 v[212:215], v143 offset:55296
	ds_read_b128 v[216:219], v143 offset:56320
	global_load_lds_dwordx4 v134, s[20:21]
	s_add_i32 m0, s61, 0x2000
	s_add_u32 s18, s18, 0xc000
	s_addc_u32 s19, s19, 0
	global_load_lds_dwordx4 v130, s[20:21]
	s_add_i32 s20, s62, s28
	s_mov_b32 m0, s20
	v_lshl_add_u64 v[192:193], v[192:193], 0, s[88:89]
	global_load_lds_dwordx4 v134, s[18:19]
	s_add_i32 m0, s20, 0x2000
	s_nop 0
	global_load_lds_dwordx4 v130, s[18:19]
	s_mov_b32 m0, s35
	s_nop 0
	global_load_lds_dwordx4 v[192:193], off
	v_lshl_add_u64 v[192:193], v[220:221], 0, s[88:89]
	s_mov_b32 m0, s52
	s_nop 0
	global_load_lds_dwordx4 v[192:193], off
	s_waitcnt vmcnt(8)
	s_waitcnt lgkmcnt(0)
	s_barrier
	s_setprio 1
	s_waitcnt lgkmcnt(0)
	v_mfma_f32_16x16x32_bf16 v[62:65], v[144:147], v[176:179], v[62:65]
	v_mfma_f32_16x16x32_bf16 v[58:61], v[152:155], v[176:179], v[58:61]
	v_mfma_f32_16x16x32_bf16 v[54:57], v[144:147], v[184:187], v[54:57]
	v_mfma_f32_16x16x32_bf16 v[50:53], v[152:155], v[184:187], v[50:53]
	v_mfma_f32_16x16x32_bf16 v[38:41], v[144:147], v[204:207], v[38:41]
	v_mfma_f32_16x16x32_bf16 v[34:37], v[152:155], v[204:207], v[34:37]
	v_mfma_f32_16x16x32_bf16 v[22:25], v[144:147], v[212:215], v[22:25]
	v_mfma_f32_16x16x32_bf16 v[18:21], v[152:155], v[212:215], v[18:21]
	v_mfma_f32_16x16x32_bf16 v[62:65], v[148:151], v[180:183], v[62:65]
	v_mfma_f32_16x16x32_bf16 v[58:61], v[156:159], v[180:183], v[58:61]
	v_mfma_f32_16x16x32_bf16 v[54:57], v[148:151], v[188:191], v[54:57]
	v_mfma_f32_16x16x32_bf16 v[50:53], v[156:159], v[188:191], v[50:53]
	v_mfma_f32_16x16x32_bf16 v[38:41], v[148:151], v[208:211], v[38:41]
	v_mfma_f32_16x16x32_bf16 v[34:37], v[156:159], v[208:211], v[34:37]
	v_mfma_f32_16x16x32_bf16 v[22:25], v[148:151], v[216:219], v[22:25]
	v_mfma_f32_16x16x32_bf16 v[18:21], v[156:159], v[216:219], v[18:21]
	s_setprio 0
	s_setprio 1
	v_mfma_f32_16x16x32_bf16 v[46:49], v[160:163], v[176:179], v[46:49]
	v_mfma_f32_16x16x32_bf16 v[42:45], v[168:171], v[176:179], v[42:45]
	v_mfma_f32_16x16x32_bf16 v[30:33], v[160:163], v[184:187], v[30:33]
	v_mfma_f32_16x16x32_bf16 v[26:29], v[168:171], v[184:187], v[26:29]
	v_mfma_f32_16x16x32_bf16 v[14:17], v[160:163], v[204:207], v[14:17]
	v_mfma_f32_16x16x32_bf16 v[10:13], v[168:171], v[204:207], v[10:13]
	v_mfma_f32_16x16x32_bf16 v[6:9], v[160:163], v[212:215], v[6:9]
	v_mfma_f32_16x16x32_bf16 v[2:5], v[168:171], v[212:215], v[2:5]
	v_mfma_f32_16x16x32_bf16 v[46:49], v[164:167], v[180:183], v[46:49]
	v_mfma_f32_16x16x32_bf16 v[42:45], v[172:175], v[180:183], v[42:45]
	v_mfma_f32_16x16x32_bf16 v[30:33], v[164:167], v[188:191], v[30:33]
	v_mfma_f32_16x16x32_bf16 v[26:29], v[172:175], v[188:191], v[26:29]
	v_mfma_f32_16x16x32_bf16 v[14:17], v[164:167], v[208:211], v[14:17]
	v_mfma_f32_16x16x32_bf16 v[10:13], v[172:175], v[208:211], v[10:13]
	v_mfma_f32_16x16x32_bf16 v[6:9], v[164:167], v[216:219], v[6:9]
	v_mfma_f32_16x16x32_bf16 v[2:5], v[172:175], v[216:219], v[2:5]
	s_setprio 0
	s_barrier
	s_add_i32 s60, s60, 2
	s_add_u32 s58, s58, 0x10000
	s_addc_u32 s59, s59, 0
	s_add_u32 s6, s6, 0x100
	s_addc_u32 s7, s7, 0
	s_cmp_gt_u32 s60, 9
	s_cbranch_scc0 .LBB0_404
	s_and_b64 vcc, exec, s[10:11]
	s_cbranch_vccz .LBB0_407
	s_barrier

;     __device__ bool next(int i, Unit& u) const { Unit b; if (!so.next(i / 3, b)) return false; const int br = i % 3; u.pm = br * 64 + b.pm; u.pn = br * 8 + b.pn; return true; }
; #define PG8_STAGE(bufoff, gbase, voff) do { _Pragma("unroll") for (int _i = 0; _i < 2; ++_i) \
;         __builtin_amdgcn_global_load_lds((const unsigned*)((const char*)(gbase) + (voff)[_i]), (LAS unsigned*)(lds + (bufoff) + ldsw + _i * 8192), 16, 0, 0); } while (0)
; #define PG8_LDA(dst, b, h) do { _Pragma("unroll") for (int m = 0; m < 4; ++m) _Pragma("unroll") for (int k = 0; k < 2; ++k) dst[m][k] = *(const LAS bf16x8*)(lds + PG8_SA(b, h) + aoff + m * 2048 + k * 1024); } while (0)
; #define PG8_LDB(dst, b, h) do { _Pragma("unroll") for (int n = 0; n < 2; ++n) _Pragma("unroll") for (int k = 0; k < 2; ++k) dst[n][k] = *(const LAS bf16x8*)(lds + PG8_SB(b, h) + boff + n * 2048 + k * 1024); } while (0)
; #define PG8_WAIT_V(n) asm volatile("s_waitcnt vmcnt(" #n ")" ::: "memory")
; #define PG8_WAIT_L(n) asm volatile("s_waitcnt lgkmcnt(" #n ")" ::: "memory")
; #define PG8_BAR __builtin_amdgcn_s_barrier()
; template <class Epi, class Sched>
; __device__ __forceinline__ void gemm_phase(const int tid, LAS unsigned char* lds, const Gemm g, const Sched& S, const Epi& E) {
;     ...
;         const bool has_next = S.next(ui + 1, nxt);
;         const char* nA = has_next ? (const char*)g.A + (size_t)nxt.pm * tstepA : cA; const char* nB = has_next ? (const char*)g.Bt + (size_t)nxt.pn * tstepB : cB;
;         for (int t = 0; t < nt; t += 2) {
;             const bool last = (t == nt - 2);
;             const char* a1 = cA + (size_t)(t + 1) * kstepA;
;             const char* a2 = last ? nA : cA + (size_t)(t + 2) * kstepA; const char* b2 = last ? nB : cB + (size_t)(t + 2) * kstepB;
;             const char* a3 = a2 + kstepA; const char* b3 = b2 + kstepB;
;             PG8_LDB(B0, 0, 0); PG8_LDB(B1, 0, 1); PG8_SCHED; PG8_LDA(At, 0, 0); PG8_STAGE(PG8_SA(1, 1), a1 + hstepA, voffA);
;             PG8_WAIT_V(8); PG8_WAIT_L(0); PG8_BAR; PG8_MMA(0, 0, At, B0); PG8_MMA(0, 1, At, B1); PG8_BAR; PG8_SCHED;
;             PG8_LDA(At, 0, 1); PG8_STAGE(PG8_SB(0, 0), b2, voffB); PG8_STAGE(PG8_SB(0, 1), b2 + hstepB, voffB); PG8_STAGE(PG8_SA(0, 0), a2, voffA);
;             PG8_WAIT_V(8); PG8_WAIT_L(0); PG8_BAR; PG8_MMA(1, 0, At, B0); PG8_MMA(1, 1, At, B1); PG8_BAR; PG8_SCHED;
.LBB0_428:
	s_add_u32 s20, s18, 0xffe00080
	s_addc_u32 s21, s19, -1
	s_add_i32 s63, 16, 0x10000
	s_cmp_eq_u32 s62, 4
	s_cselect_b32 s23, s13, s21
	s_cselect_b32 s22, s58, s20
	s_cselect_b32 s21, s11, s61
	s_cselect_b32 s20, s59, s60
	s_add_i32 s66, 16, 0x14000
	v_add_u32_e32 v156, s63, v141
	v_add_u32_e32 v172, s66, v141
	ds_read_b128 v[144:147], v156
	ds_read_b128 v[148:151], v156 offset:1024
	ds_read_b128 v[152:155], v156 offset:2048
	ds_read_b128 v[156:159], v156 offset:3072
	ds_read_b128 v[160:163], v172
	ds_read_b128 v[164:167], v172 offset:1024
	ds_read_b128 v[168:171], v172 offset:2048
	ds_read_b128 v[172:175], v172 offset:3072
	s_add_i32 m0, s9, 0xc000
	ds_read_b128 v[176:179], v143
	ds_read_b128 v[180:183], v143 offset:1024
	ds_read_b128 v[184:187], v143 offset:2048
	ds_read_b128 v[188:191], v143 offset:3072
	ds_read_b128 v[204:207], v143 offset:4096
	ds_read_b128 v[208:211], v143 offset:5120
	ds_read_b128 v[212:215], v143 offset:6144
	ds_read_b128 v[216:219], v143 offset:7168
	global_load_lds_dwordx4 v138, s[18:19]
	s_add_i32 m0, s9, 0xe000
	s_nop 0
	global_load_lds_dwordx4 v136, s[18:19]
	s_waitcnt vmcnt(8)
	s_waitcnt lgkmcnt(0)
	s_barrier
	s_setprio 1
	s_waitcnt lgkmcnt(0)
	v_mfma_f32_16x16x32_bf16 v[126:129], v[144:147], v[176:179], v[126:129]
	v_mfma_f32_16x16x32_bf16 v[122:125], v[152:155], v[176:179], v[122:125]
	v_mfma_f32_16x16x32_bf16 v[118:121], v[144:147], v[184:187], v[118:121]
	v_mfma_f32_16x16x32_bf16 v[114:117], v[152:155], v[184:187], v[114:117]
	v_mfma_f32_16x16x32_bf16 v[102:105], v[144:147], v[204:207], v[102:105]
	v_mfma_f32_16x16x32_bf16 v[98:101], v[152:155], v[204:207], v[98:101]
	v_mfma_f32_16x16x32_bf16 v[86:89], v[144:147], v[212:215], v[86:89]
	v_mfma_f32_16x16x32_bf16 v[82:85], v[152:155], v[212:215], v[82:85]
	v_mfma_f32_16x16x32_bf16 v[126:129], v[148:151], v[180:183], v[126:129]
	v_mfma_f32_16x16x32_bf16 v[122:125], v[156:159], v[180:183], v[122:125]
	v_mfma_f32_16x16x32_bf16 v[118:121], v[148:151], v[188:191], v[118:121]
	v_mfma_f32_16x16x32_bf16 v[114:117], v[156:159], v[188:191], v[114:117]
	v_mfma_f32_16x16x32_bf16 v[102:105], v[148:151], v[208:211], v[102:105]
	v_mfma_f32_16x16x32_bf16 v[98:101], v[156:159], v[208:211], v[98:101]
	v_mfma_f32_16x16x32_bf16 v[86:89], v[148:151], v[216:219], v[86:89]
	v_mfma_f32_16x16x32_bf16 v[82:85], v[156:159], v[216:219], v[82:85]
	s_setprio 0
	s_setprio 1
	v_mfma_f32_16x16x32_bf16 v[110:113], v[160:163], v[176:179], v[110:113]
	v_mfma_f32_16x16x32_bf16 v[106:109], v[168:171], v[176:179], v[106:109]
	v_mfma_f32_16x16x32_bf16 v[94:97], v[160:163], v[184:187], v[94:97]
	v_mfma_f32_16x16x32_bf16 v[90:93], v[168:171], v[184:187], v[90:93]
	v_mfma_f32_16x16x32_bf16 v[78:81], v[160:163], v[204:207], v[78:81]
	v_mfma_f32_16x16x32_bf16 v[74:77], v[168:171], v[204:207], v[74:77]
	v_mfma_f32_16x16x32_bf16 v[70:73], v[160:163], v[212:215], v[70:73]
	v_mfma_f32_16x16x32_bf16 v[66:69], v[168:171], v[212:215], v[66:69]
	v_mfma_f32_16x16x32_bf16 v[110:113], v[164:167], v[180:183], v[110:113]
	v_mfma_f32_16x16x32_bf16 v[106:109], v[172:175], v[180:183], v[106:109]
	v_mfma_f32_16x16x32_bf16 v[94:97], v[164:167], v[188:191], v[94:97]
	v_mfma_f32_16x16x32_bf16 v[90:93], v[172:175], v[188:191], v[90:93]
	v_mfma_f32_16x16x32_bf16 v[78:81], v[164:167], v[208:211], v[78:81]
	v_mfma_f32_16x16x32_bf16 v[74:77], v[172:175], v[208:211], v[74:77]
	v_mfma_f32_16x16x32_bf16 v[70:73], v[164:167], v[216:219], v[70:73]
	v_mfma_f32_16x16x32_bf16 v[66:69], v[172:175], v[216:219], v[66:69]
	s_setprio 0
	s_barrier
	s_add_i32 s63, s63, s31
	s_mov_b32 m0, s63
	ds_read_b128 v[176:179], v143 offset:16384
	ds_read_b128 v[180:183], v143 offset:17408
	ds_read_b128 v[184:187], v143 offset:18432
	ds_read_b128 v[188:191], v143 offset:19456
	ds_read_b128 v[204:207], v143 offset:20480
	ds_read_b128 v[208:211], v143 offset:21504
	ds_read_b128 v[212:215], v143 offset:22528
	ds_read_b128 v[216:219], v143 offset:23552
	global_load_lds_dwordx4 v130, s[20:21]
	s_add_i32 m0, s63, 0x2000
	s_add_u32 s64, s20, 0x4000
	s_addc_u32 s65, s21, 0
	s_add_i32 s63, s66, s31
	global_load_lds_dwordx4 v134, s[20:21]
	s_mov_b32 m0, s63
	v_lshl_add_u64 v[220:221], s[22:23], 0, v[132:133]
	global_load_lds_dwordx4 v130, s[64:65]
	s_add_i32 m0, s63, 0x2000
	s_nop 0
	global_load_lds_dwordx4 v134, s[64:65]
	v_lshl_add_u64 v[192:193], s[22:23], 0, v[0:1]
	s_mov_b32 m0, s9
	s_nop 0
	global_load_lds_dwordx4 v[192:193], off
	s_mov_b32 m0, s34
	s_nop 0
	global_load_lds_dwordx4 v[220:221], off
	s_waitcnt vmcnt(8)
	s_waitcnt lgkmcnt(0)
	s_barrier
; #define PG8_STAGE(bufoff, gbase, voff) do { _Pragma("unroll") for (int _i = 0; _i < 2; ++_i) \
;         __builtin_amdgcn_global_load_lds((const unsigned*)((const char*)(gbase) + (voff)[_i]), (LAS unsigned*)(lds + (bufoff) + ldsw + _i * 8192), 16, 0, 0); } while (0)
; #define PG8_LDA(dst, b, h) do { _Pragma("unroll") for (int m = 0; m < 4; ++m) _Pragma("unroll") for (int k = 0; k < 2; ++k) dst[m][k] = *(const LAS bf16x8*)(lds + PG8_SA(b, h) + aoff + m * 2048 + k * 1024); } while (0)
; #define PG8_LDB(dst, b, h) do { _Pragma("unroll") for (int n = 0; n < 2; ++n) _Pragma("unroll") for (int k = 0; k < 2; ++k) dst[n][k] = *(const LAS bf16x8*)(lds + PG8_SB(b, h) + boff + n * 2048 + k * 1024); } while (0)
; #define PG8_MMA(ai, bj, At, Bt) do { __builtin_amdgcn_s_setprio(1); _Pragma("unroll") for (int m = 0; m < 4; ++m) _Pragma("unroll") for (int n = 0; n < 2; ++n) _Pragma("unroll") for (int k = 0; k < 2; ++k) \
;         acc[ai][bj][m][n] = __builtin_amdgcn_mfma_f32_16x16x32_bf16(Bt[n][k], At[m][k], acc[ai][bj][m][n], 0, 0, 0); __builtin_amdgcn_s_setprio(0); } while (0)
; #define PG8_WAIT_V(n) asm volatile("s_waitcnt vmcnt(" #n ")" ::: "memory")
; #define PG8_WAIT_L(n) asm volatile("s_waitcnt lgkmcnt(" #n ")" ::: "memory")
; #define PG8_BAR __builtin_amdgcn_s_barrier()
; #define PG8_SCHED __builtin_amdgcn_sched_barrier(0)
; template <class Epi, class Sched>
; __device__ __forceinline__ void gemm_phase(const int tid, LAS unsigned char* lds, const Gemm g, const Sched& S, const Epi& E) {
;     ...
;             PG8_WAIT_V(8); PG8_WAIT_L(0); PG8_BAR; PG8_MMA(1, 0, At, B0); PG8_MMA(1, 1, At, B1); PG8_BAR; PG8_SCHED;
;             PG8_LDB(B0, 1, 0); PG8_LDB(B1, 1, 1); PG8_SCHED; PG8_LDA(At, 1, 0); PG8_STAGE(PG8_SA(0, 1), a2 + hstepA, voffA);
;             PG8_WAIT_V(8); PG8_WAIT_L(0); PG8_BAR; PG8_MMA(0, 0, At, B0); PG8_MMA(0, 1, At, B1); PG8_BAR; PG8_SCHED;
	s_setprio 1
	s_waitcnt lgkmcnt(0)
	v_mfma_f32_16x16x32_bf16 v[62:65], v[144:147], v[176:179], v[62:65]
	v_mfma_f32_16x16x32_bf16 v[58:61], v[152:155], v[176:179], v[58:61]
	v_mfma_f32_16x16x32_bf16 v[54:57], v[144:147], v[184:187], v[54:57]
	v_mfma_f32_16x16x32_bf16 v[50:53], v[152:155], v[184:187], v[50:53]
	v_mfma_f32_16x16x32_bf16 v[38:41], v[144:147], v[204:207], v[38:41]
	v_mfma_f32_16x16x32_bf16 v[34:37], v[152:155], v[204:207], v[34:37]
	v_mfma_f32_16x16x32_bf16 v[22:25], v[144:147], v[212:215], v[22:25]
	v_mfma_f32_16x16x32_bf16 v[18:21], v[152:155], v[212:215], v[18:21]
	v_mfma_f32_16x16x32_bf16 v[62:65], v[148:151], v[180:183], v[62:65]
	v_mfma_f32_16x16x32_bf16 v[58:61], v[156:159], v[180:183], v[58:61]
	v_mfma_f32_16x16x32_bf16 v[54:57], v[148:151], v[188:191], v[54:57]
	v_mfma_f32_16x16x32_bf16 v[50:53], v[156:159], v[188:191], v[50:53]
	v_mfma_f32_16x16x32_bf16 v[38:41], v[148:151], v[208:211], v[38:41]
	v_mfma_f32_16x16x32_bf16 v[34:37], v[156:159], v[208:211], v[34:37]
	v_mfma_f32_16x16x32_bf16 v[22:25], v[148:151], v[216:219], v[22:25]
	v_mfma_f32_16x16x32_bf16 v[18:21], v[156:159], v[216:219], v[18:21]
	s_setprio 0
	s_setprio 1
	v_mfma_f32_16x16x32_bf16 v[46:49], v[160:163], v[176:179], v[46:49]
	v_mfma_f32_16x16x32_bf16 v[42:45], v[168:171], v[176:179], v[42:45]
	v_mfma_f32_16x16x32_bf16 v[30:33], v[160:163], v[184:187], v[30:33]
	v_mfma_f32_16x16x32_bf16 v[26:29], v[168:171], v[184:187], v[26:29]
	v_mfma_f32_16x16x32_bf16 v[14:17], v[160:163], v[204:207], v[14:17]
	v_mfma_f32_16x16x32_bf16 v[10:13], v[168:171], v[204:207], v[10:13]
	v_mfma_f32_16x16x32_bf16 v[6:9], v[160:163], v[212:215], v[6:9]
	v_mfma_f32_16x16x32_bf16 v[2:5], v[168:171], v[212:215], v[2:5]
	v_mfma_f32_16x16x32_bf16 v[46:49], v[164:167], v[180:183], v[46:49]
	v_mfma_f32_16x16x32_bf16 v[42:45], v[172:175], v[180:183], v[42:45]
	v_mfma_f32_16x16x32_bf16 v[30:33], v[164:167], v[188:191], v[30:33]
	v_mfma_f32_16x16x32_bf16 v[26:29], v[172:175], v[188:191], v[26:29]
	v_mfma_f32_16x16x32_bf16 v[14:17], v[164:167], v[208:211], v[14:17]
	v_mfma_f32_16x16x32_bf16 v[10:13], v[172:175], v[208:211], v[10:13]
	v_mfma_f32_16x16x32_bf16 v[6:9], v[164:167], v[216:219], v[6:9]
	v_mfma_f32_16x16x32_bf16 v[2:5], v[172:175], v[216:219], v[2:5]
	s_setprio 0
	s_barrier
	s_add_i32 s63, 16, 0x18000
	s_add_i32 s64, 16, 0x1c000
	v_add_u32_e32 v156, s63, v141
	v_add_u32_e32 v172, s64, v141
	ds_read_b128 v[144:147], v156
	ds_read_b128 v[148:151], v156 offset:1024
	ds_read_b128 v[152:155], v156 offset:2048
	ds_read_b128 v[156:159], v156 offset:3072
	ds_read_b128 v[160:163], v172
	ds_read_b128 v[164:167], v172 offset:1024
	ds_read_b128 v[168:171], v172 offset:2048
	ds_read_b128 v[172:175], v172 offset:3072
	s_add_u32 s22, s22, 0x200000
	s_addc_u32 s23, s23, 0
	s_mov_b32 m0, s35
	ds_read_b128 v[176:179], v143 offset:32768
	ds_read_b128 v[180:183], v143 offset:33792
	ds_read_b128 v[184:187], v143 offset:34816
	ds_read_b128 v[188:191], v143 offset:35840
	ds_read_b128 v[204:207], v143 offset:36864
	ds_read_b128 v[208:211], v143 offset:37888
	ds_read_b128 v[212:215], v143 offset:38912
	ds_read_b128 v[216:219], v143 offset:39936
	global_load_lds_dwordx4 v0, s[22:23]
	s_mov_b32 m0, s52
	s_nop 0
	global_load_lds_dwordx4 v132, s[22:23]
	s_waitcnt vmcnt(8)
	s_waitcnt lgkmcnt(0)
	s_barrier
	s_setprio 1
	s_waitcnt lgkmcnt(0)
	v_mfma_f32_16x16x32_bf16 v[126:129], v[144:147], v[176:179], v[126:129]
	v_mfma_f32_16x16x32_bf16 v[122:125], v[152:155], v[176:179], v[122:125]
	v_mfma_f32_16x16x32_bf16 v[118:121], v[144:147], v[184:187], v[118:121]
	v_mfma_f32_16x16x32_bf16 v[114:117], v[152:155], v[184:187], v[114:117]
	v_mfma_f32_16x16x32_bf16 v[102:105], v[144:147], v[204:207], v[102:105]
	v_mfma_f32_16x16x32_bf16 v[98:101], v[152:155], v[204:207], v[98:101]
	v_mfma_f32_16x16x32_bf16 v[86:89], v[144:147], v[212:215], v[86:89]
	v_mfma_f32_16x16x32_bf16 v[82:85], v[152:155], v[212:215], v[82:85]
	v_mfma_f32_16x16x32_bf16 v[126:129], v[148:151], v[180:183], v[126:129]
	v_mfma_f32_16x16x32_bf16 v[122:125], v[156:159], v[180:183], v[122:125]
	v_mfma_f32_16x16x32_bf16 v[118:121], v[148:151], v[188:191], v[118:121]
	v_mfma_f32_16x16x32_bf16 v[114:117], v[156:159], v[188:191], v[114:117]
	v_mfma_f32_16x16x32_bf16 v[102:105], v[148:151], v[208:211], v[102:105]
	v_mfma_f32_16x16x32_bf16 v[98:101], v[156:159], v[208:211], v[98:101]
	v_mfma_f32_16x16x32_bf16 v[86:89], v[148:151], v[216:219], v[86:89]
	v_mfma_f32_16x16x32_bf16 v[82:85], v[156:159], v[216:219], v[82:85]
	s_setprio 0
	s_setprio 1
	v_mfma_f32_16x16x32_bf16 v[110:113], v[160:163], v[176:179], v[110:113]
	v_mfma_f32_16x16x32_bf16 v[106:109], v[168:171], v[176:179], v[106:109]
	v_mfma_f32_16x16x32_bf16 v[94:97], v[160:163], v[184:187], v[94:97]
	v_mfma_f32_16x16x32_bf16 v[90:93], v[168:171], v[184:187], v[90:93]
	v_mfma_f32_16x16x32_bf16 v[78:81], v[160:163], v[204:207], v[78:81]
	v_mfma_f32_16x16x32_bf16 v[74:77], v[168:171], v[204:207], v[74:77]
	v_mfma_f32_16x16x32_bf16 v[70:73], v[160:163], v[212:215], v[70:73]
	v_mfma_f32_16x16x32_bf16 v[66:69], v[168:171], v[212:215], v[66:69]
	v_mfma_f32_16x16x32_bf16 v[110:113], v[164:167], v[180:183], v[110:113]
	v_mfma_f32_16x16x32_bf16 v[106:109], v[172:175], v[180:183], v[106:109]
	v_mfma_f32_16x16x32_bf16 v[94:97], v[164:167], v[188:191], v[94:97]
	v_mfma_f32_16x16x32_bf16 v[90:93], v[172:175], v[188:191], v[90:93]
	v_mfma_f32_16x16x32_bf16 v[78:81], v[164:167], v[208:211], v[78:81]
	v_mfma_f32_16x16x32_bf16 v[74:77], v[172:175], v[208:211], v[74:77]
	v_mfma_f32_16x16x32_bf16 v[70:73], v[164:167], v[216:219], v[70:73]
	v_mfma_f32_16x16x32_bf16 v[66:69], v[172:175], v[216:219], v[66:69]
	s_setprio 0
	s_barrier
; #define PG8_STAGE(bufoff, gbase, voff) do { _Pragma("unroll") for (int _i = 0; _i < 2; ++_i) \
;         __builtin_amdgcn_global_load_lds((const unsigned*)((const char*)(gbase) + (voff)[_i]), (LAS unsigned*)(lds + (bufoff) + ldsw + _i * 8192), 16, 0, 0); } while (0)
; #define PG8_LDA(dst, b, h) do { _Pragma("unroll") for (int m = 0; m < 4; ++m) _Pragma("unroll") for (int k = 0; k < 2; ++k) dst[m][k] = *(const LAS bf16x8*)(lds + PG8_SA(b, h) + aoff + m * 2048 + k * 1024); } while (0)
; #define PG8_MMA(ai, bj, At, Bt) do { __builtin_amdgcn_s_setprio(1); _Pragma("unroll") for (int m = 0; m < 4; ++m) _Pragma("unroll") for (int n = 0; n < 2; ++n) _Pragma("unroll") for (int k = 0; k < 2; ++k) \
;         acc[ai][bj][m][n] = __builtin_amdgcn_mfma_f32_16x16x32_bf16(Bt[n][k], At[m][k], acc[ai][bj][m][n], 0, 0, 0); __builtin_amdgcn_s_setprio(0); } while (0)
; #define PG8_WAIT_V(n) asm volatile("s_waitcnt vmcnt(" #n ")" ::: "memory")
; #define PG8_WAIT_L(n) asm volatile("s_waitcnt lgkmcnt(" #n ")" ::: "memory")
; #define PG8_BAR __builtin_amdgcn_s_barrier()
; #define PG8_SCHED __builtin_amdgcn_sched_barrier(0)
; template <class Epi, class Sched>
; __device__ __forceinline__ void gemm_phase(const int tid, LAS unsigned char* lds, const Gemm g, const Sched& S, const Epi& E) {
;     ...
;             PG8_LDA(At, 1, 1); PG8_STAGE(PG8_SB(1, 0), b3, voffB); PG8_STAGE(PG8_SB(1, 1), b3 + hstepB, voffB); PG8_STAGE(PG8_SA(1, 0), a3, voffA);
;             PG8_WAIT_V(8); PG8_WAIT_L(0); PG8_BAR; PG8_MMA(1, 0, At, B0); PG8_MMA(1, 1, At, B1); PG8_BAR; PG8_SCHED;
;         }
;         if (wr == 0) PG8_BAR;
	s_add_u32 s22, s20, 0x8000
	s_addc_u32 s23, s21, 0
	s_add_i32 s63, s63, s31
	s_mov_b32 m0, s63
	ds_read_b128 v[176:179], v143 offset:49152
	ds_read_b128 v[180:183], v143 offset:50176
	ds_read_b128 v[184:187], v143 offset:51200
	ds_read_b128 v[188:191], v143 offset:52224
	ds_read_b128 v[204:207], v143 offset:53248
	ds_read_b128 v[208:211], v143 offset:54272
	ds_read_b128 v[212:215], v143 offset:55296
	ds_read_b128 v[216:219], v143 offset:56320
	global_load_lds_dwordx4 v130, s[22:23]
	s_add_i32 m0, s63, 0x2000
	s_add_u32 s20, s20, 0xc000
	s_addc_u32 s21, s21, 0
	global_load_lds_dwordx4 v134, s[22:23]
	s_add_i32 s22, s64, s31
	s_mov_b32 m0, s22
	v_lshl_add_u64 v[192:193], v[192:193], 0, s[88:89]
	global_load_lds_dwordx4 v130, s[20:21]
	s_add_i32 m0, s22, 0x2000
	s_nop 0
	global_load_lds_dwordx4 v134, s[20:21]
	s_mov_b32 m0, s53
	s_nop 0
	global_load_lds_dwordx4 v[192:193], off
	v_lshl_add_u64 v[192:193], v[220:221], 0, s[88:89]
	s_mov_b32 m0, s54
	s_nop 0
	global_load_lds_dwordx4 v[192:193], off
	s_waitcnt vmcnt(8)
	s_waitcnt lgkmcnt(0)
	s_barrier
	s_setprio 1
	s_waitcnt lgkmcnt(0)
	v_mfma_f32_16x16x32_bf16 v[62:65], v[144:147], v[176:179], v[62:65]
	v_mfma_f32_16x16x32_bf16 v[58:61], v[152:155], v[176:179], v[58:61]
	v_mfma_f32_16x16x32_bf16 v[54:57], v[144:147], v[184:187], v[54:57]
	v_mfma_f32_16x16x32_bf16 v[50:53], v[152:155], v[184:187], v[50:53]
	v_mfma_f32_16x16x32_bf16 v[38:41], v[144:147], v[204:207], v[38:41]
	v_mfma_f32_16x16x32_bf16 v[34:37], v[152:155], v[204:207], v[34:37]
	v_mfma_f32_16x16x32_bf16 v[22:25], v[144:147], v[212:215], v[22:25]
	v_mfma_f32_16x16x32_bf16 v[18:21], v[152:155], v[212:215], v[18:21]
	v_mfma_f32_16x16x32_bf16 v[62:65], v[148:151], v[180:183], v[62:65]
	v_mfma_f32_16x16x32_bf16 v[58:61], v[156:159], v[180:183], v[58:61]
	v_mfma_f32_16x16x32_bf16 v[54:57], v[148:151], v[188:191], v[54:57]
	v_mfma_f32_16x16x32_bf16 v[50:53], v[156:159], v[188:191], v[50:53]
	v_mfma_f32_16x16x32_bf16 v[38:41], v[148:151], v[208:211], v[38:41]
	v_mfma_f32_16x16x32_bf16 v[34:37], v[156:159], v[208:211], v[34:37]
	v_mfma_f32_16x16x32_bf16 v[22:25], v[148:151], v[216:219], v[22:25]
	v_mfma_f32_16x16x32_bf16 v[18:21], v[156:159], v[216:219], v[18:21]
	s_setprio 0
	s_setprio 1
	v_mfma_f32_16x16x32_bf16 v[46:49], v[160:163], v[176:179], v[46:49]
	v_mfma_f32_16x16x32_bf16 v[42:45], v[168:171], v[176:179], v[42:45]
	v_mfma_f32_16x16x32_bf16 v[30:33], v[160:163], v[184:187], v[30:33]
	v_mfma_f32_16x16x32_bf16 v[26:29], v[168:171], v[184:187], v[26:29]
	v_mfma_f32_16x16x32_bf16 v[14:17], v[160:163], v[204:207], v[14:17]
	v_mfma_f32_16x16x32_bf16 v[10:13], v[168:171], v[204:207], v[10:13]
	v_mfma_f32_16x16x32_bf16 v[6:9], v[160:163], v[212:215], v[6:9]
	v_mfma_f32_16x16x32_bf16 v[2:5], v[168:171], v[212:215], v[2:5]
	v_mfma_f32_16x16x32_bf16 v[46:49], v[164:167], v[180:183], v[46:49]
	v_mfma_f32_16x16x32_bf16 v[42:45], v[172:175], v[180:183], v[42:45]
	v_mfma_f32_16x16x32_bf16 v[30:33], v[164:167], v[188:191], v[30:33]
	v_mfma_f32_16x16x32_bf16 v[26:29], v[172:175], v[188:191], v[26:29]
	v_mfma_f32_16x16x32_bf16 v[14:17], v[164:167], v[208:211], v[14:17]
	v_mfma_f32_16x16x32_bf16 v[10:13], v[172:175], v[208:211], v[10:13]
	v_mfma_f32_16x16x32_bf16 v[6:9], v[164:167], v[216:219], v[6:9]
	v_mfma_f32_16x16x32_bf16 v[2:5], v[172:175], v[216:219], v[2:5]
	s_setprio 0
	s_barrier
	s_add_i32 s62, s62, 2
	s_add_u32 s60, s60, 0x10000
	s_addc_u32 s61, s61, 0
	s_add_u32 s18, s18, 0x100
	s_addc_u32 s19, s19, 0
	s_cmp_gt_u32 s62, 5
	s_cbranch_scc0 .LBB0_428
	s_and_b64 vcc, exec, s[6:7]
	s_cbranch_vccz .LBB0_431
	s_barrier

; __device__ __forceinline__ unsigned pk2(float lo, float hi) { f32x2 v = {lo, hi}; bf16x2_t b = __builtin_convertvector(v, bf16x2_t); return __builtin_bit_cast(unsigned, b); }
; __device__ __forceinline__ float ex2(float x) { return __builtin_amdgcn_exp2f(x); }
; #define MFMA32(a, b, c) __builtin_amdgcn_mfma_f32_32x32x16_bf16((a), (b), (c), 0, 0, 0)
; template <int DQK, int DV, int MODE, int VR> ...
;     ...
;         constexpr int SSTR = DQK * 2 + 16, SP_OFF = STG, NLD = DV * DQK / 4 / 512;
;         static_assert(SP_OFF + DV * SSTR <= 147456, "Sprev staging");
; #pragma unroll 4
;         for (int i = 0; i < NLD; ++i) { const int idx = tid + 512 * i, e = idx / (DQK / 4), c4 = idx % (DQK / 4);
;             const f32x4 v = *(const f32x4*)(Sprev + (size_t)e * DQK + 4 * c4);
;             u32x2 w; w.x = pk2(v[0], v[1]); w.y = pk2(v[2], v[3]);
;             *(u32x2*)(lds + SP_OFF + e * SSTR + c4 * 8) = w; }
;         __syncthreads();
; #pragma unroll
;         for (int b = 0; b < NBLK; ++b)
; #pragma unroll
;             for (int ks = 0; ks < NKS; ++ks) { const bf16x8 a = *(const bf16x8*)(lds + SP_OFF + (32 * b + r32) * SSTR + (16 * ks + 8 * hi) * 2); o[b] = MFMA32(a, qf[ks], o[b]); }
;         const float dq = ex2(a2t - a2[qb * 256 - 1]);
; #pragma unroll
;         for (int b = 0; b < NBLK; ++b)
; #pragma unroll
;             for (int r = 0; r < 16; ++r) o[b][r] *= dq;
.LBB0_658:
	s_lshl_b32 s4, s13, 8
	s_lshl_b32 s5, s12, 4
	v_ashrrev_i32_e32 v0, 31, v179
	s_add_i32 s4, s4, s5
	v_lshrrev_b32_e32 v0, 27, v0
	s_or_b32 s8, s4, s18
	s_mov_b32 s9, s87
	v_add_u32_e32 v0, v179, v0
	s_lshl_b64 s[8:9], s[8:9], 15
	v_readlane_b32 s4, v255, 27
	v_ashrrev_i32_e32 v6, 5, v0
	v_and_b32_e32 v0, 0xffffffe0, v0
	s_add_u32 s8, s4, s8
	v_readlane_b32 s4, v255, 28
	v_sub_u32_e32 v0, v179, v0
	v_ashrrev_i32_e32 v7, 31, v6
	s_addc_u32 s9, s4, s9
	v_lshlrev_b64 v[2:3], 9, v[6:7]
	v_lshlrev_b32_e32 v4, 2, v0
	v_lshl_add_u64 v[2:3], s[8:9], 0, v[2:3]
	v_ashrrev_i32_e32 v5, 31, v4
	v_lshl_add_u64 v[2:3], v[4:5], 2, v[2:3]
	global_load_dwordx4 v[120:123], v[2:3], off
	v_lshlrev_b32_e32 v0, 3, v0
	v_mul_lo_u32 v4, v6, s97
	v_add3_u32 v136, 16, v4, v0
	v_add_u32_e32 v0, 0x200, v179
	v_ashrrev_i32_e32 v2, 31, v0
	v_lshrrev_b32_e32 v2, 27, v2
	v_add_u32_e32 v2, v0, v2
	v_ashrrev_i32_e32 v6, 5, v2
	v_and_b32_e32 v2, 0xffffffe0, v2
	v_sub_u32_e32 v0, v0, v2
	v_ashrrev_i32_e32 v7, 31, v6
	v_lshlrev_b64 v[2:3], 9, v[6:7]
	v_lshlrev_b32_e32 v4, 2, v0
	v_lshl_add_u64 v[2:3], s[8:9], 0, v[2:3]
	v_ashrrev_i32_e32 v5, 31, v4
	v_lshl_add_u64 v[2:3], v[4:5], 2, v[2:3]
	global_load_dwordx4 v[124:127], v[2:3], off
	v_lshlrev_b32_e32 v0, 3, v0
	v_mul_lo_u32 v4, v6, s97
	v_add3_u32 v137, 16, v4, v0
	v_add_u32_e32 v0, 0x400, v179
	v_ashrrev_i32_e32 v2, 31, v0
	v_lshrrev_b32_e32 v2, 27, v2
	v_add_u32_e32 v2, v0, v2
	v_ashrrev_i32_e32 v6, 5, v2
	v_and_b32_e32 v2, 0xffffffe0, v2
	v_sub_u32_e32 v0, v0, v2
	v_ashrrev_i32_e32 v7, 31, v6
	v_lshlrev_b64 v[2:3], 9, v[6:7]
	v_lshlrev_b32_e32 v4, 2, v0
	v_lshl_add_u64 v[2:3], s[8:9], 0, v[2:3]
	v_ashrrev_i32_e32 v5, 31, v4
	v_lshl_add_u64 v[2:3], v[4:5], 2, v[2:3]
	global_load_dwordx4 v[128:131], v[2:3], off
	v_lshlrev_b32_e32 v0, 3, v0
	v_mul_lo_u32 v4, v6, s97
	v_add3_u32 v138, 16, v4, v0
	v_add_u32_e32 v0, 0x600, v179
	v_ashrrev_i32_e32 v2, 31, v0
	v_lshrrev_b32_e32 v2, 27, v2
	v_add_u32_e32 v2, v0, v2
	v_ashrrev_i32_e32 v6, 5, v2
	v_and_b32_e32 v2, 0xffffffe0, v2
	v_sub_u32_e32 v0, v0, v2
	v_ashrrev_i32_e32 v7, 31, v6
	v_lshlrev_b64 v[2:3], 9, v[6:7]
	v_lshlrev_b32_e32 v4, 2, v0
	v_lshl_add_u64 v[2:3], s[8:9], 0, v[2:3]
	v_ashrrev_i32_e32 v5, 31, v4
	v_lshl_add_u64 v[2:3], v[4:5], 2, v[2:3]
	global_load_dwordx4 v[132:135], v[2:3], off
	v_lshlrev_b32_e32 v0, 3, v0
	s_lshl_b64 s[8:9], s[86:87], 2
	s_add_u32 s2, s2, s8
	s_addc_u32 s3, s3, s9
	v_mul_lo_u32 v4, v6, s97
	v_add3_u32 v139, 16, v4, v0
	s_waitcnt vmcnt(0)
	v_cvt_pk_bf16_f32 v120, v120, v121
	v_cvt_pk_bf16_f32 v121, v122, v123
	ds_write_b64 v136, v[120:121] offset:26880
	v_cvt_pk_bf16_f32 v124, v124, v125
	v_cvt_pk_bf16_f32 v125, v126, v127
	ds_write_b64 v137, v[124:125] offset:26880
	v_cvt_pk_bf16_f32 v128, v128, v129
	v_cvt_pk_bf16_f32 v129, v130, v131
	ds_write_b64 v138, v[128:129] offset:26880
	v_cvt_pk_bf16_f32 v132, v132, v133
	v_cvt_pk_bf16_f32 v133, v134, v135
	ds_write_b64 v139, v[132:133] offset:26880
	v_mul_u32_u24_e32 v0, 0x110, v34
	v_add3_u32 v0, 16, v100, v0
	s_waitcnt lgkmcnt(0)
	s_barrier
	ds_read_b128 v[2:5], v0 offset:26880
	ds_read_b128 v[18:21], v0 offset:26912
	s_waitcnt lgkmcnt(1)
	v_mfma_f32_32x32x16_bf16 v[2:17], v[2:5], v[74:77], 0
	ds_read_b128 v[36:39], v0 offset:35616
	s_waitcnt lgkmcnt(1)
	v_mfma_f32_32x32x16_bf16 v[2:17], v[18:21], v[78:81], v[2:17]
	ds_read_b128 v[212:215], v0 offset:26944
	ds_read_b128 v[216:219], v0 offset:26976
	ds_read_b128 v[220:223], v0 offset:27008
	s_waitcnt lgkmcnt(2)
	v_mfma_f32_32x32x16_bf16 v[2:17], v[212:215], v[70:73], v[2:17]
	ds_read_b128 v[212:215], v0 offset:27040
	s_waitcnt lgkmcnt(2)
	v_mfma_f32_32x32x16_bf16 v[2:17], v[216:219], v[66:69], v[2:17]
	ds_read_b128 v[216:219], v0 offset:27072
	s_waitcnt lgkmcnt(2)
	v_mfma_f32_32x32x16_bf16 v[2:17], v[220:223], v[62:65], v[2:17]
	ds_read_b128 v[220:223], v0 offset:27104
	s_waitcnt lgkmcnt(2)
	v_mfma_f32_32x32x16_bf16 v[2:17], v[212:215], v[58:61], v[2:17]
	ds_read_b128 v[212:215], v0 offset:35584
	s_waitcnt lgkmcnt(2)
	v_mfma_f32_32x32x16_bf16 v[2:17], v[216:219], v[54:57], v[2:17]
	s_waitcnt lgkmcnt(1)
	v_mfma_f32_32x32x16_bf16 v[2:17], v[220:223], v[50:53], v[2:17]
	s_waitcnt lgkmcnt(0)
	v_mfma_f32_32x32x16_bf16 v[18:33], v[212:215], v[74:77], 0
	v_mfma_f32_32x32x16_bf16 v[18:33], v[36:39], v[78:81], v[18:33]
	ds_read_b128 v[212:215], v0 offset:35648
	ds_read_b128 v[216:219], v0 offset:35680
	ds_read_b128 v[220:223], v0 offset:35712
	s_waitcnt lgkmcnt(2)
	v_mfma_f32_32x32x16_bf16 v[18:33], v[212:215], v[70:73], v[18:33]
	ds_read_b128 v[212:215], v0 offset:35744
	s_waitcnt lgkmcnt(2)
	v_mfma_f32_32x32x16_bf16 v[18:33], v[216:219], v[66:69], v[18:33]
	ds_read_b128 v[216:219], v0 offset:35776
	s_waitcnt lgkmcnt(2)
	v_mfma_f32_32x32x16_bf16 v[18:33], v[220:223], v[62:65], v[18:33]
	ds_read_b128 v[220:223], v0 offset:35808
	s_waitcnt lgkmcnt(2)
	v_mfma_f32_32x32x16_bf16 v[18:33], v[212:215], v[58:61], v[18:33]
	s_waitcnt lgkmcnt(1)
	v_mfma_f32_32x32x16_bf16 v[18:33], v[216:219], v[54:57], v[18:33]
	global_load_dword v0, v1, s[2:3] offset:-4
	s_waitcnt vmcnt(0)
	v_sub_f32_e32 v0, v99, v0
	s_waitcnt lgkmcnt(0)
	v_mfma_f32_32x32x16_bf16 v[18:33], v[220:223], v[50:53], v[18:33]
	v_exp_f32_e32 v0, v0
	s_nop 0
	v_pk_mul_f32 v[16:17], v[16:17], v[0:1] op_sel_hi:[1,0]
	v_pk_mul_f32 v[14:15], v[14:15], v[0:1] op_sel_hi:[1,0]
	v_pk_mul_f32 v[12:13], v[12:13], v[0:1] op_sel_hi:[1,0]
	v_pk_mul_f32 v[10:11], v[10:11], v[0:1] op_sel_hi:[1,0]
	v_pk_mul_f32 v[8:9], v[8:9], v[0:1] op_sel_hi:[1,0]
	v_pk_mul_f32 v[6:7], v[6:7], v[0:1] op_sel_hi:[1,0]
	v_pk_mul_f32 v[4:5], v[4:5], v[0:1] op_sel_hi:[1,0]
	v_pk_mul_f32 v[2:3], v[2:3], v[0:1] op_sel_hi:[1,0]
	s_nop 1
	v_pk_mul_f32 v[32:33], v[32:33], v[0:1] op_sel_hi:[1,0]
	v_pk_mul_f32 v[30:31], v[30:31], v[0:1] op_sel_hi:[1,0]
	v_pk_mul_f32 v[28:29], v[28:29], v[0:1] op_sel_hi:[1,0]
	v_pk_mul_f32 v[26:27], v[26:27], v[0:1] op_sel_hi:[1,0]
	v_pk_mul_f32 v[24:25], v[24:25], v[0:1] op_sel_hi:[1,0]
	v_pk_mul_f32 v[22:23], v[22:23], v[0:1] op_sel_hi:[1,0]
	v_pk_mul_f32 v[20:21], v[20:21], v[0:1] op_sel_hi:[1,0]
	v_pk_mul_f32 v[18:19], v[18:19], v[0:1] op_sel_hi:[1,0]

; __device__ __forceinline__ unsigned pk2(float lo, float hi) { f32x2 v = {lo, hi}; bf16x2_t b = __builtin_convertvector(v, bf16x2_t); return __builtin_bit_cast(unsigned, b); }
; __device__ __forceinline__ float ex2(float x) { return __builtin_amdgcn_exp2f(x); }
; #define MFMA32(a, b, c) __builtin_amdgcn_mfma_f32_32x32x16_bf16((a), (b), (c), 0, 0, 0)
; template <int DQK, int DV, int MODE, int VR> ...
;     ...
;                 for (int kb = 0; kb < 2; ++kb) {
;                     if (kv0 + 32 * kb > t0 + 31) continue;
;                     f32x16 p;
; #pragma unroll
;                     for (int r = 0; r < 16; ++r) p[r] = 0.f;
; #pragma unroll
;                     for (int ks = 0; ks < NKS; ++ks) { const bf16x8 a = *(const bf16x8*)(Kl + (32 * kb + pirow) * KSTR + (16 * ks + 8 * hi) * 2); p = MFMA32(a, qf[ks], p); }
;                     bf16x8 pb[2];
; #pragma unroll
;                     for (int sl = 0; sl < 2; ++sl) {
;                         const f32x4 s0 = *(const f32x4*)(Al + 32 * kb + 16 * sl + 8 * hi), s1 = *(const f32x4*)(Al + 32 * kb + 16 * sl + 8 * hi + 4);
;                         float e[8];
; #pragma unroll
;                         for (int jj = 0; jj < 8; ++jj) { const float as = jj < 4 ? s0[jj] : s1[jj - 4]; const int kv = kv0 + 32 * kb + 16 * sl + 8 * hi + jj;
;                             const float w = ex2(a2t - as); e[jj] = (diag && kv > t) ? 0.f : p[8 * sl + jj] * w; }
;                         u32x4 w; w.x = pk2(e[0], e[1]); w.y = pk2(e[2], e[3]); w.z = pk2(e[4], e[5]); w.w = pk2(e[6], e[7]);
;                         pb[sl] = __builtin_bit_cast(bf16x8, w);
;                     }
; #pragma unroll
;                     for (int b = 0; b < NBLK; ++b)
; #pragma unroll
;                         for (int sl = 0; sl < 2; ++sl) { const bf16x8 a = *(const bf16x8*)(Vl + (32 * b + r32) * VSTR + (32 * kb + 16 * sl + 8 * hi) * 2); o[b] = MFMA32(a, pb[sl], o[b]); }
.LBB0_670:
	s_add_u32 s25, s86, s8
	s_cmp_gt_i32 s25, s20
	s_cbranch_scc1 .LBB0_673
	s_bitcmp1_b32 s14, 0
	s_cselect_b32 s4, 0x6900, 0
	s_add_i32 s26, s4, 16
	v_add_u32_e32 v34, s26, v100
	v_add_u32_e32 v111, v34, v109
	v_add_u32_e32 v110, v34, v100
	ds_read_b128 v[34:37], v111
	ds_read_b128 v[112:115], v111 offset:32
	v_lshl_add_u64 v[104:105], v[0:1], 0, s[8:9]
	s_add_i32 s4, s25, 63
	s_waitcnt lgkmcnt(1)
	v_mfma_f32_32x32x16_bf16 v[34:49], v[34:37], v[74:77], 0
	s_cmp_gt_i32 s4, s16
	s_cselect_b64 s[12:13], -1, 0
	v_cmp_gt_i32_e32 vcc, v104, v98
	s_and_b64 s[14:15], s[12:13], vcc
	v_cmp_ge_i32_e32 vcc, v104, v98
	s_add_i32 s25, s25, 32
	s_waitcnt lgkmcnt(0)
	v_mfma_f32_32x32x16_bf16 v[34:49], v[112:115], v[78:81], v[34:49]
	ds_read_b128 v[212:215], v111 offset:64
	ds_read_b128 v[216:219], v111 offset:96
	ds_read_b128 v[220:223], v111 offset:128
	s_waitcnt lgkmcnt(2)
	v_mfma_f32_32x32x16_bf16 v[34:49], v[212:215], v[70:73], v[34:49]
	ds_read_b128 v[212:215], v111 offset:160
	s_waitcnt lgkmcnt(2)
	v_mfma_f32_32x32x16_bf16 v[34:49], v[216:219], v[66:69], v[34:49]
	ds_read_b128 v[216:219], v111 offset:192
	s_waitcnt lgkmcnt(2)
	v_mfma_f32_32x32x16_bf16 v[34:49], v[220:223], v[62:65], v[34:49]
	ds_read_b128 v[220:223], v111 offset:224
	s_waitcnt lgkmcnt(2)
	v_mfma_f32_32x32x16_bf16 v[34:49], v[212:215], v[58:61], v[34:49]
	s_waitcnt lgkmcnt(1)
	v_mfma_f32_32x32x16_bf16 v[34:49], v[216:219], v[54:57], v[34:49]
	s_waitcnt lgkmcnt(0)
	v_mfma_f32_32x32x16_bf16 v[34:49], v[220:223], v[50:53], v[34:49]
	ds_read_b128 v[112:115], v110 offset:26624
	ds_read_b128 v[116:119], v110 offset:26640
	s_waitcnt lgkmcnt(1)
	v_sub_f32_e32 v105, v99, v112
	v_exp_f32_e32 v105, v105
	v_add_u32_e32 v112, 2, v104
	s_nop 5
	v_mul_f32_e32 v34, v34, v105
	v_sub_f32_e32 v105, v99, v113
	v_exp_f32_e32 v105, v105
	v_cndmask_b32_e64 v34, v34, 0, s[14:15]
	s_and_b64 s[14:15], s[12:13], vcc
	v_cmp_gt_i32_e32 vcc, v112, v98
	v_mul_f32_e32 v35, v35, v105
	v_sub_f32_e32 v105, v99, v114
	v_exp_f32_e32 v105, v105
	v_add_u32_e32 v112, 3, v104
	v_cndmask_b32_e64 v35, v35, 0, s[14:15]
	s_and_b64 s[14:15], s[12:13], vcc
	v_mul_f32_e32 v36, v36, v105
	v_sub_f32_e32 v105, v99, v115
	v_exp_f32_e32 v105, v105
	v_cmp_gt_i32_e32 vcc, v112, v98
	v_add_u32_e32 v112, 4, v104
	v_cndmask_b32_e64 v36, v36, 0, s[14:15]
	v_mul_f32_e32 v37, v37, v105
	s_waitcnt lgkmcnt(0)
	v_sub_f32_e32 v105, v99, v116
	v_exp_f32_e32 v105, v105
	s_and_b64 s[14:15], s[12:13], vcc
	v_cmp_gt_i32_e32 vcc, v112, v98
	v_add_u32_e32 v112, 5, v104
	v_mul_f32_e32 v38, v38, v105
	v_sub_f32_e32 v105, v99, v117
	v_exp_f32_e32 v105, v105
	v_cndmask_b32_e64 v37, v37, 0, s[14:15]
	s_and_b64 s[14:15], s[12:13], vcc
	v_cmp_gt_i32_e32 vcc, v112, v98
	v_mul_f32_e32 v39, v39, v105
	v_sub_f32_e32 v105, v99, v118
	v_exp_f32_e32 v105, v105
	v_add_u32_e32 v112, 6, v104
	v_cndmask_b32_e64 v38, v38, 0, s[14:15]
	s_and_b64 s[14:15], s[12:13], vcc
	v_mul_f32_e32 v40, v40, v105
	v_sub_f32_e32 v105, v99, v119
	v_exp_f32_e32 v105, v105
	v_cmp_gt_i32_e32 vcc, v112, v98
	v_add_u32_e32 v112, 7, v104
	v_cndmask_b32_e64 v39, v39, 0, s[14:15]
	s_and_b64 s[14:15], s[12:13], vcc
	v_cmp_gt_i32_e32 vcc, v112, v98
	v_cndmask_b32_e64 v40, v40, 0, s[14:15]
	s_and_b64 s[14:15], s[12:13], vcc
	v_mul_f32_e32 v41, v41, v105
	v_cndmask_b32_e64 v41, v41, 0, s[14:15]
	v_cvt_pk_bf16_f32 v34, v34, v35
	v_cvt_pk_bf16_f32 v35, v36, v37
	v_cvt_pk_bf16_f32 v36, v38, v39
	v_cvt_pk_bf16_f32 v37, v40, v41
	ds_read_b128 v[38:41], v110 offset:26688
	ds_read_b128 v[112:115], v110 offset:26704
	v_add_u32_e32 v105, 16, v104
	v_cmp_gt_i32_e32 vcc, v105, v98
	s_and_b64 s[14:15], s[12:13], vcc
	s_waitcnt lgkmcnt(1)
	v_sub_f32_e32 v38, v99, v38
	v_exp_f32_e32 v38, v38
	v_sub_f32_e32 v39, v99, v39
	v_exp_f32_e32 v39, v39
	v_sub_f32_e32 v40, v99, v40
	v_mul_f32_e32 v38, v42, v38
	v_add_u32_e32 v42, 17, v104
	v_cmp_gt_i32_e32 vcc, v42, v98
	v_add_u32_e32 v42, 18, v104
	v_cndmask_b32_e64 v38, v38, 0, s[14:15]
	s_and_b64 s[14:15], s[12:13], vcc
	v_mul_f32_e32 v39, v43, v39
	v_exp_f32_e32 v40, v40
	v_cmp_gt_i32_e32 vcc, v42, v98
	v_sub_f32_e32 v41, v99, v41
	v_add_u32_e32 v42, 19, v104
	v_cndmask_b32_e64 v39, v39, 0, s[14:15]
	s_and_b64 s[14:15], s[12:13], vcc
	v_exp_f32_e32 v41, v41
	v_cmp_gt_i32_e32 vcc, v42, v98
	s_waitcnt lgkmcnt(0)
	v_sub_f32_e32 v42, v99, v112
	v_exp_f32_e32 v42, v42
	v_mul_f32_e32 v40, v44, v40
	v_add_u32_e32 v43, 20, v104
	v_cndmask_b32_e64 v40, v40, 0, s[14:15]
	s_and_b64 s[14:15], s[12:13], vcc
	v_mul_f32_e32 v41, v45, v41
	v_cmp_gt_i32_e32 vcc, v43, v98
	v_sub_f32_e32 v43, v99, v113
	v_add_u32_e32 v44, 21, v104
	v_cndmask_b32_e64 v41, v41, 0, s[14:15]
	s_and_b64 s[14:15], s[12:13], vcc
	v_mul_f32_e32 v42, v46, v42
	v_exp_f32_e32 v43, v43
	v_cmp_gt_i32_e32 vcc, v44, v98
	v_sub_f32_e32 v44, v99, v114
	v_add_u32_e32 v45, 22, v104
	v_cndmask_b32_e64 v42, v42, 0, s[14:15]
	s_and_b64 s[14:15], s[12:13], vcc
	v_exp_f32_e32 v44, v44
	v_cmp_gt_i32_e32 vcc, v45, v98
	v_sub_f32_e32 v45, v99, v115
	v_exp_f32_e32 v45, v45
	v_mul_f32_e32 v43, v47, v43
	v_add_u32_e32 v46, 23, v104
	v_cndmask_b32_e64 v43, v43, 0, s[14:15]
	s_and_b64 s[14:15], s[12:13], vcc
	v_mul_f32_e32 v44, v48, v44
	v_cmp_gt_i32_e32 vcc, v46, v98
	v_cndmask_b32_e64 v44, v44, 0, s[14:15]
	s_and_b64 s[14:15], s[12:13], vcc
	v_mul_f32_e32 v45, v49, v45
	v_cvt_pk_bf16_f32 v38, v38, v39
	v_cvt_pk_bf16_f32 v39, v40, v41
	v_cvt_pk_bf16_f32 v40, v42, v43
	v_add_u32_e32 v42, s26, v108
	v_cndmask_b32_e64 v45, v45, 0, s[14:15]
	v_add_u32_e32 v105, v42, v100
	v_cvt_pk_bf16_f32 v41, v44, v45
	ds_read_b128 v[42:45], v105 offset:17408
	ds_read_b128 v[46:49], v105 offset:17440
	s_waitcnt lgkmcnt(1)
	v_mfma_f32_32x32x16_bf16 v[2:17], v[42:45], v[34:37], v[2:17]
	ds_read_b128 v[42:45], v105 offset:22016
	s_cmp_gt_i32 s25, s20
	s_waitcnt lgkmcnt(0)
	v_mfma_f32_32x32x16_bf16 v[18:33], v[42:45], v[34:37], v[18:33]
	ds_read_b128 v[34:37], v105 offset:22048
	v_mfma_f32_32x32x16_bf16 v[2:17], v[46:49], v[38:41], v[2:17]
	s_waitcnt lgkmcnt(0)
	v_mfma_f32_32x32x16_bf16 v[18:33], v[34:37], v[38:41], v[18:33]
	s_cbranch_scc1 .LBB0_673
; __device__ __forceinline__ unsigned pk2(float lo, float hi) { f32x2 v = {lo, hi}; bf16x2_t b = __builtin_convertvector(v, bf16x2_t); return __builtin_bit_cast(unsigned, b); }
; __device__ __forceinline__ float ex2(float x) { return __builtin_amdgcn_exp2f(x); }
; #define MFMA32(a, b, c) __builtin_amdgcn_mfma_f32_32x32x16_bf16((a), (b), (c), 0, 0, 0)
; template <int DQK, int DV, int MODE, int VR> ...
;     ...
;                     if (kv0 + 32 * kb > t0 + 31) continue;
;                     f32x16 p;
; #pragma unroll
;                     for (int r = 0; r < 16; ++r) p[r] = 0.f;
; #pragma unroll
;                     for (int ks = 0; ks < NKS; ++ks) { const bf16x8 a = *(const bf16x8*)(Kl + (32 * kb + pirow) * KSTR + (16 * ks + 8 * hi) * 2); p = MFMA32(a, qf[ks], p); }
;                     bf16x8 pb[2];
; #pragma unroll
;                     for (int sl = 0; sl < 2; ++sl) {
;                         const f32x4 s0 = *(const f32x4*)(Al + 32 * kb + 16 * sl + 8 * hi), s1 = *(const f32x4*)(Al + 32 * kb + 16 * sl + 8 * hi + 4);
;                         float e[8];
; #pragma unroll
;                         for (int jj = 0; jj < 8; ++jj) { const float as = jj < 4 ? s0[jj] : s1[jj - 4]; const int kv = kv0 + 32 * kb + 16 * sl + 8 * hi + jj;
;                             const float w = ex2(a2t - as); e[jj] = (diag && kv > t) ? 0.f : p[8 * sl + jj] * w; }
;                         u32x4 w; w.x = pk2(e[0], e[1]); w.y = pk2(e[2], e[3]); w.z = pk2(e[4], e[5]); w.w = pk2(e[6], e[7]);
;                         pb[sl] = __builtin_bit_cast(bf16x8, w);
;                     }
; #pragma unroll
;                     for (int b = 0; b < NBLK; ++b)
; #pragma unroll
;                         for (int sl = 0; sl < 2; ++sl) { const bf16x8 a = *(const bf16x8*)(Vl + (32 * b + r32) * VSTR + (32 * kb + 16 * sl + 8 * hi) * 2); o[b] = MFMA32(a, pb[sl], o[b]); }
	ds_read_b128 v[34:37], v111 offset:8704
	ds_read_b128 v[112:115], v111 offset:8736
	s_waitcnt lgkmcnt(1)
	v_mfma_f32_32x32x16_bf16 v[34:49], v[34:37], v[74:77], 0
	s_waitcnt lgkmcnt(0)
	v_mfma_f32_32x32x16_bf16 v[34:49], v[112:115], v[78:81], v[34:49]
	ds_read_b128 v[212:215], v111 offset:8768
	ds_read_b128 v[216:219], v111 offset:8800
	ds_read_b128 v[220:223], v111 offset:8832
	s_waitcnt lgkmcnt(2)
	v_mfma_f32_32x32x16_bf16 v[34:49], v[212:215], v[70:73], v[34:49]
	ds_read_b128 v[212:215], v111 offset:8864
	s_waitcnt lgkmcnt(2)
	v_mfma_f32_32x32x16_bf16 v[34:49], v[216:219], v[66:69], v[34:49]
	ds_read_b128 v[216:219], v111 offset:8896
	s_waitcnt lgkmcnt(2)
	v_mfma_f32_32x32x16_bf16 v[34:49], v[220:223], v[62:65], v[34:49]
	ds_read_b128 v[220:223], v111 offset:8928
	s_waitcnt lgkmcnt(2)
	v_mfma_f32_32x32x16_bf16 v[34:49], v[212:215], v[58:61], v[34:49]
	s_waitcnt lgkmcnt(1)
	v_mfma_f32_32x32x16_bf16 v[34:49], v[216:219], v[54:57], v[34:49]
	v_add_u32_e32 v111, 32, v104
	v_cmp_gt_i32_e32 vcc, v111, v98
	s_and_b64 s[14:15], s[12:13], vcc
	v_cmp_ge_i32_e32 vcc, v111, v98
	s_waitcnt lgkmcnt(0)
	v_mfma_f32_32x32x16_bf16 v[34:49], v[220:223], v[50:53], v[34:49]
	ds_read_b128 v[112:115], v110 offset:26752
	ds_read_b128 v[116:119], v110 offset:26768
	s_waitcnt lgkmcnt(1)
	v_sub_f32_e32 v111, v99, v114
	v_exp_f32_e32 v111, v111
	v_sub_f32_e32 v112, v99, v112
	v_exp_f32_e32 v112, v112
	v_add_u32_e32 v114, 48, v104
	s_nop 3
	v_mul_f32_e32 v36, v36, v111
	v_sub_f32_e32 v111, v99, v115
	v_exp_f32_e32 v111, v111
	v_mul_f32_e32 v34, v34, v112
	v_sub_f32_e32 v112, v99, v113
	v_exp_f32_e32 v112, v112
	v_mul_f32_e32 v37, v37, v111
	s_waitcnt lgkmcnt(0)
	v_sub_f32_e32 v111, v99, v116
	v_exp_f32_e32 v111, v111
	v_mul_f32_e32 v35, v35, v112
	v_add_u32_e32 v112, 34, v104
	v_cndmask_b32_e64 v34, v34, 0, s[14:15]
	v_mul_f32_e32 v38, v38, v111
	v_sub_f32_e32 v111, v99, v117
	v_exp_f32_e32 v111, v111
	s_and_b64 s[14:15], s[12:13], vcc
	v_cmp_gt_i32_e32 vcc, v112, v98
	v_add_u32_e32 v112, 35, v104
	v_mul_f32_e32 v39, v39, v111
	v_sub_f32_e32 v111, v99, v118
	v_exp_f32_e32 v111, v111
	v_cndmask_b32_e64 v35, v35, 0, s[14:15]
	s_and_b64 s[14:15], s[12:13], vcc
	v_cmp_gt_i32_e32 vcc, v112, v98
	v_add_u32_e32 v112, 36, v104
	v_mul_f32_e32 v40, v40, v111
	v_sub_f32_e32 v111, v99, v119
	v_cndmask_b32_e64 v36, v36, 0, s[14:15]
	s_and_b64 s[14:15], s[12:13], vcc
	v_cmp_gt_i32_e32 vcc, v112, v98
	v_add_u32_e32 v112, 37, v104
	v_exp_f32_e32 v111, v111
	v_cndmask_b32_e64 v37, v37, 0, s[14:15]
	s_and_b64 s[14:15], s[12:13], vcc
	v_cmp_gt_i32_e32 vcc, v112, v98
	v_add_u32_e32 v112, 38, v104
	v_cndmask_b32_e64 v38, v38, 0, s[14:15]
	s_and_b64 s[14:15], s[12:13], vcc
	v_cmp_gt_i32_e32 vcc, v112, v98
	v_add_u32_e32 v112, 39, v104
	v_cndmask_b32_e64 v39, v39, 0, s[14:15]
	s_and_b64 s[14:15], s[12:13], vcc
	v_cmp_gt_i32_e32 vcc, v112, v98
	v_cndmask_b32_e64 v40, v40, 0, s[14:15]
	s_and_b64 s[14:15], s[12:13], vcc
	v_mul_f32_e32 v41, v41, v111
	v_cndmask_b32_e64 v41, v41, 0, s[14:15]
	v_cvt_pk_bf16_f32 v34, v34, v35
	v_cvt_pk_bf16_f32 v35, v36, v37
	v_cvt_pk_bf16_f32 v36, v38, v39
	v_cvt_pk_bf16_f32 v37, v40, v41
	ds_read_b128 v[38:41], v110 offset:26816
	ds_read_b128 v[110:113], v110 offset:26832
	v_cmp_gt_i32_e32 vcc, v114, v98
	s_and_b64 s[14:15], s[12:13], vcc
	s_waitcnt lgkmcnt(1)
	v_sub_f32_e32 v38, v99, v38
	v_exp_f32_e32 v38, v38
	v_sub_f32_e32 v39, v99, v39
	v_exp_f32_e32 v39, v39
	v_sub_f32_e32 v40, v99, v40
	v_mul_f32_e32 v38, v42, v38
	v_add_u32_e32 v42, 49, v104
	v_cmp_gt_i32_e32 vcc, v42, v98
	v_add_u32_e32 v42, 50, v104
	v_cndmask_b32_e64 v38, v38, 0, s[14:15]
	s_and_b64 s[14:15], s[12:13], vcc
	v_mul_f32_e32 v39, v43, v39
	v_exp_f32_e32 v40, v40
	v_cmp_gt_i32_e32 vcc, v42, v98
	v_sub_f32_e32 v41, v99, v41
	v_add_u32_e32 v42, 51, v104
	v_cndmask_b32_e64 v39, v39, 0, s[14:15]
	s_and_b64 s[14:15], s[12:13], vcc
	v_exp_f32_e32 v41, v41
	v_cmp_gt_i32_e32 vcc, v42, v98
	s_waitcnt lgkmcnt(0)
	v_sub_f32_e32 v42, v99, v110
	v_exp_f32_e32 v42, v42
	v_mul_f32_e32 v40, v44, v40
	v_add_u32_e32 v43, 52, v104
	v_cndmask_b32_e64 v40, v40, 0, s[14:15]
	s_and_b64 s[14:15], s[12:13], vcc
	v_mul_f32_e32 v41, v45, v41
	v_cmp_gt_i32_e32 vcc, v43, v98
	v_sub_f32_e32 v43, v99, v111
	v_add_u32_e32 v44, 53, v104
	v_cndmask_b32_e64 v41, v41, 0, s[14:15]
	s_and_b64 s[14:15], s[12:13], vcc
	v_mul_f32_e32 v42, v46, v42
	v_exp_f32_e32 v43, v43
	v_cmp_gt_i32_e32 vcc, v44, v98
	v_add_u32_e32 v45, 54, v104
	v_cndmask_b32_e64 v42, v42, 0, s[14:15]
	s_and_b64 s[14:15], s[12:13], vcc
	v_sub_f32_e32 v44, v99, v112
	v_cmp_gt_i32_e32 vcc, v45, v98
	v_sub_f32_e32 v45, v99, v113
	v_exp_f32_e32 v44, v44
	v_exp_f32_e32 v45, v45
	v_mul_f32_e32 v43, v47, v43
	v_add_u32_e32 v46, 55, v104
	v_cndmask_b32_e64 v43, v43, 0, s[14:15]
	s_and_b64 s[14:15], s[12:13], vcc
	v_cmp_gt_i32_e32 vcc, v46, v98
	v_mul_f32_e32 v44, v48, v44
	s_and_b64 s[12:13], s[12:13], vcc
	v_mul_f32_e32 v45, v49, v45
	v_cndmask_b32_e64 v44, v44, 0, s[14:15]
	v_cndmask_b32_e64 v45, v45, 0, s[12:13]
	v_cvt_pk_bf16_f32 v38, v38, v39
	v_cvt_pk_bf16_f32 v39, v40, v41
	v_cvt_pk_bf16_f32 v40, v42, v43
	v_cvt_pk_bf16_f32 v41, v44, v45
	ds_read_b128 v[42:45], v105 offset:17472
	ds_read_b128 v[46:49], v105 offset:17504
	s_waitcnt lgkmcnt(1)
	v_mfma_f32_32x32x16_bf16 v[2:17], v[42:45], v[34:37], v[2:17]
	ds_read_b128 v[42:45], v105 offset:22080
	s_waitcnt lgkmcnt(0)
	v_mfma_f32_32x32x16_bf16 v[18:33], v[42:45], v[34:37], v[18:33]
	ds_read_b128 v[34:37], v105 offset:22112
	v_mfma_f32_32x32x16_bf16 v[2:17], v[46:49], v[38:41], v[2:17]
	s_waitcnt lgkmcnt(0)
	v_mfma_f32_32x32x16_bf16 v[18:33], v[34:37], v[38:41], v[18:33]

; __device__ __forceinline__ unsigned pk2(float lo, float hi) { f32x2 v = {lo, hi}; bf16x2_t b = __builtin_convertvector(v, bf16x2_t); return __builtin_bit_cast(unsigned, b); }
; __device__ __forceinline__ float ex2(float x) { return __builtin_amdgcn_exp2f(x); }
; #define MFMA32(a, b, c) __builtin_amdgcn_mfma_f32_32x32x16_bf16((a), (b), (c), 0, 0, 0)
; template <int DQK, int DV, int MODE, int VR> ...
;     ...
;                 for (int kb = 0; kb < 2; ++kb) {
;                     if (kv0 + 32 * kb > t0 + 31) continue;
;                     f32x16 p;
; #pragma unroll
;                     for (int r = 0; r < 16; ++r) p[r] = 0.f;
; #pragma unroll
;                     for (int ks = 0; ks < NKS; ++ks) { const bf16x8 a = *(const bf16x8*)(Kl + (32 * kb + pirow) * KSTR + (16 * ks + 8 * hi) * 2); p = MFMA32(a, qf[ks], p); }
;                     bf16x8 pb[2];
; #pragma unroll
;                     for (int sl = 0; sl < 2; ++sl) {
;                         const f32x4 s0 = *(const f32x4*)(Al + 32 * kb + 16 * sl + 8 * hi), s1 = *(const f32x4*)(Al + 32 * kb + 16 * sl + 8 * hi + 4);
;                         float e[8];
; #pragma unroll
;                         for (int jj = 0; jj < 8; ++jj) { const float as = jj < 4 ? s0[jj] : s1[jj - 4]; const int kv = kv0 + 32 * kb + 16 * sl + 8 * hi + jj;
;                             const float w = ex2(a2t - as); e[jj] = (diag && kv > t) ? 0.f : p[8 * sl + jj] * w; }
;                         u32x4 w; w.x = pk2(e[0], e[1]); w.y = pk2(e[2], e[3]); w.z = pk2(e[4], e[5]); w.w = pk2(e[6], e[7]);
;                         pb[sl] = __builtin_bit_cast(bf16x8, w);
;                     }
; #pragma unroll
;                     for (int b = 0; b < NBLK; ++b)
; #pragma unroll
;                         for (int sl = 0; sl < 2; ++sl) { const bf16x8 a = *(const bf16x8*)(Vl + (32 * b + r32) * VSTR + (32 * kb + 16 * sl + 8 * hi) * 2); o[b] = MFMA32(a, pb[sl], o[b]); }
.LBB0_681:
	s_lshl_b32 s6, s24, 6
	s_cmp_gt_i32 s6, s20
	s_cbranch_scc1 .LBB0_684
	s_bitcmp1_b32 s24, 0
	s_cselect_b32 s0, 0x6900, 0
	s_add_i32 s7, s0, 16
	v_add_u32_e32 v34, s7, v100
	s_waitcnt vmcnt(1)
	v_add_u32_e32 v83, v34, v109
	v_add_u32_e32 v0, v34, v100
	ds_read_b128 v[34:37], v83
	s_waitcnt vmcnt(0)
	ds_read_b128 v[84:87], v83 offset:32
	s_or_b32 s0, s6, 63
	s_cmp_gt_i32 s0, s16
	s_waitcnt lgkmcnt(1)
	v_mfma_f32_32x32x16_bf16 v[34:49], v[34:37], v[74:77], 0
	v_or_b32_e32 v82, s6, v107
	s_cselect_b64 s[0:1], -1, 0
	v_cmp_gt_i32_e32 vcc, v82, v98
	s_and_b64 s[2:3], s[0:1], vcc
	v_cmp_ge_i32_e32 vcc, v82, v98
	s_waitcnt lgkmcnt(0)
	v_mfma_f32_32x32x16_bf16 v[34:49], v[84:87], v[78:81], v[34:49]
	ds_read_b128 v[212:215], v83 offset:64
	ds_read_b128 v[216:219], v83 offset:96
	ds_read_b128 v[220:223], v83 offset:128
	s_waitcnt lgkmcnt(2)
	v_mfma_f32_32x32x16_bf16 v[34:49], v[212:215], v[70:73], v[34:49]
	ds_read_b128 v[212:215], v83 offset:160
	s_waitcnt lgkmcnt(2)
	v_mfma_f32_32x32x16_bf16 v[34:49], v[216:219], v[66:69], v[34:49]
	ds_read_b128 v[216:219], v83 offset:192
	s_waitcnt lgkmcnt(2)
	v_mfma_f32_32x32x16_bf16 v[34:49], v[220:223], v[62:65], v[34:49]
	ds_read_b128 v[220:223], v83 offset:224
	s_waitcnt lgkmcnt(2)
	v_mfma_f32_32x32x16_bf16 v[34:49], v[212:215], v[58:61], v[34:49]
	s_waitcnt lgkmcnt(1)
	v_mfma_f32_32x32x16_bf16 v[34:49], v[216:219], v[54:57], v[34:49]
	s_waitcnt lgkmcnt(0)
	v_mfma_f32_32x32x16_bf16 v[34:49], v[220:223], v[50:53], v[34:49]
	ds_read_b128 v[84:87], v0 offset:26624
	ds_read_b128 v[88:91], v0 offset:26640
	s_waitcnt lgkmcnt(1)
	v_sub_f32_e32 v84, v99, v84
	v_exp_f32_e32 v84, v84
	s_nop 6
	v_mul_f32_e32 v34, v34, v84
	v_sub_f32_e32 v84, v99, v85
	v_exp_f32_e32 v84, v84
	v_or_b32_e32 v85, 2, v82
	v_cndmask_b32_e64 v34, v34, 0, s[2:3]
	s_and_b64 s[2:3], s[0:1], vcc
	v_mul_f32_e32 v35, v35, v84
	v_sub_f32_e32 v84, v99, v86
	v_exp_f32_e32 v84, v84
	v_cmp_gt_i32_e32 vcc, v85, v98
	v_or_b32_e32 v85, 3, v82
	v_cndmask_b32_e64 v35, v35, 0, s[2:3]
	v_mul_f32_e32 v36, v36, v84
	v_sub_f32_e32 v84, v99, v87
	v_exp_f32_e32 v84, v84
	s_and_b64 s[2:3], s[0:1], vcc
	v_cmp_gt_i32_e32 vcc, v85, v98
	v_or_b32_e32 v85, 4, v82
	v_mul_f32_e32 v37, v37, v84
	s_waitcnt lgkmcnt(0)
	v_sub_f32_e32 v84, v99, v88
	v_exp_f32_e32 v84, v84
	v_cndmask_b32_e64 v36, v36, 0, s[2:3]
	s_and_b64 s[2:3], s[0:1], vcc
	v_cmp_gt_i32_e32 vcc, v85, v98
	v_mul_f32_e32 v38, v38, v84
	v_sub_f32_e32 v84, v99, v89
	v_exp_f32_e32 v84, v84
	v_or_b32_e32 v85, 5, v82
	v_cndmask_b32_e64 v37, v37, 0, s[2:3]
	s_and_b64 s[2:3], s[0:1], vcc
	v_mul_f32_e32 v39, v39, v84
	v_sub_f32_e32 v84, v99, v90
	v_exp_f32_e32 v84, v84
	v_cmp_gt_i32_e32 vcc, v85, v98
	v_or_b32_e32 v85, 6, v82
	v_cndmask_b32_e64 v38, v38, 0, s[2:3]
	v_mul_f32_e32 v40, v40, v84
	v_sub_f32_e32 v84, v99, v91
	v_exp_f32_e32 v84, v84
	s_and_b64 s[2:3], s[0:1], vcc
	v_cmp_gt_i32_e32 vcc, v85, v98
	v_or_b32_e32 v85, 7, v82
	v_cndmask_b32_e64 v39, v39, 0, s[2:3]
	s_and_b64 s[2:3], s[0:1], vcc
	v_cmp_gt_i32_e32 vcc, v85, v98
	v_cndmask_b32_e64 v40, v40, 0, s[2:3]
	s_and_b64 s[2:3], s[0:1], vcc
	v_mul_f32_e32 v41, v41, v84
	v_cndmask_b32_e64 v41, v41, 0, s[2:3]
	v_cvt_pk_bf16_f32 v34, v34, v35
	v_cvt_pk_bf16_f32 v35, v36, v37
	v_cvt_pk_bf16_f32 v36, v38, v39
	v_cvt_pk_bf16_f32 v37, v40, v41
	ds_read_b128 v[38:41], v0 offset:26688
	ds_read_b128 v[84:87], v0 offset:26704
	v_or_b32_e32 v88, 16, v82
	v_cmp_gt_i32_e32 vcc, v88, v98
	s_and_b64 s[2:3], s[0:1], vcc
	s_waitcnt lgkmcnt(1)
	v_sub_f32_e32 v38, v99, v38
	v_exp_f32_e32 v38, v38
	v_sub_f32_e32 v39, v99, v39
	v_exp_f32_e32 v39, v39
	v_sub_f32_e32 v40, v99, v40
	v_mul_f32_e32 v38, v42, v38
	v_or_b32_e32 v42, 17, v82
	v_cmp_gt_i32_e32 vcc, v42, v98
	v_or_b32_e32 v42, 18, v82
	v_cndmask_b32_e64 v38, v38, 0, s[2:3]
	s_and_b64 s[2:3], s[0:1], vcc
	v_mul_f32_e32 v39, v43, v39
	v_exp_f32_e32 v40, v40
	v_cmp_gt_i32_e32 vcc, v42, v98
	v_sub_f32_e32 v41, v99, v41
	v_or_b32_e32 v42, 19, v82
	v_cndmask_b32_e64 v39, v39, 0, s[2:3]
	s_and_b64 s[2:3], s[0:1], vcc
	v_exp_f32_e32 v41, v41
	v_cmp_gt_i32_e32 vcc, v42, v98
	s_waitcnt lgkmcnt(0)
	v_sub_f32_e32 v42, v99, v84
	v_exp_f32_e32 v42, v42
	v_mul_f32_e32 v40, v44, v40
	v_or_b32_e32 v43, 20, v82
	v_cndmask_b32_e64 v40, v40, 0, s[2:3]
	s_and_b64 s[2:3], s[0:1], vcc
	v_mul_f32_e32 v41, v45, v41
	v_cmp_gt_i32_e32 vcc, v43, v98
	v_sub_f32_e32 v43, v99, v85
	v_or_b32_e32 v44, 21, v82
	v_cndmask_b32_e64 v41, v41, 0, s[2:3]
	s_and_b64 s[2:3], s[0:1], vcc
	v_mul_f32_e32 v42, v46, v42
	v_exp_f32_e32 v43, v43
	v_cmp_gt_i32_e32 vcc, v44, v98
	v_sub_f32_e32 v44, v99, v86
	v_or_b32_e32 v45, 22, v82
	v_cndmask_b32_e64 v42, v42, 0, s[2:3]
	s_and_b64 s[2:3], s[0:1], vcc
	v_exp_f32_e32 v44, v44
	v_cmp_gt_i32_e32 vcc, v45, v98
	v_sub_f32_e32 v45, v99, v87
	v_exp_f32_e32 v45, v45
	v_mul_f32_e32 v43, v47, v43
	v_or_b32_e32 v46, 23, v82
	v_cndmask_b32_e64 v43, v43, 0, s[2:3]
	s_and_b64 s[2:3], s[0:1], vcc
	v_mul_f32_e32 v44, v48, v44
	v_cmp_gt_i32_e32 vcc, v46, v98
	v_cndmask_b32_e64 v44, v44, 0, s[2:3]
	s_and_b64 s[2:3], s[0:1], vcc
	v_mul_f32_e32 v45, v49, v45
	v_cvt_pk_bf16_f32 v38, v38, v39
	v_cvt_pk_bf16_f32 v39, v40, v41
	v_cvt_pk_bf16_f32 v40, v42, v43
	v_add_u32_e32 v42, s7, v108
	v_cndmask_b32_e64 v45, v45, 0, s[2:3]
	v_add_u32_e32 v82, v42, v100
	v_cvt_pk_bf16_f32 v41, v44, v45
	ds_read_b128 v[42:45], v82 offset:17408
	ds_read_b128 v[46:49], v82 offset:17440
	s_waitcnt lgkmcnt(1)
	v_mfma_f32_32x32x16_bf16 v[2:17], v[42:45], v[34:37], v[2:17]
	ds_read_b128 v[42:45], v82 offset:22016
	s_or_b32 s2, s6, 32
	s_cmp_gt_i32 s2, s20
	s_waitcnt lgkmcnt(0)
	v_mfma_f32_32x32x16_bf16 v[18:33], v[42:45], v[34:37], v[18:33]
	ds_read_b128 v[34:37], v82 offset:22048
	v_mfma_f32_32x32x16_bf16 v[2:17], v[46:49], v[38:41], v[2:17]
	s_waitcnt lgkmcnt(0)
	v_mfma_f32_32x32x16_bf16 v[18:33], v[34:37], v[38:41], v[18:33]
	s_cbranch_scc1 .LBB0_684
; __device__ __forceinline__ unsigned pk2(float lo, float hi) { f32x2 v = {lo, hi}; bf16x2_t b = __builtin_convertvector(v, bf16x2_t); return __builtin_bit_cast(unsigned, b); }
; __device__ __forceinline__ float ex2(float x) { return __builtin_amdgcn_exp2f(x); }
; #define MFMA32(a, b, c) __builtin_amdgcn_mfma_f32_32x32x16_bf16((a), (b), (c), 0, 0, 0)
; template <int DQK, int DV, int MODE, int VR> ...
;     ...
;                     if (kv0 + 32 * kb > t0 + 31) continue;
;                     f32x16 p;
; #pragma unroll
;                     for (int r = 0; r < 16; ++r) p[r] = 0.f;
; #pragma unroll
;                     for (int ks = 0; ks < NKS; ++ks) { const bf16x8 a = *(const bf16x8*)(Kl + (32 * kb + pirow) * KSTR + (16 * ks + 8 * hi) * 2); p = MFMA32(a, qf[ks], p); }
;                     bf16x8 pb[2];
; #pragma unroll
;                     for (int sl = 0; sl < 2; ++sl) {
;                         const f32x4 s0 = *(const f32x4*)(Al + 32 * kb + 16 * sl + 8 * hi), s1 = *(const f32x4*)(Al + 32 * kb + 16 * sl + 8 * hi + 4);
;                         float e[8];
; #pragma unroll
;                         for (int jj = 0; jj < 8; ++jj) { const float as = jj < 4 ? s0[jj] : s1[jj - 4]; const int kv = kv0 + 32 * kb + 16 * sl + 8 * hi + jj;
;                             const float w = ex2(a2t - as); e[jj] = (diag && kv > t) ? 0.f : p[8 * sl + jj] * w; }
;                         u32x4 w; w.x = pk2(e[0], e[1]); w.y = pk2(e[2], e[3]); w.z = pk2(e[4], e[5]); w.w = pk2(e[6], e[7]);
;                         pb[sl] = __builtin_bit_cast(bf16x8, w);
;                     }
; #pragma unroll
;                     for (int b = 0; b < NBLK; ++b)
; #pragma unroll
;                         for (int sl = 0; sl < 2; ++sl) { const bf16x8 a = *(const bf16x8*)(Vl + (32 * b + r32) * VSTR + (32 * kb + 16 * sl + 8 * hi) * 2); o[b] = MFMA32(a, pb[sl], o[b]); }
	ds_read_b128 v[34:37], v83 offset:8704
	ds_read_b128 v[84:87], v83 offset:8736
	s_waitcnt lgkmcnt(1)
	v_mfma_f32_32x32x16_bf16 v[34:49], v[34:37], v[74:77], 0
	ds_read_b128 v[74:77], v83 offset:8768
	s_waitcnt lgkmcnt(1)
	v_mfma_f32_32x32x16_bf16 v[34:49], v[84:87], v[78:81], v[34:49]
	s_waitcnt lgkmcnt(0)
	v_mfma_f32_32x32x16_bf16 v[34:49], v[74:77], v[70:73], v[34:49]
	ds_read_b128 v[70:73], v83 offset:8800
	s_waitcnt lgkmcnt(0)
	v_mfma_f32_32x32x16_bf16 v[34:49], v[70:73], v[66:69], v[34:49]
	ds_read_b128 v[66:69], v83 offset:8832
	s_waitcnt lgkmcnt(0)
	v_mfma_f32_32x32x16_bf16 v[34:49], v[66:69], v[62:65], v[34:49]
	ds_read_b128 v[62:65], v83 offset:8864
	s_waitcnt lgkmcnt(0)
	v_mfma_f32_32x32x16_bf16 v[34:49], v[62:65], v[58:61], v[34:49]
	ds_read_b128 v[58:61], v83 offset:8896
	s_waitcnt lgkmcnt(0)
	v_mfma_f32_32x32x16_bf16 v[34:49], v[58:61], v[54:57], v[34:49]
	ds_read_b128 v[54:57], v83 offset:8928
	s_waitcnt lgkmcnt(0)
	v_mfma_f32_32x32x16_bf16 v[34:49], v[54:57], v[50:53], v[34:49]
	ds_read_b128 v[52:55], v0 offset:26752
	ds_read_b128 v[56:59], v0 offset:26768
	v_or_b32_e32 v50, s2, v107
	v_cmp_gt_i32_e32 vcc, v50, v98
	s_and_b64 s[2:3], s[0:1], vcc
	s_waitcnt lgkmcnt(1)
	v_sub_f32_e32 v51, v99, v52
	v_exp_f32_e32 v51, v51
	v_cmp_ge_i32_e32 vcc, v50, v98
	v_or_b32_e32 v52, 2, v50
	s_nop 1
	v_mul_f32_e32 v34, v34, v51
	v_sub_f32_e32 v51, v99, v53
	v_exp_f32_e32 v51, v51
	v_cndmask_b32_e64 v34, v34, 0, s[2:3]
	s_and_b64 s[2:3], s[0:1], vcc
	v_cmp_gt_i32_e32 vcc, v52, v98
	v_mul_f32_e32 v35, v35, v51
	v_sub_f32_e32 v51, v99, v54
	v_exp_f32_e32 v51, v51
	v_or_b32_e32 v52, 3, v50
	v_cndmask_b32_e64 v35, v35, 0, s[2:3]
	s_and_b64 s[2:3], s[0:1], vcc
	v_mul_f32_e32 v36, v36, v51
	v_sub_f32_e32 v51, v99, v55
	v_exp_f32_e32 v51, v51
	v_cmp_gt_i32_e32 vcc, v52, v98
	v_or_b32_e32 v52, 4, v50
	v_cndmask_b32_e64 v36, v36, 0, s[2:3]
	v_mul_f32_e32 v37, v37, v51
	s_waitcnt lgkmcnt(0)
	v_sub_f32_e32 v51, v99, v56
	v_exp_f32_e32 v51, v51
	s_and_b64 s[2:3], s[0:1], vcc
	v_cmp_gt_i32_e32 vcc, v52, v98
	v_or_b32_e32 v52, 5, v50
	v_mul_f32_e32 v38, v38, v51
	v_sub_f32_e32 v51, v99, v57
	v_exp_f32_e32 v51, v51
	v_cndmask_b32_e64 v37, v37, 0, s[2:3]
	s_and_b64 s[2:3], s[0:1], vcc
	v_cmp_gt_i32_e32 vcc, v52, v98
	v_mul_f32_e32 v39, v39, v51
	v_sub_f32_e32 v51, v99, v58
	v_exp_f32_e32 v51, v51
	v_or_b32_e32 v52, 6, v50
	v_cndmask_b32_e64 v38, v38, 0, s[2:3]
	s_and_b64 s[2:3], s[0:1], vcc
	v_mul_f32_e32 v40, v40, v51
	v_sub_f32_e32 v51, v99, v59
	v_exp_f32_e32 v51, v51
	v_cmp_gt_i32_e32 vcc, v52, v98
	v_or_b32_e32 v52, 7, v50
	v_cndmask_b32_e64 v39, v39, 0, s[2:3]
	s_and_b64 s[2:3], s[0:1], vcc
	v_cmp_gt_i32_e32 vcc, v52, v98
	v_cndmask_b32_e64 v40, v40, 0, s[2:3]
	s_and_b64 s[2:3], s[0:1], vcc
	v_mul_f32_e32 v41, v41, v51
	v_cndmask_b32_e64 v41, v41, 0, s[2:3]
	v_cvt_pk_bf16_f32 v34, v34, v35
	v_cvt_pk_bf16_f32 v35, v36, v37
	v_cvt_pk_bf16_f32 v36, v38, v39
	v_cvt_pk_bf16_f32 v37, v40, v41
	ds_read_b128 v[38:41], v0 offset:26816
	ds_read_b128 v[52:55], v0 offset:26832
	v_or_b32_e32 v0, 16, v50
	v_cmp_gt_i32_e32 vcc, v0, v98
	s_and_b64 s[2:3], s[0:1], vcc
	s_waitcnt lgkmcnt(1)
	v_sub_f32_e32 v38, v99, v38
	v_exp_f32_e32 v38, v38
	s_nop 0
	v_mul_f32_e32 v0, v42, v38
	v_sub_f32_e32 v38, v99, v39
	v_exp_f32_e32 v38, v38
	v_or_b32_e32 v39, 17, v50
	v_cmp_gt_i32_e32 vcc, v39, v98
	v_sub_f32_e32 v39, v99, v40
	v_or_b32_e32 v40, 18, v50
	v_cndmask_b32_e64 v0, v0, 0, s[2:3]
	s_and_b64 s[2:3], s[0:1], vcc
	v_mul_f32_e32 v38, v43, v38
	v_exp_f32_e32 v39, v39
	v_cmp_gt_i32_e32 vcc, v40, v98
	v_sub_f32_e32 v40, v99, v41
	v_or_b32_e32 v41, 19, v50
	v_cndmask_b32_e64 v38, v38, 0, s[2:3]
	s_and_b64 s[2:3], s[0:1], vcc
	v_exp_f32_e32 v40, v40
	v_cmp_gt_i32_e32 vcc, v41, v98
	s_waitcnt lgkmcnt(0)
	v_sub_f32_e32 v41, v99, v52
	v_exp_f32_e32 v41, v41
	v_mul_f32_e32 v39, v44, v39
	v_or_b32_e32 v42, 20, v50
	v_cndmask_b32_e64 v39, v39, 0, s[2:3]
	s_and_b64 s[2:3], s[0:1], vcc
	v_mul_f32_e32 v40, v45, v40
	v_cmp_gt_i32_e32 vcc, v42, v98
	v_sub_f32_e32 v42, v99, v53
	v_or_b32_e32 v43, 21, v50
	v_cndmask_b32_e64 v40, v40, 0, s[2:3]
	s_and_b64 s[2:3], s[0:1], vcc
	v_mul_f32_e32 v41, v46, v41
	v_exp_f32_e32 v42, v42
	v_cmp_gt_i32_e32 vcc, v43, v98
	v_or_b32_e32 v44, 22, v50
	v_cndmask_b32_e64 v41, v41, 0, s[2:3]
	s_and_b64 s[2:3], s[0:1], vcc
	v_sub_f32_e32 v43, v99, v54
	v_cmp_gt_i32_e32 vcc, v44, v98
	v_sub_f32_e32 v44, v99, v55
	v_exp_f32_e32 v43, v43
	v_exp_f32_e32 v44, v44
	v_mul_f32_e32 v42, v47, v42
	v_or_b32_e32 v45, 23, v50
	v_cndmask_b32_e64 v42, v42, 0, s[2:3]
	s_and_b64 s[2:3], s[0:1], vcc
	v_cmp_gt_i32_e32 vcc, v45, v98
	v_mul_f32_e32 v43, v48, v43
	s_and_b64 s[0:1], s[0:1], vcc
	v_mul_f32_e32 v44, v49, v44
	v_cndmask_b32_e64 v43, v43, 0, s[2:3]
	v_cndmask_b32_e64 v44, v44, 0, s[0:1]
	v_cvt_pk_bf16_f32 v39, v39, v40
	v_cvt_pk_bf16_f32 v40, v41, v42
	v_cvt_pk_bf16_f32 v41, v43, v44
	ds_read_b128 v[42:45], v82 offset:17472
	ds_read_b128 v[46:49], v82 offset:17504
	s_waitcnt lgkmcnt(1)
	v_mfma_f32_32x32x16_bf16 v[2:17], v[42:45], v[34:37], v[2:17]
	ds_read_b128 v[42:45], v82 offset:22080
	v_cvt_pk_bf16_f32 v38, v0, v38
	s_waitcnt lgkmcnt(0)
	v_mfma_f32_32x32x16_bf16 v[18:33], v[42:45], v[34:37], v[18:33]
	ds_read_b128 v[34:37], v82 offset:22112
	v_mfma_f32_32x32x16_bf16 v[2:17], v[46:49], v[38:41], v[2:17]
	s_waitcnt lgkmcnt(0)
	v_mfma_f32_32x32x16_bf16 v[18:33], v[34:37], v[38:41], v[18:33]

; __device__ __forceinline__ unsigned pk2(float lo, float hi) { f32x2 v = {lo, hi}; bf16x2_t b = __builtin_convertvector(v, bf16x2_t); return __builtin_bit_cast(unsigned, b); }
; template <int DQK, int DV, int MODE, int VR> ...
;     ...
;         constexpr int SSTR = DQK * 2 + 16, SP_OFF = STG, NLD = DV * DQK / 4 / 512;
;         static_assert(SP_OFF + DV * SSTR <= 147456, "Sprev staging");
; #pragma unroll 4
;         for (int i = 0; i < NLD; ++i) { const int idx = tid + 512 * i, e = idx / (DQK / 4), c4 = idx % (DQK / 4);
;             const f32x4 v = *(const f32x4*)(Sprev + (size_t)e * DQK + 4 * c4);
;             u32x2 w; w.x = pk2(v[0], v[1]); w.y = pk2(v[2], v[3]);
;             *(u32x2*)(lds + SP_OFF + e * SSTR + c4 * 8) = w; }
.LBB0_694:
	v_add_u32_e32 v8, s11, v179
	v_mov_b32_e32 v2, v8
	v_ashrrev_i32_e32 v3, 31, v2
	v_lshrrev_b32_e32 v3, 26, v3
	v_add_u32_e32 v3, v2, v3
	v_ashrrev_i32_e32 v6, 6, v3
	v_and_b32_e32 v3, 0xffffffc0, v3
	v_sub_u32_e32 v9, v2, v3
	v_ashrrev_i32_e32 v7, 31, v6
	v_lshlrev_b64 v[2:3], 10, v[6:7]
	v_lshlrev_b32_e32 v4, 2, v9
	v_lshl_add_u64 v[2:3], s[2:3], 0, v[2:3]
	v_ashrrev_i32_e32 v5, 31, v4
	v_lshl_add_u64 v[2:3], v[4:5], 2, v[2:3]
	global_load_dwordx4 v[182:185], v[2:3], off
	v_mul_lo_u32 v4, v6, s94
	v_lshlrev_b32_e32 v5, 3, v9
	v_add3_u32 v74, 16, v4, v5
	v_add_u32_e32 v2, 0x200, v8
	v_ashrrev_i32_e32 v3, 31, v2
	v_lshrrev_b32_e32 v3, 26, v3
	v_add_u32_e32 v3, v2, v3
	v_ashrrev_i32_e32 v6, 6, v3
	v_and_b32_e32 v3, 0xffffffc0, v3
	v_sub_u32_e32 v9, v2, v3
	v_ashrrev_i32_e32 v7, 31, v6
	v_lshlrev_b64 v[2:3], 10, v[6:7]
	v_lshlrev_b32_e32 v4, 2, v9
	v_lshl_add_u64 v[2:3], s[2:3], 0, v[2:3]
	v_ashrrev_i32_e32 v5, 31, v4
	v_lshl_add_u64 v[2:3], v[4:5], 2, v[2:3]
	global_load_dwordx4 v[186:189], v[2:3], off
	v_mul_lo_u32 v4, v6, s94
	v_lshlrev_b32_e32 v5, 3, v9
	v_add3_u32 v75, 16, v4, v5
	v_add_u32_e32 v2, 0x400, v8
	v_ashrrev_i32_e32 v3, 31, v2
	v_lshrrev_b32_e32 v3, 26, v3
	v_add_u32_e32 v3, v2, v3
	v_ashrrev_i32_e32 v6, 6, v3
	v_and_b32_e32 v3, 0xffffffc0, v3
	v_sub_u32_e32 v9, v2, v3
	v_ashrrev_i32_e32 v7, 31, v6
	v_lshlrev_b64 v[2:3], 10, v[6:7]
	v_lshlrev_b32_e32 v4, 2, v9
	v_lshl_add_u64 v[2:3], s[2:3], 0, v[2:3]
	v_ashrrev_i32_e32 v5, 31, v4
	v_lshl_add_u64 v[2:3], v[4:5], 2, v[2:3]
	global_load_dwordx4 v[190:193], v[2:3], off
	v_mul_lo_u32 v4, v6, s94
	v_lshlrev_b32_e32 v5, 3, v9
	v_add3_u32 v76, 16, v4, v5
	v_add_u32_e32 v2, 0x600, v8
	v_ashrrev_i32_e32 v3, 31, v2
	v_lshrrev_b32_e32 v3, 26, v3
	v_add_u32_e32 v3, v2, v3
	v_ashrrev_i32_e32 v6, 6, v3
	v_and_b32_e32 v3, 0xffffffc0, v3
	v_sub_u32_e32 v9, v2, v3
	v_ashrrev_i32_e32 v7, 31, v6
	v_lshlrev_b64 v[2:3], 10, v[6:7]
	v_lshlrev_b32_e32 v4, 2, v9
	v_lshl_add_u64 v[2:3], s[2:3], 0, v[2:3]
	v_ashrrev_i32_e32 v5, 31, v4
	v_lshl_add_u64 v[2:3], v[4:5], 2, v[2:3]
	global_load_dwordx4 v[204:207], v[2:3], off
	v_mul_lo_u32 v4, v6, s94
	v_lshlrev_b32_e32 v5, 3, v9
	v_add3_u32 v77, 16, v4, v5
	v_add_u32_e32 v2, 0x800, v8
	v_ashrrev_i32_e32 v3, 31, v2
	v_lshrrev_b32_e32 v3, 26, v3
	v_add_u32_e32 v3, v2, v3
	v_ashrrev_i32_e32 v6, 6, v3
	v_and_b32_e32 v3, 0xffffffc0, v3
	v_sub_u32_e32 v9, v2, v3
	v_ashrrev_i32_e32 v7, 31, v6
	v_lshlrev_b64 v[2:3], 10, v[6:7]
	v_lshlrev_b32_e32 v4, 2, v9
	v_lshl_add_u64 v[2:3], s[2:3], 0, v[2:3]
	v_ashrrev_i32_e32 v5, 31, v4
	v_lshl_add_u64 v[2:3], v[4:5], 2, v[2:3]
	global_load_dwordx4 v[208:211], v[2:3], off
	v_mul_lo_u32 v4, v6, s94
	v_lshlrev_b32_e32 v5, 3, v9
	v_add3_u32 v78, 16, v4, v5
	v_add_u32_e32 v2, 0xa00, v8
	v_ashrrev_i32_e32 v3, 31, v2
	v_lshrrev_b32_e32 v3, 26, v3
	v_add_u32_e32 v3, v2, v3
	v_ashrrev_i32_e32 v6, 6, v3
	v_and_b32_e32 v3, 0xffffffc0, v3
	v_sub_u32_e32 v9, v2, v3
	v_ashrrev_i32_e32 v7, 31, v6
	v_lshlrev_b64 v[2:3], 10, v[6:7]
	v_lshlrev_b32_e32 v4, 2, v9
	v_lshl_add_u64 v[2:3], s[2:3], 0, v[2:3]
	v_ashrrev_i32_e32 v5, 31, v4
	v_lshl_add_u64 v[2:3], v[4:5], 2, v[2:3]
	global_load_dwordx4 v[212:215], v[2:3], off
	v_mul_lo_u32 v4, v6, s94
	v_lshlrev_b32_e32 v5, 3, v9
	v_add3_u32 v79, 16, v4, v5
	v_add_u32_e32 v2, 0xc00, v8
	v_ashrrev_i32_e32 v3, 31, v2
	v_lshrrev_b32_e32 v3, 26, v3
	v_add_u32_e32 v3, v2, v3
	v_ashrrev_i32_e32 v6, 6, v3
	v_and_b32_e32 v3, 0xffffffc0, v3
	v_sub_u32_e32 v9, v2, v3
	v_ashrrev_i32_e32 v7, 31, v6
	v_lshlrev_b64 v[2:3], 10, v[6:7]
	v_lshlrev_b32_e32 v4, 2, v9
	v_lshl_add_u64 v[2:3], s[2:3], 0, v[2:3]
	v_ashrrev_i32_e32 v5, 31, v4
	v_lshl_add_u64 v[2:3], v[4:5], 2, v[2:3]
	global_load_dwordx4 v[216:219], v[2:3], off
	v_mul_lo_u32 v4, v6, s94
	v_lshlrev_b32_e32 v5, 3, v9
	v_add3_u32 v80, 16, v4, v5
	v_add_u32_e32 v2, 0xe00, v8
	v_ashrrev_i32_e32 v3, 31, v2
	v_lshrrev_b32_e32 v3, 26, v3
	v_add_u32_e32 v3, v2, v3
	v_ashrrev_i32_e32 v6, 6, v3
	v_and_b32_e32 v3, 0xffffffc0, v3
	v_sub_u32_e32 v9, v2, v3
	v_ashrrev_i32_e32 v7, 31, v6
	v_lshlrev_b64 v[2:3], 10, v[6:7]
	v_lshlrev_b32_e32 v4, 2, v9
	v_lshl_add_u64 v[2:3], s[2:3], 0, v[2:3]
	v_ashrrev_i32_e32 v5, 31, v4
	v_lshl_add_u64 v[2:3], v[4:5], 2, v[2:3]
	global_load_dwordx4 v[220:223], v[2:3], off
	v_mul_lo_u32 v4, v6, s94
	v_lshlrev_b32_e32 v5, 3, v9
	v_add3_u32 v81, 16, v4, v5
	s_waitcnt vmcnt(0)
	v_cvt_pk_bf16_f32 v182, v182, v183
	v_cvt_pk_bf16_f32 v183, v184, v185
	ds_write_b64 v74, v[182:183] offset:52480
	v_cvt_pk_bf16_f32 v186, v186, v187
	v_cvt_pk_bf16_f32 v187, v188, v189
	ds_write_b64 v75, v[186:187] offset:52480
	v_cvt_pk_bf16_f32 v190, v190, v191
	v_cvt_pk_bf16_f32 v191, v192, v193
	ds_write_b64 v76, v[190:191] offset:52480
	v_cvt_pk_bf16_f32 v204, v204, v205
	v_cvt_pk_bf16_f32 v205, v206, v207
	ds_write_b64 v77, v[204:205] offset:52480
	v_cvt_pk_bf16_f32 v208, v208, v209
	v_cvt_pk_bf16_f32 v209, v210, v211
	ds_write_b64 v78, v[208:209] offset:52480
	v_cvt_pk_bf16_f32 v212, v212, v213
	v_cvt_pk_bf16_f32 v213, v214, v215
	ds_write_b64 v79, v[212:213] offset:52480
	v_cvt_pk_bf16_f32 v216, v216, v217
	v_cvt_pk_bf16_f32 v217, v218, v219
	ds_write_b64 v80, v[216:217] offset:52480
	v_cvt_pk_bf16_f32 v220, v220, v221
	v_cvt_pk_bf16_f32 v221, v222, v223
	ds_write_b64 v81, v[220:221] offset:52480
	s_addk_i32 s11, 0x1000
	s_cmpk_eq_i32 s11, 0x2000
	s_cbranch_scc0 .LBB0_694
	v_mul_u32_u24_e32 v2, 0x210, v180
	v_add3_u32 v22, 16, v0, v2
	s_waitcnt lgkmcnt(0)
	s_barrier
; #define MFMA32(a, b, c) __builtin_amdgcn_mfma_f32_32x32x16_bf16((a), (b), (c), 0, 0, 0)
; template <int DQK, int DV, int MODE, int VR> ...
;     ...
; #pragma unroll
;         for (int b = 0; b < NBLK; ++b)
; #pragma unroll
;             for (int ks = 0; ks < NKS; ++ks) { const bf16x8 a = *(const bf16x8*)(lds + SP_OFF + (32 * b + r32) * SSTR + (16 * ks + 8 * hi) * 2); o[b] = MFMA32(a, qf[ks], o[b]); }
	ds_read_b128 v[2:5], v22 offset:52480
	ds_read_b128 v[18:21], v22 offset:52512
	s_waitcnt lgkmcnt(1)
	v_mfma_f32_32x32x16_bf16 v[2:17], v[2:5], v[138:141], 0
	v_add_u32_e32 v69, 0xcd00, v22
	s_mov_b32 s11, s87
	s_lshl_b64 s[2:3], s[10:11], 2
	s_add_u32 s2, s0, s2
	s_addc_u32 s3, s1, s3
	s_waitcnt lgkmcnt(0)
	v_mfma_f32_32x32x16_bf16 v[2:17], v[18:21], v[82:85], v[2:17]
	ds_read_b128 v[212:215], v22 offset:52544
	ds_read_b128 v[216:219], v22 offset:52576
	ds_read_b128 v[220:223], v22 offset:52608
	s_waitcnt lgkmcnt(2)
	v_mfma_f32_32x32x16_bf16 v[2:17], v[212:215], v[86:89], v[2:17]
	ds_read_b128 v[212:215], v22 offset:52640
	s_waitcnt lgkmcnt(2)
	v_mfma_f32_32x32x16_bf16 v[2:17], v[216:219], v[90:93], v[2:17]
	ds_read_b128 v[216:219], v22 offset:52672
	s_waitcnt lgkmcnt(2)
	v_mfma_f32_32x32x16_bf16 v[2:17], v[220:223], v[94:97], v[2:17]
	ds_read_b128 v[220:223], v22 offset:52704
	s_waitcnt lgkmcnt(2)
	v_mfma_f32_32x32x16_bf16 v[2:17], v[212:215], v[98:101], v[2:17]
	ds_read_b128 v[212:215], v22 offset:52736
	s_waitcnt lgkmcnt(2)
	v_mfma_f32_32x32x16_bf16 v[2:17], v[216:219], v[102:105], v[2:17]
	ds_read_b128 v[216:219], v22 offset:52768
	s_waitcnt lgkmcnt(2)
	v_mfma_f32_32x32x16_bf16 v[2:17], v[220:223], v[106:109], v[2:17]
	ds_read_b128 v[220:223], v22 offset:52800
	s_waitcnt lgkmcnt(2)
	v_mfma_f32_32x32x16_bf16 v[2:17], v[212:215], v[110:113], v[2:17]
	ds_read_b128 v[212:215], v22 offset:52832
	s_waitcnt lgkmcnt(2)
	v_mfma_f32_32x32x16_bf16 v[2:17], v[216:219], v[114:117], v[2:17]
	ds_read_b128 v[216:219], v22 offset:52864
	s_waitcnt lgkmcnt(2)
	v_mfma_f32_32x32x16_bf16 v[2:17], v[220:223], v[118:121], v[2:17]
	ds_read_b128 v[220:223], v22 offset:52896
	s_waitcnt lgkmcnt(2)
	v_mfma_f32_32x32x16_bf16 v[2:17], v[212:215], v[122:125], v[2:17]
	ds_read_b128 v[212:215], v22 offset:52928
	s_waitcnt lgkmcnt(2)
	v_mfma_f32_32x32x16_bf16 v[2:17], v[216:219], v[126:129], v[2:17]
	ds_read_b128 v[216:219], v22 offset:52960
	s_waitcnt lgkmcnt(2)
	v_mfma_f32_32x32x16_bf16 v[2:17], v[220:223], v[130:133], v[2:17]
	s_waitcnt lgkmcnt(1)
	v_mfma_f32_32x32x16_bf16 v[2:17], v[212:215], v[134:137], v[2:17]
	s_waitcnt lgkmcnt(0)
	v_mfma_f32_32x32x16_bf16 v[2:17], v[216:219], v[142:145], v[2:17]
	ds_read_b128 v[18:21], v69 offset:16896
	ds_read_b128 v[34:37], v69 offset:16928
	ds_read_b128 v[50:53], v69 offset:33824
	ds_read_b128 v[70:73], v69 offset:50720
	s_waitcnt lgkmcnt(3)
	v_mfma_f32_32x32x16_bf16 v[18:33], v[18:21], v[138:141], 0
	s_waitcnt lgkmcnt(2)
	v_mfma_f32_32x32x16_bf16 v[18:33], v[34:37], v[82:85], v[18:33]
	ds_read_b128 v[212:215], v69 offset:16960
	ds_read_b128 v[216:219], v69 offset:16992
	ds_read_b128 v[220:223], v69 offset:17024
	s_waitcnt lgkmcnt(2)
	v_mfma_f32_32x32x16_bf16 v[18:33], v[212:215], v[86:89], v[18:33]
	ds_read_b128 v[212:215], v69 offset:17056
	s_waitcnt lgkmcnt(2)
	v_mfma_f32_32x32x16_bf16 v[18:33], v[216:219], v[90:93], v[18:33]
	ds_read_b128 v[216:219], v69 offset:17088
	s_waitcnt lgkmcnt(2)
	v_mfma_f32_32x32x16_bf16 v[18:33], v[220:223], v[94:97], v[18:33]
	ds_read_b128 v[220:223], v69 offset:17120
	s_waitcnt lgkmcnt(2)
	v_mfma_f32_32x32x16_bf16 v[18:33], v[212:215], v[98:101], v[18:33]
	ds_read_b128 v[212:215], v69 offset:17152
	s_waitcnt lgkmcnt(2)
	v_mfma_f32_32x32x16_bf16 v[18:33], v[216:219], v[102:105], v[18:33]
	ds_read_b128 v[216:219], v69 offset:17184
	s_waitcnt lgkmcnt(2)
	v_mfma_f32_32x32x16_bf16 v[18:33], v[220:223], v[106:109], v[18:33]
	ds_read_b128 v[220:223], v69 offset:17216
	s_waitcnt lgkmcnt(2)
	v_mfma_f32_32x32x16_bf16 v[18:33], v[212:215], v[110:113], v[18:33]
	ds_read_b128 v[212:215], v69 offset:17248
	s_waitcnt lgkmcnt(2)
	v_mfma_f32_32x32x16_bf16 v[18:33], v[216:219], v[114:117], v[18:33]
	ds_read_b128 v[216:219], v69 offset:17280
	s_waitcnt lgkmcnt(2)
	v_mfma_f32_32x32x16_bf16 v[18:33], v[220:223], v[118:121], v[18:33]
	ds_read_b128 v[220:223], v69 offset:17312
	s_waitcnt lgkmcnt(2)
	v_mfma_f32_32x32x16_bf16 v[18:33], v[212:215], v[122:125], v[18:33]
	ds_read_b128 v[212:215], v69 offset:17344
	s_waitcnt lgkmcnt(2)
	v_mfma_f32_32x32x16_bf16 v[18:33], v[216:219], v[126:129], v[18:33]
	ds_read_b128 v[216:219], v69 offset:17376
	s_waitcnt lgkmcnt(2)
	v_mfma_f32_32x32x16_bf16 v[18:33], v[220:223], v[130:133], v[18:33]
	ds_read_b128 v[220:223], v69 offset:33792
	s_waitcnt lgkmcnt(2)
	v_mfma_f32_32x32x16_bf16 v[18:33], v[212:215], v[134:137], v[18:33]
	s_waitcnt lgkmcnt(1)
	v_mfma_f32_32x32x16_bf16 v[18:33], v[216:219], v[142:145], v[18:33]
	s_waitcnt lgkmcnt(0)
	v_mfma_f32_32x32x16_bf16 v[34:49], v[220:223], v[138:141], 0
	v_mfma_f32_32x32x16_bf16 v[34:49], v[50:53], v[82:85], v[34:49]
	ds_read_b128 v[212:215], v69 offset:33856
	ds_read_b128 v[216:219], v69 offset:33888
	ds_read_b128 v[220:223], v69 offset:33920
	s_waitcnt lgkmcnt(2)
	v_mfma_f32_32x32x16_bf16 v[34:49], v[212:215], v[86:89], v[34:49]
	ds_read_b128 v[212:215], v69 offset:33952
	s_waitcnt lgkmcnt(2)
	v_mfma_f32_32x32x16_bf16 v[34:49], v[216:219], v[90:93], v[34:49]
	ds_read_b128 v[216:219], v69 offset:33984
	s_waitcnt lgkmcnt(2)
	v_mfma_f32_32x32x16_bf16 v[34:49], v[220:223], v[94:97], v[34:49]
	ds_read_b128 v[220:223], v69 offset:34016
	s_waitcnt lgkmcnt(2)
	v_mfma_f32_32x32x16_bf16 v[34:49], v[212:215], v[98:101], v[34:49]
	ds_read_b128 v[212:215], v69 offset:34048
	s_waitcnt lgkmcnt(2)
; __device__ __forceinline__ float ex2(float x) { return __builtin_amdgcn_exp2f(x); }
; #define MFMA32(a, b, c) __builtin_amdgcn_mfma_f32_32x32x16_bf16((a), (b), (c), 0, 0, 0)
; template <int DQK, int DV, int MODE, int VR> ...
;     ...
; #pragma unroll
;         for (int b = 0; b < NBLK; ++b)
; #pragma unroll
;             for (int ks = 0; ks < NKS; ++ks) { const bf16x8 a = *(const bf16x8*)(lds + SP_OFF + (32 * b + r32) * SSTR + (16 * ks + 8 * hi) * 2); o[b] = MFMA32(a, qf[ks], o[b]); }
;         const float dq = ex2(a2t - a2[qb * 256 - 1]);
; #pragma unroll
;         for (int b = 0; b < NBLK; ++b)
; #pragma unroll
;             for (int r = 0; r < 16; ++r) o[b][r] *= dq;
	v_mfma_f32_32x32x16_bf16 v[34:49], v[216:219], v[102:105], v[34:49]
	ds_read_b128 v[216:219], v69 offset:34080
	s_waitcnt lgkmcnt(2)
	v_mfma_f32_32x32x16_bf16 v[34:49], v[220:223], v[106:109], v[34:49]
	ds_read_b128 v[220:223], v69 offset:34112
	s_waitcnt lgkmcnt(2)
	v_mfma_f32_32x32x16_bf16 v[34:49], v[212:215], v[110:113], v[34:49]
	ds_read_b128 v[212:215], v69 offset:34144
	s_waitcnt lgkmcnt(2)
	v_mfma_f32_32x32x16_bf16 v[34:49], v[216:219], v[114:117], v[34:49]
	ds_read_b128 v[216:219], v69 offset:34176
	s_waitcnt lgkmcnt(2)
	v_mfma_f32_32x32x16_bf16 v[34:49], v[220:223], v[118:121], v[34:49]
	ds_read_b128 v[220:223], v69 offset:34208
	s_waitcnt lgkmcnt(2)
	v_mfma_f32_32x32x16_bf16 v[34:49], v[212:215], v[122:125], v[34:49]
	ds_read_b128 v[212:215], v69 offset:34240
	s_waitcnt lgkmcnt(2)
	v_mfma_f32_32x32x16_bf16 v[34:49], v[216:219], v[126:129], v[34:49]
	ds_read_b128 v[216:219], v69 offset:34272
	s_waitcnt lgkmcnt(2)
	v_mfma_f32_32x32x16_bf16 v[34:49], v[220:223], v[130:133], v[34:49]
	ds_read_b128 v[220:223], v69 offset:50688
	s_waitcnt lgkmcnt(2)
	v_mfma_f32_32x32x16_bf16 v[34:49], v[212:215], v[134:137], v[34:49]
	s_waitcnt lgkmcnt(1)
	v_mfma_f32_32x32x16_bf16 v[34:49], v[216:219], v[142:145], v[34:49]
	s_waitcnt lgkmcnt(0)
	v_mfma_f32_32x32x16_bf16 v[50:65], v[220:223], v[138:141], 0
	v_mfma_f32_32x32x16_bf16 v[50:65], v[70:73], v[82:85], v[50:65]
	ds_read_b128 v[212:215], v69 offset:50752
	ds_read_b128 v[216:219], v69 offset:50784
	ds_read_b128 v[220:223], v69 offset:50816
	s_waitcnt lgkmcnt(2)
	v_mfma_f32_32x32x16_bf16 v[50:65], v[212:215], v[86:89], v[50:65]
	ds_read_b128 v[212:215], v69 offset:50848
	s_waitcnt lgkmcnt(2)
	v_mfma_f32_32x32x16_bf16 v[50:65], v[216:219], v[90:93], v[50:65]
	ds_read_b128 v[216:219], v69 offset:50880
	s_waitcnt lgkmcnt(2)
	v_mfma_f32_32x32x16_bf16 v[50:65], v[220:223], v[94:97], v[50:65]
	ds_read_b128 v[220:223], v69 offset:50912
	s_waitcnt lgkmcnt(2)
	v_mfma_f32_32x32x16_bf16 v[50:65], v[212:215], v[98:101], v[50:65]
	ds_read_b128 v[212:215], v69 offset:50944
	s_waitcnt lgkmcnt(2)
	v_mfma_f32_32x32x16_bf16 v[50:65], v[216:219], v[102:105], v[50:65]
	ds_read_b128 v[216:219], v69 offset:50976
	s_waitcnt lgkmcnt(2)
	v_mfma_f32_32x32x16_bf16 v[50:65], v[220:223], v[106:109], v[50:65]
	ds_read_b128 v[220:223], v69 offset:51008
	s_waitcnt lgkmcnt(2)
	v_mfma_f32_32x32x16_bf16 v[50:65], v[212:215], v[110:113], v[50:65]
	ds_read_b128 v[212:215], v69 offset:51040
	s_waitcnt lgkmcnt(2)
	v_mfma_f32_32x32x16_bf16 v[50:65], v[216:219], v[114:117], v[50:65]
	ds_read_b128 v[216:219], v69 offset:51072
	s_waitcnt lgkmcnt(2)
	v_mfma_f32_32x32x16_bf16 v[50:65], v[220:223], v[118:121], v[50:65]
	ds_read_b128 v[220:223], v69 offset:51104
	s_waitcnt lgkmcnt(2)
	v_mfma_f32_32x32x16_bf16 v[50:65], v[212:215], v[122:125], v[50:65]
	ds_read_b128 v[212:215], v69 offset:51136
	s_waitcnt lgkmcnt(2)
	v_mfma_f32_32x32x16_bf16 v[50:65], v[216:219], v[126:129], v[50:65]
	ds_read_b128 v[216:219], v69 offset:51168
	s_waitcnt lgkmcnt(2)
	v_mfma_f32_32x32x16_bf16 v[50:65], v[220:223], v[130:133], v[50:65]
	s_waitcnt lgkmcnt(1)
	v_mfma_f32_32x32x16_bf16 v[50:65], v[212:215], v[134:137], v[50:65]
	global_load_dword v69, v1, s[2:3] offset:-4
	s_waitcnt vmcnt(0)
	v_sub_f32_e32 v69, v175, v69
	s_waitcnt lgkmcnt(0)
	v_mfma_f32_32x32x16_bf16 v[50:65], v[216:219], v[142:145], v[50:65]
	v_exp_f32_e32 v70, v69
	s_nop 0
	v_pk_mul_f32 v[16:17], v[16:17], v[70:71] op_sel_hi:[1,0]
	v_pk_mul_f32 v[14:15], v[14:15], v[70:71] op_sel_hi:[1,0]
	v_pk_mul_f32 v[12:13], v[12:13], v[70:71] op_sel_hi:[1,0]
	v_pk_mul_f32 v[10:11], v[10:11], v[70:71] op_sel_hi:[1,0]
	v_pk_mul_f32 v[8:9], v[8:9], v[70:71] op_sel_hi:[1,0]
	v_pk_mul_f32 v[6:7], v[6:7], v[70:71] op_sel_hi:[1,0]
	v_pk_mul_f32 v[4:5], v[4:5], v[70:71] op_sel_hi:[1,0]
	v_pk_mul_f32 v[2:3], v[2:3], v[70:71] op_sel_hi:[1,0]
	v_pk_mul_f32 v[32:33], v[32:33], v[70:71] op_sel_hi:[1,0]
	v_pk_mul_f32 v[30:31], v[30:31], v[70:71] op_sel_hi:[1,0]
	v_pk_mul_f32 v[28:29], v[28:29], v[70:71] op_sel_hi:[1,0]
	v_pk_mul_f32 v[26:27], v[26:27], v[70:71] op_sel_hi:[1,0]
	v_pk_mul_f32 v[24:25], v[24:25], v[70:71] op_sel_hi:[1,0]
	v_pk_mul_f32 v[22:23], v[22:23], v[70:71] op_sel_hi:[1,0]
	v_pk_mul_f32 v[20:21], v[20:21], v[70:71] op_sel_hi:[1,0]
	v_pk_mul_f32 v[18:19], v[18:19], v[70:71] op_sel_hi:[1,0]
	v_pk_mul_f32 v[48:49], v[48:49], v[70:71] op_sel_hi:[1,0]
	v_pk_mul_f32 v[46:47], v[46:47], v[70:71] op_sel_hi:[1,0]
	v_pk_mul_f32 v[44:45], v[44:45], v[70:71] op_sel_hi:[1,0]
	v_pk_mul_f32 v[42:43], v[42:43], v[70:71] op_sel_hi:[1,0]
	v_pk_mul_f32 v[40:41], v[40:41], v[70:71] op_sel_hi:[1,0]
	v_pk_mul_f32 v[38:39], v[38:39], v[70:71] op_sel_hi:[1,0]
	v_pk_mul_f32 v[36:37], v[36:37], v[70:71] op_sel_hi:[1,0]
	v_pk_mul_f32 v[34:35], v[34:35], v[70:71] op_sel_hi:[1,0]
	v_pk_mul_f32 v[64:65], v[64:65], v[70:71] op_sel_hi:[1,0]
	v_pk_mul_f32 v[62:63], v[62:63], v[70:71] op_sel_hi:[1,0]
	v_pk_mul_f32 v[60:61], v[60:61], v[70:71] op_sel_hi:[1,0]
	v_pk_mul_f32 v[58:59], v[58:59], v[70:71] op_sel_hi:[1,0]
	v_pk_mul_f32 v[56:57], v[56:57], v[70:71] op_sel_hi:[1,0]
	v_pk_mul_f32 v[54:55], v[54:55], v[70:71] op_sel_hi:[1,0]
	v_pk_mul_f32 v[52:53], v[52:53], v[70:71] op_sel_hi:[1,0]
	v_pk_mul_f32 v[50:51], v[50:51], v[70:71] op_sel_hi:[1,0]
	s_branch .LBB0_750

; #define MFMA32(a, b, c) __builtin_amdgcn_mfma_f32_32x32x16_bf16((a), (b), (c), 0, 0, 0)
; template <int DQK, int DV, int MODE, int VR> ...
;     ...
;             if (kv0 <= t0 + 31) {
;                 const unsigned char* Kl = lds + (j % 3) * STG; const unsigned char* Vl = Kl + KBYTES;
;                 const bool diag = (kv0 + 63 > t0);
;                 f32x16 p[2];
; #pragma unroll
;                 for (int kb = 0; kb < 2; ++kb)
; #pragma unroll
;                     for (int r = 0; r < 16; ++r) p[kb][r] = 0.f;
;                 {
;                     constexpr int NS = 2 * NKS;
;                     const unsigned char* kb0 = Kl + pirow * KSTR + 16 * hi;
;     ...
;                     bf16x8 af[3]; af[0] = AT_KF(0); af[1] = AT_KF(1);
; #pragma unroll
;                     for (int i = 0; i < NS; ++i) { if (i + 2 < NS) af[(i + 2) % 3] = AT_KF(i + 2); p[i & 1] = MFMA32(af[i % 3], qf[i >> 1], p[i & 1]); }
;     ...
;                     __builtin_amdgcn_sched_group_barrier(0x100, 2, 0);
; #pragma unroll
;                     for (int i = 0; i < NS - 2; ++i) { __builtin_amdgcn_sched_group_barrier(0x100, 1, 0); __builtin_amdgcn_sched_group_barrier(0x8, 1, 0); }
;                     __builtin_amdgcn_sched_group_barrier(0x8, 2, 0);
;                 }
;                 if (diag) {
; #pragma unroll
;                     for (int kb = 0; kb < 2; ++kb)
; #pragma unroll
;                         for (int r = 0; r < 16; ++r) { const int kv = kv0 + 32 * kb + 16 * (r >> 3) + 8 * hi + (r & 7); if (kv > t) p[kb][r] = -INFINITY; }
;                 }
.LBB0_737:
	s_sub_i32 s4, s79, 63
	s_cmp_gt_i32 s4, s63
	s_cbranch_scc1 .LBB0_743
	s_mul_hi_u32 s4, s76, 0xaaaaaaab
	s_lshr_b32 s30, s4, 1
	s_mul_i32 s30, s30, 0x20700
	v_subrev_u32_e32 v0, s30, v174
	v_add_u32_e32 v180, s64, v176
	v_add_u32_e32 v0, v180, v0
	ds_read_b128 v[66:69], v0
	ds_read_b128 v[70:73], v0 offset:12800
	ds_read_b128 v[184:187], v0 offset:32
	s_cmp_le_i32 s79, s86
	s_waitcnt lgkmcnt(2)
	v_mfma_f32_32x32x16_bf16 v[82:97], v[66:69], v[98:101], 0
	ds_read_b128 v[188:191], v0 offset:12832
	s_waitcnt lgkmcnt(2)
	v_mfma_f32_32x32x16_bf16 v[66:81], v[70:73], v[98:101], 0
	ds_read_b128 v[204:207], v0 offset:64
	s_waitcnt lgkmcnt(2)
	v_mfma_f32_32x32x16_bf16 v[82:97], v[184:187], v[102:105], v[82:97]
	ds_read_b128 v[184:187], v0 offset:12864
	s_waitcnt lgkmcnt(2)
	v_mfma_f32_32x32x16_bf16 v[66:81], v[188:191], v[102:105], v[66:81]
	ds_read_b128 v[188:191], v0 offset:96
	s_waitcnt lgkmcnt(2)
	v_mfma_f32_32x32x16_bf16 v[82:97], v[204:207], v[106:109], v[82:97]
	ds_read_b128 v[204:207], v0 offset:12896
	s_waitcnt lgkmcnt(2)
	v_mfma_f32_32x32x16_bf16 v[66:81], v[184:187], v[106:109], v[66:81]
	ds_read_b128 v[184:187], v0 offset:128
	s_waitcnt lgkmcnt(2)
	v_mfma_f32_32x32x16_bf16 v[82:97], v[188:191], v[110:113], v[82:97]
	ds_read_b128 v[188:191], v0 offset:12928
	s_waitcnt lgkmcnt(2)
	v_mfma_f32_32x32x16_bf16 v[66:81], v[204:207], v[110:113], v[66:81]
	ds_read_b128 v[204:207], v0 offset:160
	s_waitcnt lgkmcnt(2)
	v_mfma_f32_32x32x16_bf16 v[82:97], v[184:187], v[114:117], v[82:97]
	ds_read_b128 v[184:187], v0 offset:12960
	s_waitcnt lgkmcnt(2)
	v_mfma_f32_32x32x16_bf16 v[66:81], v[188:191], v[114:117], v[66:81]
	ds_read_b128 v[188:191], v0 offset:192
	s_waitcnt lgkmcnt(2)
	v_mfma_f32_32x32x16_bf16 v[82:97], v[204:207], v[118:121], v[82:97]
	ds_read_b128 v[204:207], v0 offset:12992
	s_waitcnt lgkmcnt(2)
	v_mfma_f32_32x32x16_bf16 v[66:81], v[184:187], v[118:121], v[66:81]
	ds_read_b128 v[184:187], v0 offset:224
	s_waitcnt lgkmcnt(2)
	v_mfma_f32_32x32x16_bf16 v[82:97], v[188:191], v[122:125], v[82:97]
	ds_read_b128 v[188:191], v0 offset:13024
	s_waitcnt lgkmcnt(2)
	v_mfma_f32_32x32x16_bf16 v[66:81], v[204:207], v[122:125], v[66:81]
	ds_read_b128 v[204:207], v0 offset:256
	s_waitcnt lgkmcnt(2)
	v_mfma_f32_32x32x16_bf16 v[82:97], v[184:187], v[126:129], v[82:97]
	ds_read_b128 v[184:187], v0 offset:13056
	s_waitcnt lgkmcnt(2)
	v_mfma_f32_32x32x16_bf16 v[66:81], v[188:191], v[126:129], v[66:81]
	ds_read_b128 v[188:191], v0 offset:288
	s_waitcnt lgkmcnt(2)
	v_mfma_f32_32x32x16_bf16 v[82:97], v[204:207], v[130:133], v[82:97]
	ds_read_b128 v[204:207], v0 offset:13088
	s_waitcnt lgkmcnt(2)
	v_mfma_f32_32x32x16_bf16 v[66:81], v[184:187], v[130:133], v[66:81]
	ds_read_b128 v[184:187], v0 offset:320
	s_waitcnt lgkmcnt(2)
	v_mfma_f32_32x32x16_bf16 v[82:97], v[188:191], v[134:137], v[82:97]
	ds_read_b128 v[188:191], v0 offset:13120
	s_waitcnt lgkmcnt(2)
	v_mfma_f32_32x32x16_bf16 v[66:81], v[204:207], v[134:137], v[66:81]
	ds_read_b128 v[204:207], v0 offset:352
	s_waitcnt lgkmcnt(2)
	v_mfma_f32_32x32x16_bf16 v[82:97], v[184:187], v[138:141], v[82:97]
	ds_read_b128 v[184:187], v0 offset:13152
	s_waitcnt lgkmcnt(2)
	v_mfma_f32_32x32x16_bf16 v[66:81], v[188:191], v[138:141], v[66:81]
	s_waitcnt lgkmcnt(1)
	v_mfma_f32_32x32x16_bf16 v[82:97], v[204:207], v[142:145], v[82:97]
	s_waitcnt lgkmcnt(0)
	v_mfma_f32_32x32x16_bf16 v[66:81], v[184:187], v[142:145], v[66:81]
	s_cbranch_scc1 .LBB0_740
	v_add_u32_e32 v0, s79, v173
	v_subrev_u32_e32 v177, 63, v0
	v_cmp_gt_i32_e32 vcc, v177, v172
	s_nop 6
	v_cndmask_b32_e32 v183, v82, v227, vcc
	v_cmp_lt_i32_e32 vcc, v177, v172
	v_subrev_u32_e32 v177, 61, v0
	s_nop 0
	v_cndmask_b32_e32 v82, v183, v82, vcc
	v_cndmask_b32_e32 v83, v227, v83, vcc
	v_cmp_le_i32_e32 vcc, v177, v172
	v_subrev_u32_e32 v177, 60, v0
	s_nop 0
	v_cndmask_b32_e32 v84, v227, v84, vcc
	v_cmp_le_i32_e32 vcc, v177, v172
	v_subrev_u32_e32 v177, 59, v0
	s_nop 0
	v_cndmask_b32_e32 v85, v227, v85, vcc
	v_cmp_le_i32_e32 vcc, v177, v172
	v_subrev_u32_e32 v177, 58, v0
	s_nop 0
	v_cndmask_b32_e32 v86, v227, v86, vcc
	v_cmp_le_i32_e32 vcc, v177, v172
	v_subrev_u32_e32 v177, 57, v0
	s_nop 0
	v_cndmask_b32_e32 v87, v227, v87, vcc
	v_cmp_le_i32_e32 vcc, v177, v172
	v_subrev_u32_e32 v177, 56, v0
	s_nop 0
	v_cndmask_b32_e32 v88, v227, v88, vcc
	v_cmp_le_i32_e32 vcc, v177, v172
	v_subrev_u32_e32 v177, 47, v0
	s_nop 0
	v_cndmask_b32_e32 v89, v227, v89, vcc
	v_cmp_le_i32_e32 vcc, v177, v172
	v_subrev_u32_e32 v177, 46, v0
	s_nop 0
	v_cndmask_b32_e32 v90, v227, v90, vcc
	v_cmp_le_i32_e32 vcc, v177, v172
	v_subrev_u32_e32 v177, 45, v0
	s_nop 0
	v_cndmask_b32_e32 v91, v227, v91, vcc
	v_cmp_le_i32_e32 vcc, v177, v172
	v_subrev_u32_e32 v177, 44, v0
	s_nop 0
	v_cndmask_b32_e32 v92, v227, v92, vcc
	v_cmp_le_i32_e32 vcc, v177, v172
	v_subrev_u32_e32 v177, 43, v0
	s_nop 0
	v_cndmask_b32_e32 v93, v227, v93, vcc
	v_cmp_le_i32_e32 vcc, v177, v172
	v_subrev_u32_e32 v177, 42, v0
	s_nop 0
	v_cndmask_b32_e32 v94, v227, v94, vcc
	v_cmp_le_i32_e32 vcc, v177, v172
	v_subrev_u32_e32 v177, 41, v0
	s_nop 0
	v_cndmask_b32_e32 v95, v227, v95, vcc
	v_cmp_le_i32_e32 vcc, v177, v172
	v_subrev_u32_e32 v177, 40, v0
	s_nop 0
	v_cndmask_b32_e32 v96, v227, v96, vcc
	v_cmp_le_i32_e32 vcc, v177, v172
	v_subrev_u32_e32 v177, 31, v0
	s_nop 0
	v_cndmask_b32_e32 v97, v227, v97, vcc
	v_cmp_le_i32_e32 vcc, v177, v172
	v_subrev_u32_e32 v177, 30, v0
	s_nop 0
	v_cndmask_b32_e32 v66, v227, v66, vcc
	v_cmp_le_i32_e32 vcc, v177, v172
	v_subrev_u32_e32 v177, 29, v0
	s_nop 0
	v_cndmask_b32_e32 v67, v227, v67, vcc
	v_cmp_le_i32_e32 vcc, v177, v172
	v_subrev_u32_e32 v177, 28, v0
	s_nop 0
	v_cndmask_b32_e32 v68, v227, v68, vcc
; __device__ __forceinline__ float ex2(float x) { return __builtin_amdgcn_exp2f(x); }
; template <int DQK, int DV, int MODE, int VR> ...
;     ...
;                 float mx = fmaxf(p[0][0], p[1][0]);
; #pragma unroll
;                 for (int r = 1; r < 16; ++r) mx = fmaxf(mx, fmaxf(p[0][r], p[1][r]));
;                 mx = fmaxf(mx, __shfl_xor(mx, 32));
;                 const float mnew = fmaxf(mrun, mx * cscale), alpha = ex2(mrun - mnew); float ls = 0.f;
; #pragma unroll
;                 for (int kb = 0; kb < 2; ++kb)
; #pragma unroll
;                     for (int r = 0; r < 16; ++r) { const float e = ex2(p[kb][r] * cscale - mnew); p[kb][r] = e; ls += e; }
;                 lrun = lrun * alpha + ls;
;                 if (__any(mnew > mrun)) {
; #pragma unroll
;                     for (int b = 0; b < NBLK; ++b)
; #pragma unroll
;                         for (int r = 0; r < 16; ++r) o[b][r] *= alpha;
;                 }
	v_cmp_le_i32_e32 vcc, v177, v172
	v_subrev_u32_e32 v177, 27, v0
	s_nop 0
	v_cndmask_b32_e32 v69, v227, v69, vcc
	v_cmp_le_i32_e32 vcc, v177, v172
	v_subrev_u32_e32 v177, 26, v0
	s_nop 0
	v_cndmask_b32_e32 v70, v227, v70, vcc
	v_cmp_le_i32_e32 vcc, v177, v172
	v_subrev_u32_e32 v177, 25, v0
	s_nop 0
	v_cndmask_b32_e32 v71, v227, v71, vcc
	v_cmp_le_i32_e32 vcc, v177, v172
	v_subrev_u32_e32 v177, 24, v0
	s_nop 0
	v_cndmask_b32_e32 v72, v227, v72, vcc
	v_cmp_le_i32_e32 vcc, v177, v172
	v_add_u32_e32 v177, -15, v0
	s_nop 0
	v_cndmask_b32_e32 v73, v227, v73, vcc
	v_cmp_le_i32_e32 vcc, v177, v172
	v_add_u32_e32 v177, -14, v0
	s_nop 0
	v_cndmask_b32_e32 v74, v227, v74, vcc
	v_cmp_le_i32_e32 vcc, v177, v172
	v_add_u32_e32 v177, -13, v0
	s_nop 0
	v_cndmask_b32_e32 v75, v227, v75, vcc
	v_cmp_le_i32_e32 vcc, v177, v172
	v_add_u32_e32 v177, -12, v0
	s_nop 0
	v_cndmask_b32_e32 v76, v227, v76, vcc
	v_cmp_le_i32_e32 vcc, v177, v172
	v_add_u32_e32 v177, -11, v0
	s_nop 0
	v_cndmask_b32_e32 v77, v227, v77, vcc
	v_cmp_le_i32_e32 vcc, v177, v172
	v_add_u32_e32 v177, -10, v0
	s_nop 0
	v_cndmask_b32_e32 v78, v227, v78, vcc
	v_cmp_le_i32_e32 vcc, v177, v172
	v_add_u32_e32 v177, -9, v0
	v_add_u32_e32 v0, -8, v0
	v_cndmask_b32_e32 v79, v227, v79, vcc
	v_cmp_le_i32_e32 vcc, v177, v172
	s_nop 1
	v_cndmask_b32_e32 v80, v227, v80, vcc
	v_cmp_le_i32_e32 vcc, v0, v172
	s_nop 1
	v_cndmask_b32_e32 v81, v227, v81, vcc
.LBB0_740:
	s_nop 10
	v_max3_f32 v0, v66, v67, v68
	v_max3_f32 v177, v82, v83, v84
	v_max3_f32 v0, v0, v69, v70
	v_max3_f32 v177, v177, v85, v86
	v_max3_f32 v0, v0, v71, v72
	v_max3_f32 v177, v177, v87, v88
	v_max3_f32 v0, v0, v73, v74
	v_max3_f32 v177, v177, v89, v90
	v_max3_f32 v0, v0, v75, v76
	v_max3_f32 v177, v177, v91, v92
	v_max3_f32 v0, v0, v77, v78
	v_max3_f32 v177, v177, v93, v94
	v_max3_f32 v0, v0, v79, v80
	v_max3_f32 v177, v177, v95, v96
	v_max_f32_e32 v0, v0, v81
	v_max_f32_e32 v177, v177, v97
	v_max_f32_e32 v0, v0, v177
	v_and_b32_e32 v183, 64, v195
	v_xor_b32_e32 v177, 32, v195
	v_add_u32_e32 v183, 64, v183
	v_cmp_lt_i32_e32 vcc, v177, v183
	s_nop 1
	v_cndmask_b32_e32 v177, v195, v177, vcc
	v_lshlrev_b32_e32 v177, 2, v177
	ds_bpermute_b32 v177, v177, v0
	s_waitcnt lgkmcnt(0)
	v_max_f32_e32 v177, v177, v177
	v_max_f32_e32 v0, v0, v177
	v_mul_f32_e32 v0, 0x3dd53b94, v0
	v_max_f32_e32 v177, v182, v182
	v_max_f32_e32 v177, v177, v0
	v_sub_f32_e32 v0, v182, v177
	v_exp_f32_e32 v0, v0
	v_cmp_gt_f32_e32 vcc, v177, v182
	s_cbranch_vccz .LBB0_742
	v_pk_mul_f32 v[64:65], v[64:65], v[0:1] op_sel_hi:[1,0]
	v_pk_mul_f32 v[62:63], v[62:63], v[0:1] op_sel_hi:[1,0]
	v_pk_mul_f32 v[60:61], v[60:61], v[0:1] op_sel_hi:[1,0]
	v_pk_mul_f32 v[58:59], v[58:59], v[0:1] op_sel_hi:[1,0]
	v_pk_mul_f32 v[56:57], v[56:57], v[0:1] op_sel_hi:[1,0]
	v_pk_mul_f32 v[54:55], v[54:55], v[0:1] op_sel_hi:[1,0]
	v_pk_mul_f32 v[52:53], v[52:53], v[0:1] op_sel_hi:[1,0]
	v_pk_mul_f32 v[50:51], v[50:51], v[0:1] op_sel_hi:[1,0]
	v_pk_mul_f32 v[48:49], v[48:49], v[0:1] op_sel_hi:[1,0]
	v_pk_mul_f32 v[46:47], v[46:47], v[0:1] op_sel_hi:[1,0]
	v_pk_mul_f32 v[44:45], v[44:45], v[0:1] op_sel_hi:[1,0]
	v_pk_mul_f32 v[42:43], v[42:43], v[0:1] op_sel_hi:[1,0]
	v_pk_mul_f32 v[40:41], v[40:41], v[0:1] op_sel_hi:[1,0]
	v_pk_mul_f32 v[38:39], v[38:39], v[0:1] op_sel_hi:[1,0]
	v_pk_mul_f32 v[36:37], v[36:37], v[0:1] op_sel_hi:[1,0]
	v_pk_mul_f32 v[34:35], v[34:35], v[0:1] op_sel_hi:[1,0]
	v_pk_mul_f32 v[32:33], v[32:33], v[0:1] op_sel_hi:[1,0]
	v_pk_mul_f32 v[30:31], v[30:31], v[0:1] op_sel_hi:[1,0]
	v_pk_mul_f32 v[28:29], v[28:29], v[0:1] op_sel_hi:[1,0]
	v_pk_mul_f32 v[26:27], v[26:27], v[0:1] op_sel_hi:[1,0]
	v_pk_mul_f32 v[24:25], v[24:25], v[0:1] op_sel_hi:[1,0]
	v_pk_mul_f32 v[22:23], v[22:23], v[0:1] op_sel_hi:[1,0]
	v_pk_mul_f32 v[20:21], v[20:21], v[0:1] op_sel_hi:[1,0]
	v_pk_mul_f32 v[18:19], v[18:19], v[0:1] op_sel_hi:[1,0]
	v_pk_mul_f32 v[16:17], v[16:17], v[0:1] op_sel_hi:[1,0]
	v_pk_mul_f32 v[14:15], v[14:15], v[0:1] op_sel_hi:[1,0]
	v_pk_mul_f32 v[12:13], v[12:13], v[0:1] op_sel_hi:[1,0]
	v_pk_mul_f32 v[10:11], v[10:11], v[0:1] op_sel_hi:[1,0]
	v_pk_mul_f32 v[8:9], v[8:9], v[0:1] op_sel_hi:[1,0]
	v_pk_mul_f32 v[6:7], v[6:7], v[0:1] op_sel_hi:[1,0]
	v_pk_mul_f32 v[4:5], v[4:5], v[0:1] op_sel_hi:[1,0]
	v_pk_mul_f32 v[2:3], v[2:3], v[0:1] op_sel_hi:[1,0]
; __device__ __forceinline__ unsigned pk2(float lo, float hi) { f32x2 v = {lo, hi}; bf16x2_t b = __builtin_convertvector(v, bf16x2_t); return __builtin_bit_cast(unsigned, b); }
; __device__ __forceinline__ float ex2(float x) { return __builtin_amdgcn_exp2f(x); }
; #define MFMA32(a, b, c) __builtin_amdgcn_mfma_f32_32x32x16_bf16((a), (b), (c), 0, 0, 0)
; template <int DQK, int DV, int MODE, int VR> ...
;     ...
;                 const float mnew = fmaxf(mrun, mx * cscale), alpha = ex2(mrun - mnew); float ls = 0.f;
; #pragma unroll
;                 for (int kb = 0; kb < 2; ++kb)
; #pragma unroll
;                     for (int r = 0; r < 16; ++r) { const float e = ex2(p[kb][r] * cscale - mnew); p[kb][r] = e; ls += e; }
;                 lrun = lrun * alpha + ls;
;                 if (__any(mnew > mrun)) {
; #pragma unroll
;                     for (int b = 0; b < NBLK; ++b)
; #pragma unroll
;                         for (int r = 0; r < 16; ++r) o[b][r] *= alpha;
;                 }
;                 mrun = mnew;
;                 bf16x8 pb[2][2];
; #pragma unroll
;                 for (int kb = 0; kb < 2; ++kb)
; #pragma unroll
;                     for (int sl = 0; sl < 2; ++sl) { u32x4 w; w.x = pk2(p[kb][8 * sl + 0], p[kb][8 * sl + 1]); w.y = pk2(p[kb][8 * sl + 2], p[kb][8 * sl + 3]); w.z = pk2(p[kb][8 * sl + 4], p[kb][8 * sl + 5]); w.w = pk2(p[kb][8 * sl + 6], p[kb][8 * sl + 7]);
;                         pb[kb][sl] = __builtin_bit_cast(bf16x8, w); }
;                 {
;                     constexpr int NP = 4 * NBLK;
;                     const unsigned char* vb0 = Vl + r32 * VSTR + 16 * hi;
;     ...
;                     bf16x8 vf[3]; vf[0] = AT_VF(0); vf[1] = AT_VF(1);
; #pragma unroll
;                     for (int i = 0; i < NP; ++i) { if (i + 2 < NP) vf[(i + 2) % 3] = AT_VF(i + 2); o[i % NBLK] = MFMA32(vf[i % 3], pb[(i / NBLK) >> 1][(i / NBLK) & 1], o[i % NBLK]); }
;     ...
;                     __builtin_amdgcn_sched_group_barrier(0x100, 2, 1);
; #pragma unroll
;                     for (int i = 0; i < NP - 2; ++i) { __builtin_amdgcn_sched_group_barrier(0x100, 1, 1); __builtin_amdgcn_sched_group_barrier(0x8, 1, 1); }
;                     __builtin_amdgcn_sched_group_barrier(0x8, 2, 1);
;                 }
.LBB0_742:
	v_fma_f32 v82, v82, s83, -v177
	v_exp_f32_e32 v82, v82
	v_fma_f32 v83, v83, s83, -v177
	v_exp_f32_e32 v83, v83
	v_fma_f32 v84, v84, s83, -v177
	v_exp_f32_e32 v84, v84
	v_fma_f32 v85, v85, s83, -v177
	v_exp_f32_e32 v85, v85
	v_fma_f32 v86, v86, s83, -v177
	v_add_f32_e32 v182, 0, v82
	v_exp_f32_e32 v86, v86
	v_fma_f32 v87, v87, s83, -v177
	v_add_f32_e32 v182, v83, v182
	v_exp_f32_e32 v87, v87
	v_fma_f32 v88, v88, s83, -v177
	v_add_f32_e32 v182, v84, v182
	v_exp_f32_e32 v88, v88
	v_fma_f32 v89, v89, s83, -v177
	v_add_f32_e32 v182, v85, v182
	v_exp_f32_e32 v89, v89
	v_fma_f32 v90, v90, s83, -v177
	v_add_f32_e32 v182, v86, v182
	v_exp_f32_e32 v90, v90
	v_fma_f32 v91, v91, s83, -v177
	v_add_f32_e32 v182, v87, v182
	v_exp_f32_e32 v91, v91
	v_fma_f32 v92, v92, s83, -v177
	v_add_f32_e32 v182, v88, v182
	v_exp_f32_e32 v92, v92
	v_fma_f32 v93, v93, s83, -v177
	v_add_f32_e32 v182, v89, v182
	v_exp_f32_e32 v93, v93
	v_fma_f32 v94, v94, s83, -v177
	v_add_f32_e32 v182, v90, v182
	v_exp_f32_e32 v94, v94
	v_fma_f32 v95, v95, s83, -v177
	v_add_f32_e32 v182, v91, v182
	v_exp_f32_e32 v95, v95
	v_fma_f32 v96, v96, s83, -v177
	v_add_f32_e32 v182, v92, v182
	v_exp_f32_e32 v96, v96
	v_fma_f32 v97, v97, s83, -v177
	v_add_f32_e32 v182, v93, v182
	v_exp_f32_e32 v97, v97
	v_fma_f32 v66, v66, s83, -v177
	v_add_f32_e32 v182, v94, v182
	v_exp_f32_e32 v66, v66
	v_fma_f32 v67, v67, s83, -v177
	v_add_f32_e32 v182, v95, v182
	v_exp_f32_e32 v67, v67
	v_fma_f32 v68, v68, s83, -v177
	v_add_f32_e32 v182, v96, v182
	v_exp_f32_e32 v68, v68
	v_fma_f32 v69, v69, s83, -v177
	v_add_f32_e32 v182, v97, v182
	v_exp_f32_e32 v69, v69
	v_fma_f32 v70, v70, s83, -v177
	v_add_f32_e32 v182, v66, v182
	v_exp_f32_e32 v183, v70
	v_add_f32_e32 v182, v67, v182
	v_add_f32_e32 v182, v68, v182
	v_add_f32_e32 v182, v69, v182
	v_fma_f32 v71, v71, s83, -v177
	v_add_f32_e32 v70, v183, v182
	v_exp_f32_e32 v182, v71
	v_fma_f32 v71, v72, s83, -v177
	v_exp_f32_e32 v184, v71
	v_fma_f32 v71, v73, s83, -v177
	v_exp_f32_e32 v73, v71
	v_fma_f32 v71, v74, s83, -v177
	v_exp_f32_e32 v185, v71
	v_fma_f32 v71, v75, s83, -v177
	v_add_f32_e32 v70, v182, v70
	v_exp_f32_e32 v186, v71
	v_fma_f32 v71, v76, s83, -v177
	v_add_f32_e32 v70, v184, v70
	v_exp_f32_e32 v187, v71
	v_fma_f32 v71, v77, s83, -v177
	v_add_f32_e32 v70, v73, v70
	v_exp_f32_e32 v188, v71
	v_fma_f32 v71, v78, s83, -v177
	v_add_f32_e32 v70, v185, v70
	v_exp_f32_e32 v189, v71
	v_fma_f32 v71, v79, s83, -v177
	v_add_f32_e32 v70, v186, v70
	v_exp_f32_e32 v79, v71
	v_fma_f32 v71, v80, s83, -v177
	v_add_f32_e32 v70, v187, v70
	v_exp_f32_e32 v190, v71
	v_fma_f32 v71, v81, s83, -v177
	v_add_f32_e32 v70, v188, v70
	v_exp_f32_e32 v191, v71
	v_add_f32_e32 v70, v189, v70
	v_add_f32_e32 v70, v79, v70
	v_add_f32_e32 v70, v190, v70
	v_add_f32_e32 v78, v191, v70
	v_fmac_f32_e32 v78, v181, v0
	v_subrev_u32_e32 v0, s30, v175
	v_add_u32_e32 v0, v180, v0
	v_cvt_pk_bf16_f32 v80, v82, v83
	v_cvt_pk_bf16_f32 v81, v84, v85
	v_cvt_pk_bf16_f32 v82, v86, v87
	v_cvt_pk_bf16_f32 v83, v88, v89
	v_cvt_pk_bf16_f32 v74, v90, v91
	v_cvt_pk_bf16_f32 v75, v92, v93
	v_cvt_pk_bf16_f32 v76, v94, v95
	ds_read_b128 v[84:87], v0 offset:30208
	ds_read_b128 v[88:91], v0 offset:34816
	ds_read_b128 v[92:95], v0 offset:25600
	v_cvt_pk_bf16_f32 v72, v183, v182
	s_waitcnt lgkmcnt(0)
	v_mfma_f32_32x32x16_bf16 v[50:65], v[92:95], v[80:83], v[50:65]
	ds_read_b128 v[180:183], v0 offset:25632
	v_cvt_pk_bf16_f32 v77, v96, v97
	v_cvt_pk_bf16_f32 v70, v66, v67
	v_cvt_pk_bf16_f32 v71, v68, v69
	v_cvt_pk_bf16_f32 v73, v184, v73
	v_cvt_pk_bf16_f32 v66, v185, v186
	v_cvt_pk_bf16_f32 v67, v187, v188
	v_mfma_f32_32x32x16_bf16 v[34:49], v[84:87], v[80:83], v[34:49]
	ds_read_b128 v[92:95], v0 offset:39424
	v_cvt_pk_bf16_f32 v68, v189, v79
	v_cvt_pk_bf16_f32 v69, v190, v191
	v_mfma_f32_32x32x16_bf16 v[18:33], v[88:91], v[80:83], v[18:33]
	ds_read_b128 v[84:87], v0 offset:30240
	s_waitcnt lgkmcnt(1)
	v_mfma_f32_32x32x16_bf16 v[2:17], v[92:95], v[80:83], v[2:17]
	ds_read_b128 v[80:83], v0 offset:34848
	v_mfma_f32_32x32x16_bf16 v[50:65], v[180:183], v[74:77], v[50:65]
	ds_read_b128 v[88:91], v0 offset:39456
	v_mov_b32_e32 v181, v78
	s_waitcnt lgkmcnt(2)
	v_mfma_f32_32x32x16_bf16 v[34:49], v[84:87], v[74:77], v[34:49]
	ds_read_b128 v[84:87], v0 offset:25664
	s_waitcnt lgkmcnt(2)
	v_mfma_f32_32x32x16_bf16 v[18:33], v[80:83], v[74:77], v[18:33]
	ds_read_b128 v[80:83], v0 offset:30272
	s_waitcnt lgkmcnt(2)
	v_mfma_f32_32x32x16_bf16 v[2:17], v[88:91], v[74:77], v[2:17]
	ds_read_b128 v[74:77], v0 offset:34880
	s_waitcnt lgkmcnt(2)
	v_mfma_f32_32x32x16_bf16 v[50:65], v[84:87], v[70:73], v[50:65]
	ds_read_b128 v[84:87], v0 offset:39488
	s_waitcnt lgkmcnt(2)
	v_mfma_f32_32x32x16_bf16 v[34:49], v[80:83], v[70:73], v[34:49]
	ds_read_b128 v[80:83], v0 offset:25696
	s_waitcnt lgkmcnt(2)
	v_mfma_f32_32x32x16_bf16 v[18:33], v[74:77], v[70:73], v[18:33]
	ds_read_b128 v[74:77], v0 offset:30304
	s_waitcnt lgkmcnt(2)
	v_mfma_f32_32x32x16_bf16 v[2:17], v[84:87], v[70:73], v[2:17]
	ds_read_b128 v[70:73], v0 offset:34912
	s_waitcnt lgkmcnt(2)
	v_mfma_f32_32x32x16_bf16 v[50:65], v[80:83], v[66:69], v[50:65]
	ds_read_b128 v[80:83], v0 offset:39520
	s_waitcnt lgkmcnt(2)
	v_mfma_f32_32x32x16_bf16 v[34:49], v[74:77], v[66:69], v[34:49]
	s_waitcnt lgkmcnt(1)
	v_mfma_f32_32x32x16_bf16 v[18:33], v[70:73], v[66:69], v[18:33]
	s_waitcnt lgkmcnt(0)
	v_mfma_f32_32x32x16_bf16 v[2:17], v[80:83], v[66:69], v[2:17]
	s_mov_b64 s[30:31], -1
	s_and_b64 vcc, exec, s[60:61]
	s_cbranch_vccnz .LBB0_744
	s_branch .LBB0_745

; __device__ __forceinline__ unsigned pk2(float lo, float hi) { f32x2 v = {lo, hi}; bf16x2_t b = __builtin_convertvector(v, bf16x2_t); return __builtin_bit_cast(unsigned, b); }
; __device__ __forceinline__ float ex2(float x) { return __builtin_amdgcn_exp2f(x); }
; #define MFMA32(a, b, c) __builtin_amdgcn_mfma_f32_32x32x16_bf16((a), (b), (c), 0, 0, 0)
; template <int DQK, int DV, int MODE, int VR> ...
;     ...
;                 for (int kb = 0; kb < 2; ++kb) {
;                     if (kv0 + 32 * kb > t0 + 31) continue;
;                     f32x16 p;
; #pragma unroll
;                     for (int r = 0; r < 16; ++r) p[r] = 0.f;
; #pragma unroll
;                     for (int ks = 0; ks < NKS; ++ks) { const bf16x8 a = *(const bf16x8*)(Kl + (32 * kb + pirow) * KSTR + (16 * ks + 8 * hi) * 2); p = MFMA32(a, qf[ks], p); }
;                     bf16x8 pb[2];
; #pragma unroll
;                     for (int sl = 0; sl < 2; ++sl) {
;                         const f32x4 s0 = *(const f32x4*)(Al + 32 * kb + 16 * sl + 8 * hi), s1 = *(const f32x4*)(Al + 32 * kb + 16 * sl + 8 * hi + 4);
;                         float e[8];
; #pragma unroll
;                         for (int jj = 0; jj < 8; ++jj) { const float as = jj < 4 ? s0[jj] : s1[jj - 4]; const int kv = kv0 + 32 * kb + 16 * sl + 8 * hi + jj;
;                             const float w = ex2(a2t - as); e[jj] = (diag && kv > t) ? 0.f : p[8 * sl + jj] * w; }
;                         u32x4 w; w.x = pk2(e[0], e[1]); w.y = pk2(e[2], e[3]); w.z = pk2(e[4], e[5]); w.w = pk2(e[6], e[7]);
.LBB0_764:
	s_bitcmp1_b32 s24, 0
	s_cselect_b32 s2, 0xcd00, 0
	s_add_i32 s24, s2, 16
	v_add_u32_e32 v66, s24, v0
	v_add_u32_e32 v189, v66, v184
	v_add_u32_e32 v188, v66, v0
	ds_read_b128 v[66:69], v189
	ds_read_b128 v[190:193], v189 offset:32
	s_add_i32 s2, s25, 63
	s_cmp_gt_i32 s2, s14
	s_waitcnt lgkmcnt(1)
	v_mfma_f32_32x32x16_bf16 v[66:81], v[66:69], v[138:141], 0
	v_add_u32_e32 v187, s22, v186
	s_cselect_b64 s[2:3], -1, 0
	v_cmp_gt_i32_e32 vcc, v187, v174
	s_and_b64 s[12:13], s[2:3], vcc
	v_cmp_ge_i32_e32 vcc, v187, v174
	v_add_u32_e32 v199, 16, v187
	s_add_i32 s25, s25, 32
	s_waitcnt lgkmcnt(0)
	v_mfma_f32_32x32x16_bf16 v[66:81], v[190:193], v[82:85], v[66:81]
	ds_read_b128 v[212:215], v189 offset:64
	ds_read_b128 v[216:219], v189 offset:96
	ds_read_b128 v[220:223], v189 offset:128
	s_waitcnt lgkmcnt(2)
	v_mfma_f32_32x32x16_bf16 v[66:81], v[212:215], v[86:89], v[66:81]
	ds_read_b128 v[212:215], v189 offset:160
	s_waitcnt lgkmcnt(2)
	v_mfma_f32_32x32x16_bf16 v[66:81], v[216:219], v[90:93], v[66:81]
	ds_read_b128 v[216:219], v189 offset:192
	s_waitcnt lgkmcnt(2)
	v_mfma_f32_32x32x16_bf16 v[66:81], v[220:223], v[94:97], v[66:81]
	ds_read_b128 v[220:223], v189 offset:224
	s_waitcnt lgkmcnt(2)
	v_mfma_f32_32x32x16_bf16 v[66:81], v[212:215], v[98:101], v[66:81]
	ds_read_b128 v[212:215], v189 offset:256
	s_waitcnt lgkmcnt(2)
	v_mfma_f32_32x32x16_bf16 v[66:81], v[216:219], v[102:105], v[66:81]
	ds_read_b128 v[216:219], v189 offset:288
	s_waitcnt lgkmcnt(2)
	v_mfma_f32_32x32x16_bf16 v[66:81], v[220:223], v[106:109], v[66:81]
	ds_read_b128 v[220:223], v189 offset:320
	s_waitcnt lgkmcnt(2)
	v_mfma_f32_32x32x16_bf16 v[66:81], v[212:215], v[110:113], v[66:81]
	ds_read_b128 v[212:215], v189 offset:352
	s_waitcnt lgkmcnt(2)
	v_mfma_f32_32x32x16_bf16 v[66:81], v[216:219], v[114:117], v[66:81]
	ds_read_b128 v[216:219], v189 offset:384
	s_waitcnt lgkmcnt(2)
	v_mfma_f32_32x32x16_bf16 v[66:81], v[220:223], v[118:121], v[66:81]
	ds_read_b128 v[220:223], v189 offset:416
	s_waitcnt lgkmcnt(2)
	v_mfma_f32_32x32x16_bf16 v[66:81], v[212:215], v[122:125], v[66:81]
	ds_read_b128 v[212:215], v189 offset:448
	s_waitcnt lgkmcnt(2)
	v_mfma_f32_32x32x16_bf16 v[66:81], v[216:219], v[126:129], v[66:81]
	ds_read_b128 v[216:219], v189 offset:480
	s_waitcnt lgkmcnt(2)
	v_mfma_f32_32x32x16_bf16 v[66:81], v[220:223], v[130:133], v[66:81]
	s_waitcnt lgkmcnt(1)
	v_mfma_f32_32x32x16_bf16 v[66:81], v[212:215], v[134:137], v[66:81]
	s_waitcnt lgkmcnt(0)
	v_mfma_f32_32x32x16_bf16 v[66:81], v[216:219], v[142:145], v[66:81]
	ds_read_b128 v[190:193], v188 offset:52224
	ds_read_b128 v[204:207], v188 offset:52240
	s_waitcnt lgkmcnt(1)
	v_sub_f32_e32 v190, v175, v190
	v_exp_f32_e32 v190, v190
	s_nop 6
	v_mul_f32_e32 v66, v66, v190
	v_sub_f32_e32 v190, v175, v191
	v_exp_f32_e32 v190, v190
	v_add_u32_e32 v191, 2, v187
	v_cndmask_b32_e64 v66, v66, 0, s[12:13]
	s_and_b64 s[12:13], s[2:3], vcc
	v_mul_f32_e32 v67, v67, v190
	v_sub_f32_e32 v190, v175, v192
	v_exp_f32_e32 v190, v190
	v_cmp_gt_i32_e32 vcc, v191, v174
	v_add_u32_e32 v191, 3, v187
	v_cndmask_b32_e64 v67, v67, 0, s[12:13]
	v_mul_f32_e32 v68, v68, v190
	v_sub_f32_e32 v190, v175, v193
	v_exp_f32_e32 v190, v190
	s_and_b64 s[12:13], s[2:3], vcc
	v_cmp_gt_i32_e32 vcc, v191, v174
	v_add_u32_e32 v191, 4, v187
	v_mul_f32_e32 v69, v69, v190
	s_waitcnt lgkmcnt(0)
	v_sub_f32_e32 v190, v175, v204
	v_exp_f32_e32 v190, v190
	v_cndmask_b32_e64 v68, v68, 0, s[12:13]
	s_and_b64 s[12:13], s[2:3], vcc
	v_cmp_gt_i32_e32 vcc, v191, v174
	v_mul_f32_e32 v70, v70, v190
	v_sub_f32_e32 v190, v175, v205
	v_exp_f32_e32 v190, v190
	v_add_u32_e32 v191, 5, v187
	v_cndmask_b32_e64 v69, v69, 0, s[12:13]
	s_and_b64 s[12:13], s[2:3], vcc
	v_mul_f32_e32 v71, v71, v190
	v_sub_f32_e32 v190, v175, v206
	v_exp_f32_e32 v190, v190
	v_cmp_gt_i32_e32 vcc, v191, v174
	v_add_u32_e32 v191, 6, v187
	v_cndmask_b32_e64 v70, v70, 0, s[12:13]
	v_mul_f32_e32 v72, v72, v190
	v_sub_f32_e32 v190, v175, v207
	v_exp_f32_e32 v190, v190
	s_and_b64 s[12:13], s[2:3], vcc
	v_cmp_gt_i32_e32 vcc, v191, v174
	v_add_u32_e32 v191, 7, v187
	v_cndmask_b32_e64 v71, v71, 0, s[12:13]
	s_and_b64 s[12:13], s[2:3], vcc
	v_cmp_gt_i32_e32 vcc, v191, v174
	v_cndmask_b32_e64 v72, v72, 0, s[12:13]
	s_and_b64 s[12:13], s[2:3], vcc
	v_mul_f32_e32 v73, v73, v190
	v_cndmask_b32_e64 v73, v73, 0, s[12:13]
	v_cvt_pk_bf16_f32 v66, v66, v67
	v_cvt_pk_bf16_f32 v67, v68, v69
	v_cvt_pk_bf16_f32 v68, v70, v71
	v_cvt_pk_bf16_f32 v69, v72, v73
	ds_read_b128 v[190:193], v188 offset:52288
	ds_read_b128 v[70:73], v188 offset:52304
	v_cmp_gt_i32_e32 vcc, v199, v174
	s_and_b64 s[12:13], s[2:3], vcc
	s_waitcnt lgkmcnt(1)
	v_sub_f32_e32 v190, v175, v190
	v_exp_f32_e32 v190, v190
	s_waitcnt lgkmcnt(0)
; __device__ __forceinline__ unsigned pk2(float lo, float hi) { f32x2 v = {lo, hi}; bf16x2_t b = __builtin_convertvector(v, bf16x2_t); return __builtin_bit_cast(unsigned, b); }
; __device__ __forceinline__ float ex2(float x) { return __builtin_amdgcn_exp2f(x); }
; #define MFMA32(a, b, c) __builtin_amdgcn_mfma_f32_32x32x16_bf16((a), (b), (c), 0, 0, 0)
; template <int DQK, int DV, int MODE, int VR> ...
;     ...
;                     if (kv0 + 32 * kb > t0 + 31) continue;
;                     f32x16 p;
; #pragma unroll
;                     for (int r = 0; r < 16; ++r) p[r] = 0.f;
; #pragma unroll
;                     for (int ks = 0; ks < NKS; ++ks) { const bf16x8 a = *(const bf16x8*)(Kl + (32 * kb + pirow) * KSTR + (16 * ks + 8 * hi) * 2); p = MFMA32(a, qf[ks], p); }
;                     bf16x8 pb[2];
; #pragma unroll
;                     for (int sl = 0; sl < 2; ++sl) {
;                         const f32x4 s0 = *(const f32x4*)(Al + 32 * kb + 16 * sl + 8 * hi), s1 = *(const f32x4*)(Al + 32 * kb + 16 * sl + 8 * hi + 4);
;                         float e[8];
; #pragma unroll
;                         for (int jj = 0; jj < 8; ++jj) { const float as = jj < 4 ? s0[jj] : s1[jj - 4]; const int kv = kv0 + 32 * kb + 16 * sl + 8 * hi + jj;
;                             const float w = ex2(a2t - as); e[jj] = (diag && kv > t) ? 0.f : p[8 * sl + jj] * w; }
;                         u32x4 w; w.x = pk2(e[0], e[1]); w.y = pk2(e[2], e[3]); w.z = pk2(e[4], e[5]); w.w = pk2(e[6], e[7]);
;                         pb[sl] = __builtin_bit_cast(bf16x8, w);
;                     }
; #pragma unroll
;                     for (int b = 0; b < NBLK; ++b)
; #pragma unroll
;                         for (int sl = 0; sl < 2; ++sl) { const bf16x8 a = *(const bf16x8*)(Vl + (32 * b + r32) * VSTR + (32 * kb + 16 * sl + 8 * hi) * 2); o[b] = MFMA32(a, pb[sl], o[b]); }
	v_sub_f32_e32 v70, v175, v70
	v_exp_f32_e32 v70, v70
	v_mul_f32_e32 v74, v74, v190
	v_sub_f32_e32 v190, v175, v191
	v_exp_f32_e32 v190, v190
	v_add_u32_e32 v191, 17, v187
	v_cmp_gt_i32_e32 vcc, v191, v174
	v_add_u32_e32 v191, 18, v187
	v_mul_f32_e32 v75, v75, v190
	v_sub_f32_e32 v190, v175, v192
	v_exp_f32_e32 v190, v190
	v_cndmask_b32_e64 v74, v74, 0, s[12:13]
	s_and_b64 s[12:13], s[2:3], vcc
	v_cmp_gt_i32_e32 vcc, v191, v174
	v_mul_f32_e32 v76, v76, v190
	v_sub_f32_e32 v190, v175, v193
	v_exp_f32_e32 v190, v190
	v_add_u32_e32 v191, 19, v187
	v_cndmask_b32_e64 v75, v75, 0, s[12:13]
	s_and_b64 s[12:13], s[2:3], vcc
	v_cmp_gt_i32_e32 vcc, v191, v174
	v_mul_f32_e32 v77, v77, v190
	v_add_u32_e32 v190, 20, v187
	v_cndmask_b32_e64 v76, v76, 0, s[12:13]
	s_and_b64 s[12:13], s[2:3], vcc
	v_cmp_gt_i32_e32 vcc, v190, v174
	v_cndmask_b32_e64 v77, v77, 0, s[12:13]
	s_and_b64 s[12:13], s[2:3], vcc
	v_mul_f32_e32 v70, v78, v70
	v_cndmask_b32_e64 v78, v70, 0, s[12:13]
	v_sub_f32_e32 v70, v175, v71
	v_exp_f32_e32 v70, v70
	v_add_u32_e32 v71, 21, v187
	v_cmp_gt_i32_e32 vcc, v71, v174
	s_and_b64 s[12:13], s[2:3], vcc
	v_mul_f32_e32 v70, v79, v70
	v_cndmask_b32_e64 v79, v70, 0, s[12:13]
	v_sub_f32_e32 v70, v175, v72
	v_exp_f32_e32 v70, v70
	v_add_u32_e32 v71, 22, v187
	v_cmp_gt_i32_e32 vcc, v71, v174
	s_and_b64 s[12:13], s[2:3], vcc
	v_mul_f32_e32 v70, v80, v70
	v_cndmask_b32_e64 v80, v70, 0, s[12:13]
	v_sub_f32_e32 v70, v175, v73
	v_exp_f32_e32 v70, v70
	v_add_u32_e32 v71, 23, v187
	v_cmp_gt_i32_e32 vcc, v71, v174
	s_and_b64 s[12:13], s[2:3], vcc
	v_mul_f32_e32 v70, v81, v70
	v_cndmask_b32_e64 v73, v70, 0, s[12:13]
	v_cvt_pk_bf16_f32 v70, v74, v75
	v_add_u32_e32 v74, s24, v185
	v_add_u32_e32 v190, v74, v0
	v_cvt_pk_bf16_f32 v71, v76, v77
	v_cvt_pk_bf16_f32 v72, v78, v79
	v_cvt_pk_bf16_f32 v73, v80, v73
	ds_read_b128 v[74:77], v190 offset:33792
	ds_read_b128 v[78:81], v190 offset:33824
	s_waitcnt lgkmcnt(1)
	v_mfma_f32_32x32x16_bf16 v[2:17], v[74:77], v[66:69], v[2:17]
	ds_read_b128 v[212:215], v190 offset:38400
	ds_read_b128 v[216:219], v190 offset:38432
	ds_read_b128 v[220:223], v190 offset:43008
	s_cmp_gt_i32 s25, s21
	s_waitcnt lgkmcnt(2)
	v_mfma_f32_32x32x16_bf16 v[18:33], v[212:215], v[66:69], v[18:33]
	ds_read_b128 v[212:215], v190 offset:43040
	s_waitcnt lgkmcnt(2)
	v_mfma_f32_32x32x16_bf16 v[18:33], v[216:219], v[70:73], v[18:33]
	ds_read_b128 v[216:219], v190 offset:47616
	s_waitcnt lgkmcnt(2)
	v_mfma_f32_32x32x16_bf16 v[34:49], v[220:223], v[66:69], v[34:49]
	s_waitcnt lgkmcnt(1)
	v_mfma_f32_32x32x16_bf16 v[34:49], v[212:215], v[70:73], v[34:49]
	s_waitcnt lgkmcnt(0)
	v_mfma_f32_32x32x16_bf16 v[50:65], v[216:219], v[66:69], v[50:65]
	ds_read_b128 v[66:69], v190 offset:47648
	v_mfma_f32_32x32x16_bf16 v[2:17], v[78:81], v[70:73], v[2:17]
	s_waitcnt lgkmcnt(0)
	v_mfma_f32_32x32x16_bf16 v[50:65], v[66:69], v[70:73], v[50:65]
	s_cbranch_scc1 .LBB0_766
	ds_read_b128 v[66:69], v189 offset:16896
	ds_read_b128 v[204:207], v189 offset:16928
	s_waitcnt lgkmcnt(1)
	v_mfma_f32_32x32x16_bf16 v[66:81], v[66:69], v[138:141], 0
	s_waitcnt lgkmcnt(0)
	v_mfma_f32_32x32x16_bf16 v[66:81], v[204:207], v[82:85], v[66:81]
	ds_read_b128 v[212:215], v189 offset:16960
	ds_read_b128 v[216:219], v189 offset:16992
	ds_read_b128 v[220:223], v189 offset:17024
	s_waitcnt lgkmcnt(2)
	v_mfma_f32_32x32x16_bf16 v[66:81], v[212:215], v[86:89], v[66:81]
	ds_read_b128 v[212:215], v189 offset:17056
	s_waitcnt lgkmcnt(2)
	v_mfma_f32_32x32x16_bf16 v[66:81], v[216:219], v[90:93], v[66:81]
	ds_read_b128 v[216:219], v189 offset:17088
	s_waitcnt lgkmcnt(2)
	v_mfma_f32_32x32x16_bf16 v[66:81], v[220:223], v[94:97], v[66:81]
	ds_read_b128 v[220:223], v189 offset:17120
	s_waitcnt lgkmcnt(2)
	v_mfma_f32_32x32x16_bf16 v[66:81], v[212:215], v[98:101], v[66:81]
	ds_read_b128 v[212:215], v189 offset:17152
	s_waitcnt lgkmcnt(2)
	v_mfma_f32_32x32x16_bf16 v[66:81], v[216:219], v[102:105], v[66:81]
	ds_read_b128 v[216:219], v189 offset:17184
	s_waitcnt lgkmcnt(2)
	v_mfma_f32_32x32x16_bf16 v[66:81], v[220:223], v[106:109], v[66:81]
	ds_read_b128 v[220:223], v189 offset:17216
	s_waitcnt lgkmcnt(2)
	v_mfma_f32_32x32x16_bf16 v[66:81], v[212:215], v[110:113], v[66:81]
	ds_read_b128 v[212:215], v189 offset:17248
	s_waitcnt lgkmcnt(2)
	v_mfma_f32_32x32x16_bf16 v[66:81], v[216:219], v[114:117], v[66:81]
	ds_read_b128 v[216:219], v189 offset:17280
	s_waitcnt lgkmcnt(2)
	v_mfma_f32_32x32x16_bf16 v[66:81], v[220:223], v[118:121], v[66:81]
	ds_read_b128 v[220:223], v189 offset:17312
	s_waitcnt lgkmcnt(2)
	v_mfma_f32_32x32x16_bf16 v[66:81], v[212:215], v[122:125], v[66:81]
	ds_read_b128 v[212:215], v189 offset:17344
	s_waitcnt lgkmcnt(2)
	v_mfma_f32_32x32x16_bf16 v[66:81], v[216:219], v[126:129], v[66:81]
	ds_read_b128 v[216:219], v189 offset:17376
	s_waitcnt lgkmcnt(2)
	v_mfma_f32_32x32x16_bf16 v[66:81], v[220:223], v[130:133], v[66:81]
	s_waitcnt lgkmcnt(1)
	v_mfma_f32_32x32x16_bf16 v[66:81], v[212:215], v[134:137], v[66:81]
	v_add_u32_e32 v189, 32, v187
	v_cmp_gt_i32_e32 vcc, v189, v174
	s_and_b64 s[12:13], s[2:3], vcc
	v_cmp_ge_i32_e32 vcc, v189, v174
	s_waitcnt lgkmcnt(0)
; __device__ __forceinline__ unsigned pk2(float lo, float hi) { f32x2 v = {lo, hi}; bf16x2_t b = __builtin_convertvector(v, bf16x2_t); return __builtin_bit_cast(unsigned, b); }
; __device__ __forceinline__ float ex2(float x) { return __builtin_amdgcn_exp2f(x); }
; #define MFMA32(a, b, c) __builtin_amdgcn_mfma_f32_32x32x16_bf16((a), (b), (c), 0, 0, 0)
; template <int DQK, int DV, int MODE, int VR> ...
;     ...
;                     for (int ks = 0; ks < NKS; ++ks) { const bf16x8 a = *(const bf16x8*)(Kl + (32 * kb + pirow) * KSTR + (16 * ks + 8 * hi) * 2); p = MFMA32(a, qf[ks], p); }
;                     bf16x8 pb[2];
; #pragma unroll
;                     for (int sl = 0; sl < 2; ++sl) {
;                         const f32x4 s0 = *(const f32x4*)(Al + 32 * kb + 16 * sl + 8 * hi), s1 = *(const f32x4*)(Al + 32 * kb + 16 * sl + 8 * hi + 4);
;                         float e[8];
; #pragma unroll
;                         for (int jj = 0; jj < 8; ++jj) { const float as = jj < 4 ? s0[jj] : s1[jj - 4]; const int kv = kv0 + 32 * kb + 16 * sl + 8 * hi + jj;
;                             const float w = ex2(a2t - as); e[jj] = (diag && kv > t) ? 0.f : p[8 * sl + jj] * w; }
;                         u32x4 w; w.x = pk2(e[0], e[1]); w.y = pk2(e[2], e[3]); w.z = pk2(e[4], e[5]); w.w = pk2(e[6], e[7]);
;                         pb[sl] = __builtin_bit_cast(bf16x8, w);
;                     }
; #pragma unroll
;                     for (int b = 0; b < NBLK; ++b)
; #pragma unroll
;                         for (int sl = 0; sl < 2; ++sl) { const bf16x8 a = *(const bf16x8*)(Vl + (32 * b + r32) * VSTR + (32 * kb + 16 * sl + 8 * hi) * 2); o[b] = MFMA32(a, pb[sl], o[b]); }
	v_mfma_f32_32x32x16_bf16 v[66:81], v[216:219], v[142:145], v[66:81]
	ds_read_b128 v[204:207], v188 offset:52352
	ds_read_b128 v[208:211], v188 offset:52368
	s_waitcnt lgkmcnt(1)
	v_sub_f32_e32 v189, v175, v206
	v_exp_f32_e32 v189, v189
	v_sub_f32_e32 v191, v175, v204
	v_exp_f32_e32 v191, v191
	s_nop 4
	v_mul_f32_e32 v68, v68, v189
	v_sub_f32_e32 v189, v175, v207
	v_exp_f32_e32 v189, v189
	v_mul_f32_e32 v66, v66, v191
	v_sub_f32_e32 v191, v175, v205
	v_exp_f32_e32 v191, v191
	v_mul_f32_e32 v69, v69, v189
	s_waitcnt lgkmcnt(0)
	v_sub_f32_e32 v189, v175, v208
	v_exp_f32_e32 v189, v189
	v_mul_f32_e32 v67, v67, v191
	v_add_u32_e32 v191, 34, v187
	v_cndmask_b32_e64 v66, v66, 0, s[12:13]
	v_mul_f32_e32 v70, v70, v189
	v_sub_f32_e32 v189, v175, v209
	v_exp_f32_e32 v189, v189
	s_and_b64 s[12:13], s[2:3], vcc
	v_cmp_gt_i32_e32 vcc, v191, v174
	v_add_u32_e32 v191, 35, v187
	v_mul_f32_e32 v71, v71, v189
	v_sub_f32_e32 v189, v175, v210
	v_exp_f32_e32 v189, v189
	v_cndmask_b32_e64 v67, v67, 0, s[12:13]
	s_and_b64 s[12:13], s[2:3], vcc
	v_cmp_gt_i32_e32 vcc, v191, v174
	v_add_u32_e32 v191, 36, v187
	v_mul_f32_e32 v72, v72, v189
	v_sub_f32_e32 v189, v175, v211
	v_cndmask_b32_e64 v68, v68, 0, s[12:13]
	s_and_b64 s[12:13], s[2:3], vcc
	v_cmp_gt_i32_e32 vcc, v191, v174
	v_add_u32_e32 v191, 37, v187
	v_exp_f32_e32 v189, v189
	v_cndmask_b32_e64 v69, v69, 0, s[12:13]
	s_and_b64 s[12:13], s[2:3], vcc
	v_cmp_gt_i32_e32 vcc, v191, v174
	v_add_u32_e32 v191, 38, v187
	v_cndmask_b32_e64 v70, v70, 0, s[12:13]
	s_and_b64 s[12:13], s[2:3], vcc
	v_cmp_gt_i32_e32 vcc, v191, v174
	v_add_u32_e32 v191, 39, v187
	v_cndmask_b32_e64 v71, v71, 0, s[12:13]
	s_and_b64 s[12:13], s[2:3], vcc
	v_cmp_gt_i32_e32 vcc, v191, v174
	v_cndmask_b32_e64 v72, v72, 0, s[12:13]
	s_and_b64 s[12:13], s[2:3], vcc
	v_mul_f32_e32 v73, v73, v189
	v_cndmask_b32_e64 v73, v73, 0, s[12:13]
	v_cvt_pk_bf16_f32 v66, v66, v67
	v_cvt_pk_bf16_f32 v67, v68, v69
	v_cvt_pk_bf16_f32 v68, v70, v71
	v_cvt_pk_bf16_f32 v69, v72, v73
	ds_read_b128 v[204:207], v188 offset:52416
	ds_read_b128 v[70:73], v188 offset:52432
	v_add_u32_e32 v188, 48, v187
	v_cmp_gt_i32_e32 vcc, v188, v174
	s_and_b64 s[12:13], s[2:3], vcc
	s_waitcnt lgkmcnt(1)
	v_sub_f32_e32 v188, v175, v205
	v_exp_f32_e32 v188, v188
	v_sub_f32_e32 v189, v175, v204
	v_exp_f32_e32 v189, v189
	s_waitcnt lgkmcnt(0)
	v_sub_f32_e32 v70, v175, v70
	v_mul_f32_e32 v75, v75, v188
	v_sub_f32_e32 v188, v175, v206
	v_exp_f32_e32 v188, v188
	v_mul_f32_e32 v74, v74, v189
	v_add_u32_e32 v189, 49, v187
	v_cmp_gt_i32_e32 vcc, v189, v174
	v_mul_f32_e32 v76, v76, v188
	v_sub_f32_e32 v188, v175, v207
	v_exp_f32_e32 v188, v188
	v_add_u32_e32 v189, 50, v187
	v_exp_f32_e32 v70, v70
	v_cndmask_b32_e64 v74, v74, 0, s[12:13]
	s_and_b64 s[12:13], s[2:3], vcc
	v_cmp_gt_i32_e32 vcc, v189, v174
	v_add_u32_e32 v189, 51, v187
	v_cndmask_b32_e64 v75, v75, 0, s[12:13]
	s_and_b64 s[12:13], s[2:3], vcc
	v_cmp_gt_i32_e32 vcc, v189, v174
	v_mul_f32_e32 v77, v77, v188
	v_add_u32_e32 v188, 52, v187
	v_cndmask_b32_e64 v76, v76, 0, s[12:13]
	s_and_b64 s[12:13], s[2:3], vcc
	v_cmp_gt_i32_e32 vcc, v188, v174
	v_cndmask_b32_e64 v77, v77, 0, s[12:13]
	s_and_b64 s[12:13], s[2:3], vcc
	v_mul_f32_e32 v70, v78, v70
	v_cndmask_b32_e64 v78, v70, 0, s[12:13]
	v_sub_f32_e32 v70, v175, v71
	v_exp_f32_e32 v70, v70
	v_add_u32_e32 v71, 53, v187
	v_cmp_gt_i32_e32 vcc, v71, v174
	s_and_b64 s[12:13], s[2:3], vcc
	v_mul_f32_e32 v70, v79, v70
	v_cndmask_b32_e64 v79, v70, 0, s[12:13]
	v_sub_f32_e32 v70, v175, v72
	v_exp_f32_e32 v70, v70
	v_add_u32_e32 v71, 54, v187
	v_cmp_gt_i32_e32 vcc, v71, v174
	s_and_b64 s[12:13], s[2:3], vcc
	v_mul_f32_e32 v70, v80, v70
	v_cndmask_b32_e64 v80, v70, 0, s[12:13]
	v_sub_f32_e32 v70, v175, v73
	v_exp_f32_e32 v70, v70
	v_add_u32_e32 v71, 55, v187
	v_cmp_gt_i32_e32 vcc, v71, v174
	s_and_b64 s[2:3], s[2:3], vcc
	v_mul_f32_e32 v70, v81, v70
	v_cndmask_b32_e64 v73, v70, 0, s[2:3]
	v_cvt_pk_bf16_f32 v70, v74, v75
	v_cvt_pk_bf16_f32 v71, v76, v77
	v_cvt_pk_bf16_f32 v72, v78, v79
	v_cvt_pk_bf16_f32 v73, v80, v73
	ds_read_b128 v[74:77], v190 offset:33856
	ds_read_b128 v[78:81], v190 offset:33888
	s_waitcnt lgkmcnt(1)
	v_mfma_f32_32x32x16_bf16 v[2:17], v[74:77], v[66:69], v[2:17]
	ds_read_b128 v[212:215], v190 offset:38464
	ds_read_b128 v[216:219], v190 offset:38496
	ds_read_b128 v[220:223], v190 offset:43072
	s_waitcnt lgkmcnt(2)
	v_mfma_f32_32x32x16_bf16 v[18:33], v[212:215], v[66:69], v[18:33]
	ds_read_b128 v[212:215], v190 offset:43104
	s_waitcnt lgkmcnt(2)
	v_mfma_f32_32x32x16_bf16 v[18:33], v[216:219], v[70:73], v[18:33]
	ds_read_b128 v[216:219], v190 offset:47680
	s_waitcnt lgkmcnt(2)
	v_mfma_f32_32x32x16_bf16 v[34:49], v[220:223], v[66:69], v[34:49]
	s_waitcnt lgkmcnt(1)
	v_mfma_f32_32x32x16_bf16 v[34:49], v[212:215], v[70:73], v[34:49]
	s_waitcnt lgkmcnt(0)
	v_mfma_f32_32x32x16_bf16 v[50:65], v[216:219], v[66:69], v[50:65]
	ds_read_b128 v[66:69], v190 offset:47712
	v_mfma_f32_32x32x16_bf16 v[2:17], v[78:81], v[70:73], v[2:17]
	s_waitcnt lgkmcnt(0)
	v_mfma_f32_32x32x16_bf16 v[50:65], v[66:69], v[70:73], v[50:65]

; #define PG8_STAGE(bufoff, gbase, voff) do { _Pragma("unroll") for (int _i = 0; _i < 2; ++_i) \
;         __builtin_amdgcn_global_load_lds((const unsigned*)((const char*)(gbase) + (voff)[_i]), (LAS unsigned*)(lds + (bufoff) + ldsw + _i * 8192), 16, 0, 0); } while (0)
; #define PG8_LDA(dst, b, h) do { _Pragma("unroll") for (int m = 0; m < 4; ++m) _Pragma("unroll") for (int k = 0; k < 2; ++k) dst[m][k] = *(const LAS bf16x8*)(lds + PG8_SA(b, h) + aoff + m * 2048 + k * 1024); } while (0)
; #define PG8_LDB(dst, b, h) do { _Pragma("unroll") for (int n = 0; n < 2; ++n) _Pragma("unroll") for (int k = 0; k < 2; ++k) dst[n][k] = *(const LAS bf16x8*)(lds + PG8_SB(b, h) + boff + n * 2048 + k * 1024); } while (0)
; #define PG8_MMA(ai, bj, At, Bt) do { __builtin_amdgcn_s_setprio(1); _Pragma("unroll") for (int m = 0; m < 4; ++m) _Pragma("unroll") for (int n = 0; n < 2; ++n) _Pragma("unroll") for (int k = 0; k < 2; ++k) \
;         acc[ai][bj][m][n] = __builtin_amdgcn_mfma_f32_16x16x32_bf16(Bt[n][k], At[m][k], acc[ai][bj][m][n], 0, 0, 0); __builtin_amdgcn_s_setprio(0); } while (0)
; #define PG8_WAIT_V(n) asm volatile("s_waitcnt vmcnt(" #n ")" ::: "memory")
; #define PG8_WAIT_L(n) asm volatile("s_waitcnt lgkmcnt(" #n ")" ::: "memory")
; #define PG8_BAR __builtin_amdgcn_s_barrier()
; #define PG8_SCHED __builtin_amdgcn_sched_barrier(0)
; template <class Epi, class Sched>
; __device__ __forceinline__ void gemm_phase(const int tid, LAS unsigned char* lds, const Gemm g, const Sched& S, const Epi& E) {
;     ...
;         for (int t = 0; t < nt; t += 2) {
;             const bool last = (t == nt - 2);
;             const char* a1 = cA + (size_t)(t + 1) * kstepA;
;             const char* a2 = last ? nA : cA + (size_t)(t + 2) * kstepA; const char* b2 = last ? nB : cB + (size_t)(t + 2) * kstepB;
;             const char* a3 = a2 + kstepA; const char* b3 = b2 + kstepB;
;             PG8_LDB(B0, 0, 0); PG8_LDB(B1, 0, 1); PG8_SCHED; PG8_LDA(At, 0, 0); PG8_STAGE(PG8_SA(1, 1), a1 + hstepA, voffA);
;             PG8_WAIT_V(8); PG8_WAIT_L(0); PG8_BAR; PG8_MMA(0, 0, At, B0); PG8_MMA(0, 1, At, B1); PG8_BAR; PG8_SCHED;
;             PG8_LDA(At, 0, 1); PG8_STAGE(PG8_SB(0, 0), b2, voffB); PG8_STAGE(PG8_SB(0, 1), b2 + hstepB, voffB); PG8_STAGE(PG8_SA(0, 0), a2, voffA);
.LBB0_887:
	s_add_u32 s20, s18, 0xfffc0080
	s_addc_u32 s21, s19, -1
	s_add_i32 s36, 16, 0x10000
	s_cmp_eq_u32 s65, 12
	s_cselect_b32 s23, s9, s21
	s_cselect_b32 s22, s61, s20
	v_add_u32_e32 v0, s36, v236
	s_cselect_b32 s21, s11, s64
	s_cselect_b32 s20, s62, s63
	s_add_i32 s37, 16, 0x14000
	ds_read_b128 v[130:133], v0
	ds_read_b128 v[134:137], v0 offset:1024
	ds_read_b128 v[138:141], v0 offset:2048
	ds_read_b128 v[142:145], v0 offset:3072
	v_add_u32_e32 v0, s37, v236
	ds_read_b128 v[146:149], v0
	ds_read_b128 v[150:153], v0 offset:1024
	ds_read_b128 v[154:157], v0 offset:2048
	ds_read_b128 v[158:161], v0 offset:3072
	s_add_i32 m0, s34, 0xc000
	ds_read_b128 v[162:165], v237
	ds_read_b128 v[166:169], v237 offset:1024
	ds_read_b128 v[170:173], v237 offset:2048
	ds_read_b128 v[174:177], v237 offset:3072
	ds_read_b128 v[178:181], v237 offset:4096
	ds_read_b128 v[182:185], v237 offset:5120
	ds_read_b128 v[186:189], v237 offset:6144
	ds_read_b128 v[190:193], v237 offset:7168
	global_load_lds_dwordx4 v218, s[18:19]
	s_add_i32 m0, s34, 0xe000
	s_nop 0
	global_load_lds_dwordx4 v216, s[18:19]
	s_waitcnt vmcnt(8)
	s_waitcnt lgkmcnt(0)
	s_barrier
	s_setprio 1
	s_waitcnt lgkmcnt(0)
	v_mfma_f32_16x16x32_bf16 v[126:129], v[130:133], v[162:165], v[126:129]
	v_mfma_f32_16x16x32_bf16 v[122:125], v[138:141], v[162:165], v[122:125]
	v_mfma_f32_16x16x32_bf16 v[110:113], v[130:133], v[170:173], v[110:113]
	v_mfma_f32_16x16x32_bf16 v[106:109], v[138:141], v[170:173], v[106:109]
	v_mfma_f32_16x16x32_bf16 v[98:101], v[130:133], v[178:181], v[98:101]
	v_mfma_f32_16x16x32_bf16 v[90:93], v[138:141], v[178:181], v[90:93]
	v_mfma_f32_16x16x32_bf16 v[78:81], v[130:133], v[186:189], v[78:81]
	v_mfma_f32_16x16x32_bf16 v[74:77], v[138:141], v[186:189], v[74:77]
	v_mfma_f32_16x16x32_bf16 v[126:129], v[134:137], v[166:169], v[126:129]
	v_mfma_f32_16x16x32_bf16 v[122:125], v[142:145], v[166:169], v[122:125]
	v_mfma_f32_16x16x32_bf16 v[110:113], v[134:137], v[174:177], v[110:113]
	v_mfma_f32_16x16x32_bf16 v[106:109], v[142:145], v[174:177], v[106:109]
	v_mfma_f32_16x16x32_bf16 v[98:101], v[134:137], v[182:185], v[98:101]
	v_mfma_f32_16x16x32_bf16 v[90:93], v[142:145], v[182:185], v[90:93]
	v_mfma_f32_16x16x32_bf16 v[78:81], v[134:137], v[190:193], v[78:81]
	v_mfma_f32_16x16x32_bf16 v[74:77], v[142:145], v[190:193], v[74:77]
	s_setprio 0
	s_setprio 1
	v_mfma_f32_16x16x32_bf16 v[118:121], v[146:149], v[162:165], v[118:121]
	v_mfma_f32_16x16x32_bf16 v[114:117], v[154:157], v[162:165], v[114:117]
	v_mfma_f32_16x16x32_bf16 v[102:105], v[146:149], v[170:173], v[102:105]
	v_mfma_f32_16x16x32_bf16 v[94:97], v[154:157], v[170:173], v[94:97]
	v_mfma_f32_16x16x32_bf16 v[86:89], v[146:149], v[178:181], v[86:89]
	v_mfma_f32_16x16x32_bf16 v[82:85], v[154:157], v[178:181], v[82:85]
	v_mfma_f32_16x16x32_bf16 v[70:73], v[146:149], v[186:189], v[70:73]
	v_mfma_f32_16x16x32_bf16 v[66:69], v[154:157], v[186:189], v[66:69]
	v_mfma_f32_16x16x32_bf16 v[118:121], v[150:153], v[166:169], v[118:121]
	v_mfma_f32_16x16x32_bf16 v[114:117], v[158:161], v[166:169], v[114:117]
	v_mfma_f32_16x16x32_bf16 v[102:105], v[150:153], v[174:177], v[102:105]
	v_mfma_f32_16x16x32_bf16 v[94:97], v[158:161], v[174:177], v[94:97]
	v_mfma_f32_16x16x32_bf16 v[86:89], v[150:153], v[182:185], v[86:89]
	v_mfma_f32_16x16x32_bf16 v[82:85], v[158:161], v[182:185], v[82:85]
	v_mfma_f32_16x16x32_bf16 v[70:73], v[150:153], v[190:193], v[70:73]
	v_mfma_f32_16x16x32_bf16 v[66:69], v[158:161], v[190:193], v[66:69]
	s_setprio 0
	s_barrier
	s_add_i32 s36, s36, s31
	s_mov_b32 m0, s36
	ds_read_b128 v[162:165], v237 offset:16384
	ds_read_b128 v[166:169], v237 offset:17408
	ds_read_b128 v[170:173], v237 offset:18432
	ds_read_b128 v[174:177], v237 offset:19456
	ds_read_b128 v[178:181], v237 offset:20480
	ds_read_b128 v[182:185], v237 offset:21504
	ds_read_b128 v[186:189], v237 offset:22528
	ds_read_b128 v[190:193], v237 offset:23552
	global_load_lds_dwordx4 v210, s[20:21]
	s_add_i32 m0, s36, 0x2000
	s_add_u32 s66, s20, 0x4000
	s_addc_u32 s67, s21, 0
	s_add_i32 s36, s37, s31
	global_load_lds_dwordx4 v214, s[20:21]
	s_mov_b32 m0, s36
	v_lshl_add_u64 v[206:207], s[22:23], 0, v[212:213]
	global_load_lds_dwordx4 v210, s[66:67]
	s_add_i32 m0, s36, 0x2000
	s_nop 0
	global_load_lds_dwordx4 v214, s[66:67]
	v_lshl_add_u64 v[204:205], s[22:23], 0, v[208:209]
	s_mov_b32 m0, s34
	s_nop 0
	global_load_lds_dwordx4 v[204:205], off
	s_mov_b32 m0, s35
	s_nop 0
	global_load_lds_dwordx4 v[206:207], off
	s_waitcnt vmcnt(8)
	s_waitcnt lgkmcnt(0)
	s_barrier
; #define PG8_STAGE(bufoff, gbase, voff) do { _Pragma("unroll") for (int _i = 0; _i < 2; ++_i) \
;         __builtin_amdgcn_global_load_lds((const unsigned*)((const char*)(gbase) + (voff)[_i]), (LAS unsigned*)(lds + (bufoff) + ldsw + _i * 8192), 16, 0, 0); } while (0)
; #define PG8_LDA(dst, b, h) do { _Pragma("unroll") for (int m = 0; m < 4; ++m) _Pragma("unroll") for (int k = 0; k < 2; ++k) dst[m][k] = *(const LAS bf16x8*)(lds + PG8_SA(b, h) + aoff + m * 2048 + k * 1024); } while (0)
; #define PG8_LDB(dst, b, h) do { _Pragma("unroll") for (int n = 0; n < 2; ++n) _Pragma("unroll") for (int k = 0; k < 2; ++k) dst[n][k] = *(const LAS bf16x8*)(lds + PG8_SB(b, h) + boff + n * 2048 + k * 1024); } while (0)
; #define PG8_MMA(ai, bj, At, Bt) do { __builtin_amdgcn_s_setprio(1); _Pragma("unroll") for (int m = 0; m < 4; ++m) _Pragma("unroll") for (int n = 0; n < 2; ++n) _Pragma("unroll") for (int k = 0; k < 2; ++k) \
;         acc[ai][bj][m][n] = __builtin_amdgcn_mfma_f32_16x16x32_bf16(Bt[n][k], At[m][k], acc[ai][bj][m][n], 0, 0, 0); __builtin_amdgcn_s_setprio(0); } while (0)
; #define PG8_WAIT_V(n) asm volatile("s_waitcnt vmcnt(" #n ")" ::: "memory")
; #define PG8_WAIT_L(n) asm volatile("s_waitcnt lgkmcnt(" #n ")" ::: "memory")
; #define PG8_BAR __builtin_amdgcn_s_barrier()
; #define PG8_SCHED __builtin_amdgcn_sched_barrier(0)
; template <class Epi, class Sched>
; __device__ __forceinline__ void gemm_phase(const int tid, LAS unsigned char* lds, const Gemm g, const Sched& S, const Epi& E) {
;     ...
;             PG8_WAIT_V(8); PG8_WAIT_L(0); PG8_BAR; PG8_MMA(1, 0, At, B0); PG8_MMA(1, 1, At, B1); PG8_BAR; PG8_SCHED;
;             PG8_LDB(B0, 1, 0); PG8_LDB(B1, 1, 1); PG8_SCHED; PG8_LDA(At, 1, 0); PG8_STAGE(PG8_SA(0, 1), a2 + hstepA, voffA);
;             PG8_WAIT_V(8); PG8_WAIT_L(0); PG8_BAR; PG8_MMA(0, 0, At, B0); PG8_MMA(0, 1, At, B1); PG8_BAR; PG8_SCHED;
	s_setprio 1
	s_waitcnt lgkmcnt(0)
	v_mfma_f32_16x16x32_bf16 v[62:65], v[130:133], v[162:165], v[62:65]
	v_mfma_f32_16x16x32_bf16 v[58:61], v[138:141], v[162:165], v[58:61]
	v_mfma_f32_16x16x32_bf16 v[46:49], v[130:133], v[170:173], v[46:49]
	v_mfma_f32_16x16x32_bf16 v[42:45], v[138:141], v[170:173], v[42:45]
	v_mfma_f32_16x16x32_bf16 v[34:37], v[130:133], v[178:181], v[34:37]
	v_mfma_f32_16x16x32_bf16 v[26:29], v[138:141], v[178:181], v[26:29]
	v_mfma_f32_16x16x32_bf16 v[14:17], v[130:133], v[186:189], v[14:17]
	v_mfma_f32_16x16x32_bf16 v[10:13], v[138:141], v[186:189], v[10:13]
	v_mfma_f32_16x16x32_bf16 v[62:65], v[134:137], v[166:169], v[62:65]
	v_mfma_f32_16x16x32_bf16 v[58:61], v[142:145], v[166:169], v[58:61]
	v_mfma_f32_16x16x32_bf16 v[46:49], v[134:137], v[174:177], v[46:49]
	v_mfma_f32_16x16x32_bf16 v[42:45], v[142:145], v[174:177], v[42:45]
	v_mfma_f32_16x16x32_bf16 v[34:37], v[134:137], v[182:185], v[34:37]
	v_mfma_f32_16x16x32_bf16 v[26:29], v[142:145], v[182:185], v[26:29]
	v_mfma_f32_16x16x32_bf16 v[14:17], v[134:137], v[190:193], v[14:17]
	v_mfma_f32_16x16x32_bf16 v[10:13], v[142:145], v[190:193], v[10:13]
	s_setprio 0
	s_setprio 1
	v_mfma_f32_16x16x32_bf16 v[54:57], v[146:149], v[162:165], v[54:57]
	v_mfma_f32_16x16x32_bf16 v[50:53], v[154:157], v[162:165], v[50:53]
	v_mfma_f32_16x16x32_bf16 v[38:41], v[146:149], v[170:173], v[38:41]
	v_mfma_f32_16x16x32_bf16 v[30:33], v[154:157], v[170:173], v[30:33]
	v_mfma_f32_16x16x32_bf16 v[22:25], v[146:149], v[178:181], v[22:25]
	v_mfma_f32_16x16x32_bf16 v[18:21], v[154:157], v[178:181], v[18:21]
	v_mfma_f32_16x16x32_bf16 v[6:9], v[146:149], v[186:189], v[6:9]
	v_mfma_f32_16x16x32_bf16 v[2:5], v[154:157], v[186:189], v[2:5]
	v_mfma_f32_16x16x32_bf16 v[54:57], v[150:153], v[166:169], v[54:57]
	v_mfma_f32_16x16x32_bf16 v[50:53], v[158:161], v[166:169], v[50:53]
	v_mfma_f32_16x16x32_bf16 v[38:41], v[150:153], v[174:177], v[38:41]
	v_mfma_f32_16x16x32_bf16 v[30:33], v[158:161], v[174:177], v[30:33]
	v_mfma_f32_16x16x32_bf16 v[22:25], v[150:153], v[182:185], v[22:25]
	v_mfma_f32_16x16x32_bf16 v[18:21], v[158:161], v[182:185], v[18:21]
	v_mfma_f32_16x16x32_bf16 v[6:9], v[150:153], v[190:193], v[6:9]
	v_mfma_f32_16x16x32_bf16 v[2:5], v[158:161], v[190:193], v[2:5]
	s_setprio 0
	s_barrier
	s_add_i32 s36, 16, 0x18000
	v_add_u32_e32 v0, s36, v236
	s_add_i32 s37, 16, 0x1c000
	ds_read_b128 v[130:133], v0
	ds_read_b128 v[134:137], v0 offset:1024
	ds_read_b128 v[138:141], v0 offset:2048
	ds_read_b128 v[142:145], v0 offset:3072
	v_add_u32_e32 v0, s37, v236
	ds_read_b128 v[146:149], v0
	ds_read_b128 v[150:153], v0 offset:1024
	ds_read_b128 v[154:157], v0 offset:2048
	ds_read_b128 v[158:161], v0 offset:3072
	s_add_u32 s22, s22, 0x40000
	s_addc_u32 s23, s23, 0
	s_mov_b32 m0, s52
	ds_read_b128 v[162:165], v237 offset:32768
	ds_read_b128 v[166:169], v237 offset:33792
	ds_read_b128 v[170:173], v237 offset:34816
	ds_read_b128 v[174:177], v237 offset:35840
	ds_read_b128 v[178:181], v237 offset:36864
	ds_read_b128 v[182:185], v237 offset:37888
	ds_read_b128 v[186:189], v237 offset:38912
	ds_read_b128 v[190:193], v237 offset:39936
	global_load_lds_dwordx4 v208, s[22:23]
	s_mov_b32 m0, s53
	s_nop 0
	global_load_lds_dwordx4 v212, s[22:23]
	s_waitcnt vmcnt(8)
	s_waitcnt lgkmcnt(0)
	s_barrier
	s_setprio 1
	s_waitcnt lgkmcnt(0)
	v_mfma_f32_16x16x32_bf16 v[126:129], v[130:133], v[162:165], v[126:129]
	v_mfma_f32_16x16x32_bf16 v[122:125], v[138:141], v[162:165], v[122:125]
	v_mfma_f32_16x16x32_bf16 v[110:113], v[130:133], v[170:173], v[110:113]
	v_mfma_f32_16x16x32_bf16 v[106:109], v[138:141], v[170:173], v[106:109]
	v_mfma_f32_16x16x32_bf16 v[98:101], v[130:133], v[178:181], v[98:101]
	v_mfma_f32_16x16x32_bf16 v[90:93], v[138:141], v[178:181], v[90:93]
	v_mfma_f32_16x16x32_bf16 v[78:81], v[130:133], v[186:189], v[78:81]
	v_mfma_f32_16x16x32_bf16 v[74:77], v[138:141], v[186:189], v[74:77]
	v_mfma_f32_16x16x32_bf16 v[126:129], v[134:137], v[166:169], v[126:129]
	v_mfma_f32_16x16x32_bf16 v[122:125], v[142:145], v[166:169], v[122:125]
	v_mfma_f32_16x16x32_bf16 v[110:113], v[134:137], v[174:177], v[110:113]
	v_mfma_f32_16x16x32_bf16 v[106:109], v[142:145], v[174:177], v[106:109]
	v_mfma_f32_16x16x32_bf16 v[98:101], v[134:137], v[182:185], v[98:101]
	v_mfma_f32_16x16x32_bf16 v[90:93], v[142:145], v[182:185], v[90:93]
	v_mfma_f32_16x16x32_bf16 v[78:81], v[134:137], v[190:193], v[78:81]
	v_mfma_f32_16x16x32_bf16 v[74:77], v[142:145], v[190:193], v[74:77]
	s_setprio 0
	s_setprio 1
	v_mfma_f32_16x16x32_bf16 v[118:121], v[146:149], v[162:165], v[118:121]
	v_mfma_f32_16x16x32_bf16 v[114:117], v[154:157], v[162:165], v[114:117]
	v_mfma_f32_16x16x32_bf16 v[102:105], v[146:149], v[170:173], v[102:105]
	v_mfma_f32_16x16x32_bf16 v[94:97], v[154:157], v[170:173], v[94:97]
	v_mfma_f32_16x16x32_bf16 v[86:89], v[146:149], v[178:181], v[86:89]
	v_mfma_f32_16x16x32_bf16 v[82:85], v[154:157], v[178:181], v[82:85]
	v_mfma_f32_16x16x32_bf16 v[70:73], v[146:149], v[186:189], v[70:73]
	v_mfma_f32_16x16x32_bf16 v[66:69], v[154:157], v[186:189], v[66:69]
	v_mfma_f32_16x16x32_bf16 v[118:121], v[150:153], v[166:169], v[118:121]
	v_mfma_f32_16x16x32_bf16 v[114:117], v[158:161], v[166:169], v[114:117]
	v_mfma_f32_16x16x32_bf16 v[102:105], v[150:153], v[174:177], v[102:105]
	v_mfma_f32_16x16x32_bf16 v[94:97], v[158:161], v[174:177], v[94:97]
	v_mfma_f32_16x16x32_bf16 v[86:89], v[150:153], v[182:185], v[86:89]
	v_mfma_f32_16x16x32_bf16 v[82:85], v[158:161], v[182:185], v[82:85]
	v_mfma_f32_16x16x32_bf16 v[70:73], v[150:153], v[190:193], v[70:73]
	v_mfma_f32_16x16x32_bf16 v[66:69], v[158:161], v[190:193], v[66:69]
	s_setprio 0
	s_barrier
; #define PG8_STAGE(bufoff, gbase, voff) do { _Pragma("unroll") for (int _i = 0; _i < 2; ++_i) \
;         __builtin_amdgcn_global_load_lds((const unsigned*)((const char*)(gbase) + (voff)[_i]), (LAS unsigned*)(lds + (bufoff) + ldsw + _i * 8192), 16, 0, 0); } while (0)
; #define PG8_LDA(dst, b, h) do { _Pragma("unroll") for (int m = 0; m < 4; ++m) _Pragma("unroll") for (int k = 0; k < 2; ++k) dst[m][k] = *(const LAS bf16x8*)(lds + PG8_SA(b, h) + aoff + m * 2048 + k * 1024); } while (0)
; #define PG8_MMA(ai, bj, At, Bt) do { __builtin_amdgcn_s_setprio(1); _Pragma("unroll") for (int m = 0; m < 4; ++m) _Pragma("unroll") for (int n = 0; n < 2; ++n) _Pragma("unroll") for (int k = 0; k < 2; ++k) \
;         acc[ai][bj][m][n] = __builtin_amdgcn_mfma_f32_16x16x32_bf16(Bt[n][k], At[m][k], acc[ai][bj][m][n], 0, 0, 0); __builtin_amdgcn_s_setprio(0); } while (0)
; #define PG8_WAIT_V(n) asm volatile("s_waitcnt vmcnt(" #n ")" ::: "memory")
; #define PG8_WAIT_L(n) asm volatile("s_waitcnt lgkmcnt(" #n ")" ::: "memory")
; #define PG8_BAR __builtin_amdgcn_s_barrier()
; #define PG8_SCHED __builtin_amdgcn_sched_barrier(0)
; template <class Epi, class Sched>
; __device__ __forceinline__ void gemm_phase(const int tid, LAS unsigned char* lds, const Gemm g, const Sched& S, const Epi& E) {
;     ...
;             PG8_LDA(At, 1, 1); PG8_STAGE(PG8_SB(1, 0), b3, voffB); PG8_STAGE(PG8_SB(1, 1), b3 + hstepB, voffB); PG8_STAGE(PG8_SA(1, 0), a3, voffA);
;             PG8_WAIT_V(8); PG8_WAIT_L(0); PG8_BAR; PG8_MMA(1, 0, At, B0); PG8_MMA(1, 1, At, B1); PG8_BAR; PG8_SCHED;
;         }
;         if (wr == 0) PG8_BAR;
	s_add_u32 s22, s20, 0x8000
	s_addc_u32 s23, s21, 0
	s_add_i32 s36, s36, s31
	s_mov_b32 m0, s36
	ds_read_b128 v[162:165], v237 offset:49152
	ds_read_b128 v[166:169], v237 offset:50176
	ds_read_b128 v[170:173], v237 offset:51200
	ds_read_b128 v[174:177], v237 offset:52224
	ds_read_b128 v[178:181], v237 offset:53248
	ds_read_b128 v[182:185], v237 offset:54272
	ds_read_b128 v[186:189], v237 offset:55296
	ds_read_b128 v[190:193], v237 offset:56320
	global_load_lds_dwordx4 v210, s[22:23]
	s_add_i32 m0, s36, 0x2000
	s_add_u32 s20, s20, 0xc000
	s_addc_u32 s21, s21, 0
	global_load_lds_dwordx4 v214, s[22:23]
	s_add_i32 s22, s37, s31
	s_mov_b32 m0, s22
	v_lshl_add_u64 v[204:205], v[204:205], 0, s[88:89]
	global_load_lds_dwordx4 v210, s[20:21]
	s_add_i32 m0, s22, 0x2000
	s_nop 0
	global_load_lds_dwordx4 v214, s[20:21]
	s_mov_b32 m0, s58
	s_nop 0
	global_load_lds_dwordx4 v[204:205], off
	v_lshl_add_u64 v[204:205], v[206:207], 0, s[88:89]
	s_mov_b32 m0, s59
	s_nop 0
	global_load_lds_dwordx4 v[204:205], off
	s_waitcnt vmcnt(8)
	s_waitcnt lgkmcnt(0)
	s_barrier
	s_setprio 1
	s_waitcnt lgkmcnt(0)
	v_mfma_f32_16x16x32_bf16 v[62:65], v[130:133], v[162:165], v[62:65]
	v_mfma_f32_16x16x32_bf16 v[58:61], v[138:141], v[162:165], v[58:61]
	v_mfma_f32_16x16x32_bf16 v[46:49], v[130:133], v[170:173], v[46:49]
	v_mfma_f32_16x16x32_bf16 v[42:45], v[138:141], v[170:173], v[42:45]
	v_mfma_f32_16x16x32_bf16 v[34:37], v[130:133], v[178:181], v[34:37]
	v_mfma_f32_16x16x32_bf16 v[26:29], v[138:141], v[178:181], v[26:29]
	v_mfma_f32_16x16x32_bf16 v[14:17], v[130:133], v[186:189], v[14:17]
	v_mfma_f32_16x16x32_bf16 v[10:13], v[138:141], v[186:189], v[10:13]
	v_mfma_f32_16x16x32_bf16 v[62:65], v[134:137], v[166:169], v[62:65]
	v_mfma_f32_16x16x32_bf16 v[58:61], v[142:145], v[166:169], v[58:61]
	v_mfma_f32_16x16x32_bf16 v[46:49], v[134:137], v[174:177], v[46:49]
	v_mfma_f32_16x16x32_bf16 v[42:45], v[142:145], v[174:177], v[42:45]
	v_mfma_f32_16x16x32_bf16 v[34:37], v[134:137], v[182:185], v[34:37]
	v_mfma_f32_16x16x32_bf16 v[26:29], v[142:145], v[182:185], v[26:29]
	v_mfma_f32_16x16x32_bf16 v[14:17], v[134:137], v[190:193], v[14:17]
	v_mfma_f32_16x16x32_bf16 v[10:13], v[142:145], v[190:193], v[10:13]
	s_setprio 0
	s_setprio 1
	v_mfma_f32_16x16x32_bf16 v[54:57], v[146:149], v[162:165], v[54:57]
	v_mfma_f32_16x16x32_bf16 v[50:53], v[154:157], v[162:165], v[50:53]
	v_mfma_f32_16x16x32_bf16 v[38:41], v[146:149], v[170:173], v[38:41]
	v_mfma_f32_16x16x32_bf16 v[30:33], v[154:157], v[170:173], v[30:33]
	v_mfma_f32_16x16x32_bf16 v[22:25], v[146:149], v[178:181], v[22:25]
	v_mfma_f32_16x16x32_bf16 v[18:21], v[154:157], v[178:181], v[18:21]
	v_mfma_f32_16x16x32_bf16 v[6:9], v[146:149], v[186:189], v[6:9]
	v_mfma_f32_16x16x32_bf16 v[2:5], v[154:157], v[186:189], v[2:5]
	v_mfma_f32_16x16x32_bf16 v[54:57], v[150:153], v[166:169], v[54:57]
	v_mfma_f32_16x16x32_bf16 v[50:53], v[158:161], v[166:169], v[50:53]
	v_mfma_f32_16x16x32_bf16 v[38:41], v[150:153], v[174:177], v[38:41]
	v_mfma_f32_16x16x32_bf16 v[30:33], v[158:161], v[174:177], v[30:33]
	v_mfma_f32_16x16x32_bf16 v[22:25], v[150:153], v[182:185], v[22:25]
	v_mfma_f32_16x16x32_bf16 v[18:21], v[158:161], v[182:185], v[18:21]
	v_mfma_f32_16x16x32_bf16 v[6:9], v[150:153], v[190:193], v[6:9]
	v_mfma_f32_16x16x32_bf16 v[2:5], v[158:161], v[190:193], v[2:5]
	s_setprio 0
	s_barrier
	s_add_i32 s65, s65, 2
	s_add_u32 s63, s63, 0x10000
	s_addc_u32 s64, s64, 0
	s_add_u32 s18, s18, 0x100
	s_addc_u32 s19, s19, 0
	s_cmp_gt_u32 s65, 13
	s_cbranch_scc0 .LBB0_887
	s_and_b64 vcc, exec, s[6:7]
	s_cbranch_vccz .LBB0_890
	s_barrier

; #define PG8_STAGE(bufoff, gbase, voff) do { _Pragma("unroll") for (int _i = 0; _i < 2; ++_i) \
;         __builtin_amdgcn_global_load_lds((const unsigned*)((const char*)(gbase) + (voff)[_i]), (LAS unsigned*)(lds + (bufoff) + ldsw + _i * 8192), 16, 0, 0); } while (0)
; #define PG8_LDA(dst, b, h) do { _Pragma("unroll") for (int m = 0; m < 4; ++m) _Pragma("unroll") for (int k = 0; k < 2; ++k) dst[m][k] = *(const LAS bf16x8*)(lds + PG8_SA(b, h) + aoff + m * 2048 + k * 1024); } while (0)
; #define PG8_LDB(dst, b, h) do { _Pragma("unroll") for (int n = 0; n < 2; ++n) _Pragma("unroll") for (int k = 0; k < 2; ++k) dst[n][k] = *(const LAS bf16x8*)(lds + PG8_SB(b, h) + boff + n * 2048 + k * 1024); } while (0)
; #define PG8_MMA(ai, bj, At, Bt) do { __builtin_amdgcn_s_setprio(1); _Pragma("unroll") for (int m = 0; m < 4; ++m) _Pragma("unroll") for (int n = 0; n < 2; ++n) _Pragma("unroll") for (int k = 0; k < 2; ++k) \
;         acc[ai][bj][m][n] = __builtin_amdgcn_mfma_f32_16x16x32_bf16(Bt[n][k], At[m][k], acc[ai][bj][m][n], 0, 0, 0); __builtin_amdgcn_s_setprio(0); } while (0)
; #define PG8_WAIT_V(n) asm volatile("s_waitcnt vmcnt(" #n ")" ::: "memory")
; #define PG8_WAIT_L(n) asm volatile("s_waitcnt lgkmcnt(" #n ")" ::: "memory")
; #define PG8_BAR __builtin_amdgcn_s_barrier()
; #define PG8_SCHED __builtin_amdgcn_sched_barrier(0)
; template <class Epi, class Sched>
; __device__ __forceinline__ void gemm_phase(const int tid, LAS unsigned char* lds, const Gemm g, const Sched& S, const Epi& E) {
;     ...
;         for (int t = 0; t < nt; t += 2) {
;             const bool last = (t == nt - 2);
;             const char* a1 = cA + (size_t)(t + 1) * kstepA;
;             const char* a2 = last ? nA : cA + (size_t)(t + 2) * kstepA; const char* b2 = last ? nB : cB + (size_t)(t + 2) * kstepB;
;             const char* a3 = a2 + kstepA; const char* b3 = b2 + kstepB;
;             PG8_LDB(B0, 0, 0); PG8_LDB(B1, 0, 1); PG8_SCHED; PG8_LDA(At, 0, 0); PG8_STAGE(PG8_SA(1, 1), a1 + hstepA, voffA);
;             PG8_WAIT_V(8); PG8_WAIT_L(0); PG8_BAR; PG8_MMA(0, 0, At, B0); PG8_MMA(0, 1, At, B1); PG8_BAR; PG8_SCHED;
;             PG8_LDA(At, 0, 1); PG8_STAGE(PG8_SB(0, 0), b2, voffB); PG8_STAGE(PG8_SB(0, 1), b2 + hstepB, voffB); PG8_STAGE(PG8_SA(0, 0), a2, voffA);
;             PG8_WAIT_V(8); PG8_WAIT_L(0); PG8_BAR; PG8_MMA(1, 0, At, B0); PG8_MMA(1, 1, At, B1); PG8_BAR; PG8_SCHED;
.LBB0_962:
	s_add_u32 s18, s16, 0x4000
	s_addc_u32 s19, s17, 0
	s_cmp_eq_u32 s62, 28
	s_cselect_b32 s22, s58, s18
	s_cselect_b32 s23, s9, s19
	s_cselect_b32 s20, s59, s60
	s_cselect_b32 s21, s7, s61
	s_add_u32 s18, s22, 0x8000
	s_addc_u32 s19, s23, 0
	s_add_i32 s36, 16, 0x10000
	s_add_i32 s37, 16, 0x14000
	v_add_u32_e32 v148, s36, v157
	v_add_u32_e32 v168, s37, v157
	ds_read_b128 v[130:133], v148
	ds_read_b128 v[134:137], v148 offset:1024
	ds_read_b128 v[138:141], v148 offset:2048
	ds_read_b128 v[148:151], v148 offset:3072
	ds_read_b128 v[152:155], v168
	ds_read_b128 v[160:163], v168 offset:1024
	ds_read_b128 v[164:167], v168 offset:2048
	ds_read_b128 v[168:171], v168 offset:3072
	s_add_i32 m0, s34, 0xc000
	ds_read_b128 v[172:175], v159
	ds_read_b128 v[176:179], v159 offset:1024
	ds_read_b128 v[180:183], v159 offset:2048
	ds_read_b128 v[184:187], v159 offset:3072
	ds_read_b128 v[188:191], v159 offset:4096
	ds_read_b128 v[204:207], v159 offset:5120
	ds_read_b128 v[208:211], v159 offset:6144
	ds_read_b128 v[212:215], v159 offset:7168
	global_load_lds_dwordx4 v146, s[16:17]
	s_add_i32 m0, s34, 0xe000
	s_nop 0
	global_load_lds_dwordx4 v144, s[16:17]
	s_waitcnt vmcnt(8)
	s_waitcnt lgkmcnt(0)
	s_barrier
	s_setprio 1
	s_waitcnt lgkmcnt(0)
	v_mfma_f32_16x16x32_bf16 v[126:129], v[130:133], v[172:175], v[126:129]
	v_mfma_f32_16x16x32_bf16 v[122:125], v[138:141], v[172:175], v[122:125]
	v_mfma_f32_16x16x32_bf16 v[118:121], v[130:133], v[180:183], v[118:121]
	v_mfma_f32_16x16x32_bf16 v[106:109], v[138:141], v[180:183], v[106:109]
	v_mfma_f32_16x16x32_bf16 v[102:105], v[130:133], v[188:191], v[102:105]
	v_mfma_f32_16x16x32_bf16 v[90:93], v[138:141], v[188:191], v[90:93]
	v_mfma_f32_16x16x32_bf16 v[86:89], v[130:133], v[208:211], v[86:89]
	v_mfma_f32_16x16x32_bf16 v[74:77], v[138:141], v[208:211], v[74:77]
	v_mfma_f32_16x16x32_bf16 v[126:129], v[134:137], v[176:179], v[126:129]
	v_mfma_f32_16x16x32_bf16 v[122:125], v[148:151], v[176:179], v[122:125]
	v_mfma_f32_16x16x32_bf16 v[118:121], v[134:137], v[184:187], v[118:121]
	v_mfma_f32_16x16x32_bf16 v[106:109], v[148:151], v[184:187], v[106:109]
	v_mfma_f32_16x16x32_bf16 v[102:105], v[134:137], v[204:207], v[102:105]
	v_mfma_f32_16x16x32_bf16 v[90:93], v[148:151], v[204:207], v[90:93]
	v_mfma_f32_16x16x32_bf16 v[86:89], v[134:137], v[212:215], v[86:89]
	v_mfma_f32_16x16x32_bf16 v[74:77], v[148:151], v[212:215], v[74:77]
	s_setprio 0
	s_setprio 1
	v_mfma_f32_16x16x32_bf16 v[114:117], v[152:155], v[172:175], v[114:117]
	v_mfma_f32_16x16x32_bf16 v[110:113], v[164:167], v[172:175], v[110:113]
	v_mfma_f32_16x16x32_bf16 v[98:101], v[152:155], v[180:183], v[98:101]
	v_mfma_f32_16x16x32_bf16 v[94:97], v[164:167], v[180:183], v[94:97]
	v_mfma_f32_16x16x32_bf16 v[82:85], v[152:155], v[188:191], v[82:85]
	v_mfma_f32_16x16x32_bf16 v[78:81], v[164:167], v[188:191], v[78:81]
	v_mfma_f32_16x16x32_bf16 v[70:73], v[152:155], v[208:211], v[70:73]
	v_mfma_f32_16x16x32_bf16 v[66:69], v[164:167], v[208:211], v[66:69]
	v_mfma_f32_16x16x32_bf16 v[114:117], v[160:163], v[176:179], v[114:117]
	v_mfma_f32_16x16x32_bf16 v[110:113], v[168:171], v[176:179], v[110:113]
	v_mfma_f32_16x16x32_bf16 v[98:101], v[160:163], v[184:187], v[98:101]
	v_mfma_f32_16x16x32_bf16 v[94:97], v[168:171], v[184:187], v[94:97]
	v_mfma_f32_16x16x32_bf16 v[82:85], v[160:163], v[204:207], v[82:85]
	v_mfma_f32_16x16x32_bf16 v[78:81], v[168:171], v[204:207], v[78:81]
	v_mfma_f32_16x16x32_bf16 v[70:73], v[160:163], v[212:215], v[70:73]
	v_mfma_f32_16x16x32_bf16 v[66:69], v[168:171], v[212:215], v[66:69]
	s_setprio 0
	s_barrier
	s_add_i32 s36, s36, s31
	s_mov_b32 m0, s36
	ds_read_b128 v[172:175], v159 offset:16384
	ds_read_b128 v[176:179], v159 offset:17408
	ds_read_b128 v[180:183], v159 offset:18432
	ds_read_b128 v[184:187], v159 offset:19456
	ds_read_b128 v[188:191], v159 offset:20480
	ds_read_b128 v[204:207], v159 offset:21504
	ds_read_b128 v[208:211], v159 offset:22528
	ds_read_b128 v[212:215], v159 offset:23552
	global_load_lds_dwordx4 v0, s[20:21]
	s_add_i32 m0, s36, 0x2000
	s_add_u32 s64, s20, 0x4000
	s_addc_u32 s65, s21, 0
	s_add_i32 s36, s37, s31
	global_load_lds_dwordx4 v142, s[20:21]
	s_mov_b32 m0, s36
	s_nop 0
	global_load_lds_dwordx4 v0, s[64:65]
	s_add_i32 m0, s36, 0x2000
	s_nop 0
	global_load_lds_dwordx4 v142, s[64:65]
	s_mov_b32 m0, s34
	s_nop 0
	global_load_lds_dwordx4 v0, s[22:23]
	s_mov_b32 m0, s35
	s_nop 0
	global_load_lds_dwordx4 v142, s[22:23]
	s_waitcnt vmcnt(8)
	s_waitcnt lgkmcnt(0)
	s_barrier
	s_setprio 1
	s_waitcnt lgkmcnt(0)
	v_mfma_f32_16x16x32_bf16 v[62:65], v[130:133], v[172:175], v[62:65]
	v_mfma_f32_16x16x32_bf16 v[58:61], v[138:141], v[172:175], v[58:61]
	v_mfma_f32_16x16x32_bf16 v[54:57], v[130:133], v[180:183], v[54:57]
	v_mfma_f32_16x16x32_bf16 v[42:45], v[138:141], v[180:183], v[42:45]
	v_mfma_f32_16x16x32_bf16 v[38:41], v[130:133], v[188:191], v[38:41]
	v_mfma_f32_16x16x32_bf16 v[26:29], v[138:141], v[188:191], v[26:29]
	v_mfma_f32_16x16x32_bf16 v[22:25], v[130:133], v[208:211], v[22:25]
	v_mfma_f32_16x16x32_bf16 v[10:13], v[138:141], v[208:211], v[10:13]
	v_mfma_f32_16x16x32_bf16 v[62:65], v[134:137], v[176:179], v[62:65]
	v_mfma_f32_16x16x32_bf16 v[58:61], v[148:151], v[176:179], v[58:61]
	v_mfma_f32_16x16x32_bf16 v[54:57], v[134:137], v[184:187], v[54:57]
	v_mfma_f32_16x16x32_bf16 v[42:45], v[148:151], v[184:187], v[42:45]
	v_mfma_f32_16x16x32_bf16 v[38:41], v[134:137], v[204:207], v[38:41]
	v_mfma_f32_16x16x32_bf16 v[26:29], v[148:151], v[204:207], v[26:29]
	v_mfma_f32_16x16x32_bf16 v[22:25], v[134:137], v[212:215], v[22:25]
	v_mfma_f32_16x16x32_bf16 v[10:13], v[148:151], v[212:215], v[10:13]
	s_setprio 0
	s_setprio 1
	v_mfma_f32_16x16x32_bf16 v[50:53], v[152:155], v[172:175], v[50:53]
	v_mfma_f32_16x16x32_bf16 v[46:49], v[164:167], v[172:175], v[46:49]
	v_mfma_f32_16x16x32_bf16 v[34:37], v[152:155], v[180:183], v[34:37]
	v_mfma_f32_16x16x32_bf16 v[30:33], v[164:167], v[180:183], v[30:33]
	v_mfma_f32_16x16x32_bf16 v[18:21], v[152:155], v[188:191], v[18:21]
	v_mfma_f32_16x16x32_bf16 v[14:17], v[164:167], v[188:191], v[14:17]
	v_mfma_f32_16x16x32_bf16 v[6:9], v[152:155], v[208:211], v[6:9]
	v_mfma_f32_16x16x32_bf16 v[2:5], v[164:167], v[208:211], v[2:5]
	v_mfma_f32_16x16x32_bf16 v[50:53], v[160:163], v[176:179], v[50:53]
	v_mfma_f32_16x16x32_bf16 v[46:49], v[168:171], v[176:179], v[46:49]
	v_mfma_f32_16x16x32_bf16 v[34:37], v[160:163], v[184:187], v[34:37]
	v_mfma_f32_16x16x32_bf16 v[30:33], v[168:171], v[184:187], v[30:33]
	v_mfma_f32_16x16x32_bf16 v[18:21], v[160:163], v[204:207], v[18:21]
	v_mfma_f32_16x16x32_bf16 v[14:17], v[168:171], v[204:207], v[14:17]
	v_mfma_f32_16x16x32_bf16 v[6:9], v[160:163], v[212:215], v[6:9]
	v_mfma_f32_16x16x32_bf16 v[2:5], v[168:171], v[212:215], v[2:5]
	s_setprio 0
	s_barrier
; #define PG8_STAGE(bufoff, gbase, voff) do { _Pragma("unroll") for (int _i = 0; _i < 2; ++_i) \
;         __builtin_amdgcn_global_load_lds((const unsigned*)((const char*)(gbase) + (voff)[_i]), (LAS unsigned*)(lds + (bufoff) + ldsw + _i * 8192), 16, 0, 0); } while (0)
; #define PG8_LDA(dst, b, h) do { _Pragma("unroll") for (int m = 0; m < 4; ++m) _Pragma("unroll") for (int k = 0; k < 2; ++k) dst[m][k] = *(const LAS bf16x8*)(lds + PG8_SA(b, h) + aoff + m * 2048 + k * 1024); } while (0)
; #define PG8_LDB(dst, b, h) do { _Pragma("unroll") for (int n = 0; n < 2; ++n) _Pragma("unroll") for (int k = 0; k < 2; ++k) dst[n][k] = *(const LAS bf16x8*)(lds + PG8_SB(b, h) + boff + n * 2048 + k * 1024); } while (0)
; #define PG8_MMA(ai, bj, At, Bt) do { __builtin_amdgcn_s_setprio(1); _Pragma("unroll") for (int m = 0; m < 4; ++m) _Pragma("unroll") for (int n = 0; n < 2; ++n) _Pragma("unroll") for (int k = 0; k < 2; ++k) \
;         acc[ai][bj][m][n] = __builtin_amdgcn_mfma_f32_16x16x32_bf16(Bt[n][k], At[m][k], acc[ai][bj][m][n], 0, 0, 0); __builtin_amdgcn_s_setprio(0); } while (0)
; #define PG8_WAIT_V(n) asm volatile("s_waitcnt vmcnt(" #n ")" ::: "memory")
; #define PG8_WAIT_L(n) asm volatile("s_waitcnt lgkmcnt(" #n ")" ::: "memory")
; #define PG8_BAR __builtin_amdgcn_s_barrier()
; #define PG8_SCHED __builtin_amdgcn_sched_barrier(0)
; template <class Epi, class Sched>
; __device__ __forceinline__ void gemm_phase(const int tid, LAS unsigned char* lds, const Gemm g, const Sched& S, const Epi& E) {
;     ...
;             PG8_LDB(B0, 1, 0); PG8_LDB(B1, 1, 1); PG8_SCHED; PG8_LDA(At, 1, 0); PG8_STAGE(PG8_SA(0, 1), a2 + hstepA, voffA);
;             PG8_WAIT_V(8); PG8_WAIT_L(0); PG8_BAR; PG8_MMA(0, 0, At, B0); PG8_MMA(0, 1, At, B1); PG8_BAR; PG8_SCHED;
;             PG8_LDA(At, 1, 1); PG8_STAGE(PG8_SB(1, 0), b3, voffB); PG8_STAGE(PG8_SB(1, 1), b3 + hstepB, voffB); PG8_STAGE(PG8_SA(1, 0), a3, voffA);
;             PG8_WAIT_V(8); PG8_WAIT_L(0); PG8_BAR; PG8_MMA(1, 0, At, B0); PG8_MMA(1, 1, At, B1); PG8_BAR; PG8_SCHED;
;         }
;         if (wr == 0) PG8_BAR;
	s_add_i32 s36, 16, 0x18000
	s_add_i32 s37, 16, 0x1c000
	v_add_u32_e32 v148, s36, v157
	v_add_u32_e32 v168, s37, v157
	ds_read_b128 v[130:133], v148
	ds_read_b128 v[134:137], v148 offset:1024
	ds_read_b128 v[138:141], v148 offset:2048
	ds_read_b128 v[148:151], v148 offset:3072
	ds_read_b128 v[152:155], v168
	ds_read_b128 v[160:163], v168 offset:1024
	ds_read_b128 v[164:167], v168 offset:2048
	ds_read_b128 v[168:171], v168 offset:3072
	s_add_u32 s22, s22, 0x4000
	s_addc_u32 s23, s23, 0
	s_mov_b32 m0, s52
	ds_read_b128 v[172:175], v159 offset:32768
	ds_read_b128 v[176:179], v159 offset:33792
	ds_read_b128 v[180:183], v159 offset:34816
	ds_read_b128 v[184:187], v159 offset:35840
	ds_read_b128 v[188:191], v159 offset:36864
	ds_read_b128 v[204:207], v159 offset:37888
	ds_read_b128 v[208:211], v159 offset:38912
	ds_read_b128 v[212:215], v159 offset:39936
	global_load_lds_dwordx4 v0, s[22:23]
	s_mov_b32 m0, s53
	s_nop 0
	global_load_lds_dwordx4 v142, s[22:23]
	s_waitcnt vmcnt(8)
	s_waitcnt lgkmcnt(0)
	s_barrier
	s_setprio 1
	s_waitcnt lgkmcnt(0)
	v_mfma_f32_16x16x32_bf16 v[126:129], v[130:133], v[172:175], v[126:129]
	v_mfma_f32_16x16x32_bf16 v[122:125], v[138:141], v[172:175], v[122:125]
	v_mfma_f32_16x16x32_bf16 v[118:121], v[130:133], v[180:183], v[118:121]
	v_mfma_f32_16x16x32_bf16 v[106:109], v[138:141], v[180:183], v[106:109]
	v_mfma_f32_16x16x32_bf16 v[102:105], v[130:133], v[188:191], v[102:105]
	v_mfma_f32_16x16x32_bf16 v[90:93], v[138:141], v[188:191], v[90:93]
	v_mfma_f32_16x16x32_bf16 v[86:89], v[130:133], v[208:211], v[86:89]
	v_mfma_f32_16x16x32_bf16 v[74:77], v[138:141], v[208:211], v[74:77]
	v_mfma_f32_16x16x32_bf16 v[126:129], v[134:137], v[176:179], v[126:129]
	v_mfma_f32_16x16x32_bf16 v[122:125], v[148:151], v[176:179], v[122:125]
	v_mfma_f32_16x16x32_bf16 v[118:121], v[134:137], v[184:187], v[118:121]
	v_mfma_f32_16x16x32_bf16 v[106:109], v[148:151], v[184:187], v[106:109]
	v_mfma_f32_16x16x32_bf16 v[102:105], v[134:137], v[204:207], v[102:105]
	v_mfma_f32_16x16x32_bf16 v[90:93], v[148:151], v[204:207], v[90:93]
	v_mfma_f32_16x16x32_bf16 v[86:89], v[134:137], v[212:215], v[86:89]
	v_mfma_f32_16x16x32_bf16 v[74:77], v[148:151], v[212:215], v[74:77]
	s_setprio 0
	s_setprio 1
	v_mfma_f32_16x16x32_bf16 v[114:117], v[152:155], v[172:175], v[114:117]
	v_mfma_f32_16x16x32_bf16 v[110:113], v[164:167], v[172:175], v[110:113]
	v_mfma_f32_16x16x32_bf16 v[98:101], v[152:155], v[180:183], v[98:101]
	v_mfma_f32_16x16x32_bf16 v[94:97], v[164:167], v[180:183], v[94:97]
	v_mfma_f32_16x16x32_bf16 v[82:85], v[152:155], v[188:191], v[82:85]
	v_mfma_f32_16x16x32_bf16 v[78:81], v[164:167], v[188:191], v[78:81]
	v_mfma_f32_16x16x32_bf16 v[70:73], v[152:155], v[208:211], v[70:73]
	v_mfma_f32_16x16x32_bf16 v[66:69], v[164:167], v[208:211], v[66:69]
	v_mfma_f32_16x16x32_bf16 v[114:117], v[160:163], v[176:179], v[114:117]
	v_mfma_f32_16x16x32_bf16 v[110:113], v[168:171], v[176:179], v[110:113]
	v_mfma_f32_16x16x32_bf16 v[98:101], v[160:163], v[184:187], v[98:101]
	v_mfma_f32_16x16x32_bf16 v[94:97], v[168:171], v[184:187], v[94:97]
	v_mfma_f32_16x16x32_bf16 v[82:85], v[160:163], v[204:207], v[82:85]
	v_mfma_f32_16x16x32_bf16 v[78:81], v[168:171], v[204:207], v[78:81]
	v_mfma_f32_16x16x32_bf16 v[70:73], v[160:163], v[212:215], v[70:73]
	v_mfma_f32_16x16x32_bf16 v[66:69], v[168:171], v[212:215], v[66:69]
	s_setprio 0
	s_barrier
	s_add_u32 s22, s20, 0x8000
	s_addc_u32 s23, s21, 0
	s_add_i32 s36, s36, s31
	s_mov_b32 m0, s36
	ds_read_b128 v[172:175], v159 offset:49152
	ds_read_b128 v[176:179], v159 offset:50176
	ds_read_b128 v[180:183], v159 offset:51200
	ds_read_b128 v[184:187], v159 offset:52224
	ds_read_b128 v[188:191], v159 offset:53248
	ds_read_b128 v[204:207], v159 offset:54272
	ds_read_b128 v[208:211], v159 offset:55296
	ds_read_b128 v[212:215], v159 offset:56320
	global_load_lds_dwordx4 v0, s[22:23]
	s_add_i32 m0, s36, 0x2000
	s_add_u32 s20, s20, 0xc000
	s_addc_u32 s21, s21, 0
	global_load_lds_dwordx4 v142, s[22:23]
	s_add_i32 s22, s37, s31
	s_mov_b32 m0, s22
	s_nop 0
	global_load_lds_dwordx4 v0, s[20:21]
	s_add_i32 m0, s22, 0x2000
	s_nop 0
	global_load_lds_dwordx4 v142, s[20:21]
	s_mov_b32 m0, s54
	s_nop 0
	global_load_lds_dwordx4 v0, s[18:19]
	s_mov_b32 m0, s55
	s_nop 0
	global_load_lds_dwordx4 v142, s[18:19]
	s_waitcnt vmcnt(8)
	s_waitcnt lgkmcnt(0)
	s_barrier
	s_setprio 1
	s_waitcnt lgkmcnt(0)
	v_mfma_f32_16x16x32_bf16 v[62:65], v[130:133], v[172:175], v[62:65]
	v_mfma_f32_16x16x32_bf16 v[58:61], v[138:141], v[172:175], v[58:61]
	v_mfma_f32_16x16x32_bf16 v[54:57], v[130:133], v[180:183], v[54:57]
	v_mfma_f32_16x16x32_bf16 v[42:45], v[138:141], v[180:183], v[42:45]
	v_mfma_f32_16x16x32_bf16 v[38:41], v[130:133], v[188:191], v[38:41]
	v_mfma_f32_16x16x32_bf16 v[26:29], v[138:141], v[188:191], v[26:29]
	v_mfma_f32_16x16x32_bf16 v[22:25], v[130:133], v[208:211], v[22:25]
	v_mfma_f32_16x16x32_bf16 v[10:13], v[138:141], v[208:211], v[10:13]
	v_mfma_f32_16x16x32_bf16 v[62:65], v[134:137], v[176:179], v[62:65]
	v_mfma_f32_16x16x32_bf16 v[58:61], v[148:151], v[176:179], v[58:61]
	v_mfma_f32_16x16x32_bf16 v[54:57], v[134:137], v[184:187], v[54:57]
	v_mfma_f32_16x16x32_bf16 v[42:45], v[148:151], v[184:187], v[42:45]
	v_mfma_f32_16x16x32_bf16 v[38:41], v[134:137], v[204:207], v[38:41]
	v_mfma_f32_16x16x32_bf16 v[26:29], v[148:151], v[204:207], v[26:29]
	v_mfma_f32_16x16x32_bf16 v[22:25], v[134:137], v[212:215], v[22:25]
	v_mfma_f32_16x16x32_bf16 v[10:13], v[148:151], v[212:215], v[10:13]
	s_setprio 0
	s_setprio 1
	v_mfma_f32_16x16x32_bf16 v[50:53], v[152:155], v[172:175], v[50:53]
	v_mfma_f32_16x16x32_bf16 v[46:49], v[164:167], v[172:175], v[46:49]
	v_mfma_f32_16x16x32_bf16 v[34:37], v[152:155], v[180:183], v[34:37]
	v_mfma_f32_16x16x32_bf16 v[30:33], v[164:167], v[180:183], v[30:33]
	v_mfma_f32_16x16x32_bf16 v[18:21], v[152:155], v[188:191], v[18:21]
	v_mfma_f32_16x16x32_bf16 v[14:17], v[164:167], v[188:191], v[14:17]
	v_mfma_f32_16x16x32_bf16 v[6:9], v[152:155], v[208:211], v[6:9]
	v_mfma_f32_16x16x32_bf16 v[2:5], v[164:167], v[208:211], v[2:5]
	v_mfma_f32_16x16x32_bf16 v[50:53], v[160:163], v[176:179], v[50:53]
	v_mfma_f32_16x16x32_bf16 v[46:49], v[168:171], v[176:179], v[46:49]
	v_mfma_f32_16x16x32_bf16 v[34:37], v[160:163], v[184:187], v[34:37]
	v_mfma_f32_16x16x32_bf16 v[30:33], v[168:171], v[184:187], v[30:33]
	v_mfma_f32_16x16x32_bf16 v[18:21], v[160:163], v[204:207], v[18:21]
	v_mfma_f32_16x16x32_bf16 v[14:17], v[168:171], v[204:207], v[14:17]
	v_mfma_f32_16x16x32_bf16 v[6:9], v[160:163], v[212:215], v[6:9]
	v_mfma_f32_16x16x32_bf16 v[2:5], v[168:171], v[212:215], v[2:5]
	s_setprio 0
	s_barrier
	s_add_i32 s62, s62, 2
	s_add_u32 s60, s60, 0x10000
	s_addc_u32 s61, s61, 0
	s_add_u32 s16, s16, 0x10000
	s_addc_u32 s17, s17, 0
	s_cmp_gt_u32 s62, 29
	s_cbranch_scc0 .LBB0_962
	s_and_b64 vcc, exec, s[2:3]
	s_cbranch_vccz .LBB0_965
	s_barrier

; #define PG8_STAGE(bufoff, gbase, voff) do { _Pragma("unroll") for (int _i = 0; _i < 2; ++_i) \
;         __builtin_amdgcn_global_load_lds((const unsigned*)((const char*)(gbase) + (voff)[_i]), (LAS unsigned*)(lds + (bufoff) + ldsw + _i * 8192), 16, 0, 0); } while (0)
; #define PG8_LDA(dst, b, h) do { _Pragma("unroll") for (int m = 0; m < 4; ++m) _Pragma("unroll") for (int k = 0; k < 2; ++k) dst[m][k] = *(const LAS bf16x8*)(lds + PG8_SA(b, h) + aoff + m * 2048 + k * 1024); } while (0)
; #define PG8_LDB(dst, b, h) do { _Pragma("unroll") for (int n = 0; n < 2; ++n) _Pragma("unroll") for (int k = 0; k < 2; ++k) dst[n][k] = *(const LAS bf16x8*)(lds + PG8_SB(b, h) + boff + n * 2048 + k * 1024); } while (0)
; #define PG8_MMA(ai, bj, At, Bt) do { __builtin_amdgcn_s_setprio(1); _Pragma("unroll") for (int m = 0; m < 4; ++m) _Pragma("unroll") for (int n = 0; n < 2; ++n) _Pragma("unroll") for (int k = 0; k < 2; ++k) \
;         acc[ai][bj][m][n] = __builtin_amdgcn_mfma_f32_16x16x32_bf16(Bt[n][k], At[m][k], acc[ai][bj][m][n], 0, 0, 0); __builtin_amdgcn_s_setprio(0); } while (0)
; #define PG8_WAIT_V(n) asm volatile("s_waitcnt vmcnt(" #n ")" ::: "memory")
; #define PG8_WAIT_L(n) asm volatile("s_waitcnt lgkmcnt(" #n ")" ::: "memory")
; #define PG8_BAR __builtin_amdgcn_s_barrier()
; #define PG8_SCHED __builtin_amdgcn_sched_barrier(0)
; template <class Epi, class Sched>
; __device__ __forceinline__ void gemm_phase(const int tid, LAS unsigned char* lds, const Gemm g, const Sched& S, const Epi& E) {
;     ...
;         for (int t = 0; t < nt; t += 2) {
;             const bool last = (t == nt - 2);
;             const char* a1 = cA + (size_t)(t + 1) * kstepA;
;             const char* a2 = last ? nA : cA + (size_t)(t + 2) * kstepA; const char* b2 = last ? nB : cB + (size_t)(t + 2) * kstepB;
;             const char* a3 = a2 + kstepA; const char* b3 = b2 + kstepB;
;             PG8_LDB(B0, 0, 0); PG8_LDB(B1, 0, 1); PG8_SCHED; PG8_LDA(At, 0, 0); PG8_STAGE(PG8_SA(1, 1), a1 + hstepA, voffA);
;             PG8_WAIT_V(8); PG8_WAIT_L(0); PG8_BAR; PG8_MMA(0, 0, At, B0); PG8_MMA(0, 1, At, B1); PG8_BAR; PG8_SCHED;
;             PG8_LDA(At, 0, 1); PG8_STAGE(PG8_SB(0, 0), b2, voffB); PG8_STAGE(PG8_SB(0, 1), b2 + hstepB, voffB); PG8_STAGE(PG8_SA(0, 0), a2, voffA);
;             PG8_WAIT_V(8); PG8_WAIT_L(0); PG8_BAR; PG8_MMA(1, 0, At, B0); PG8_MMA(1, 1, At, B1); PG8_BAR; PG8_SCHED;
.LBB0_1100:
	s_add_u32 s22, s20, 0x4000
	s_addc_u32 s23, s21, 0
	s_cmp_eq_u32 s76, 28
	s_cselect_b32 s26, s64, s22
	s_cselect_b32 s27, s13, s23
	s_cselect_b32 s24, s65, s66
	s_cselect_b32 s25, s11, s67
	s_add_u32 s22, s26, 0x8000
	s_addc_u32 s23, s27, 0
	s_add_i32 s36, 16, 0x10000
	v_add_u32_e32 v0, s36, v145
	s_add_i32 s37, 16, 0x14000
	ds_read_b128 v[148:151], v0
	ds_read_b128 v[152:155], v0 offset:1024
	ds_read_b128 v[156:159], v0 offset:2048
	ds_read_b128 v[160:163], v0 offset:3072
	v_add_u32_e32 v0, s37, v145
	ds_read_b128 v[164:167], v0
	ds_read_b128 v[168:171], v0 offset:1024
	ds_read_b128 v[172:175], v0 offset:2048
	ds_read_b128 v[176:179], v0 offset:3072
	s_add_i32 m0, s19, 0xc000
	ds_read_b128 v[180:183], v146
	ds_read_b128 v[184:187], v146 offset:1024
	ds_read_b128 v[188:191], v146 offset:2048
	ds_read_b128 v[204:207], v146 offset:3072
	ds_read_b128 v[208:211], v146 offset:4096
	ds_read_b128 v[212:215], v146 offset:5120
	ds_read_b128 v[216:219], v146 offset:6144
	ds_read_b128 v[220:223], v146 offset:7168
	global_load_lds_dwordx4 v140, s[20:21]
	s_add_i32 m0, s19, 0xe000
	s_nop 0
	global_load_lds_dwordx4 v138, s[20:21]
	s_waitcnt vmcnt(8)
	s_waitcnt lgkmcnt(0)
	s_barrier
	s_setprio 1
	s_waitcnt lgkmcnt(0)
	v_mfma_f32_16x16x32_bf16 v[126:129], v[148:151], v[180:183], v[126:129]
	v_mfma_f32_16x16x32_bf16 v[122:125], v[156:159], v[180:183], v[122:125]
	v_mfma_f32_16x16x32_bf16 v[110:113], v[148:151], v[188:191], v[110:113]
	v_mfma_f32_16x16x32_bf16 v[106:109], v[156:159], v[188:191], v[106:109]
	v_mfma_f32_16x16x32_bf16 v[94:97], v[148:151], v[208:211], v[94:97]
	v_mfma_f32_16x16x32_bf16 v[90:93], v[156:159], v[208:211], v[90:93]
	v_mfma_f32_16x16x32_bf16 v[78:81], v[148:151], v[216:219], v[78:81]
	v_mfma_f32_16x16x32_bf16 v[74:77], v[156:159], v[216:219], v[74:77]
	v_mfma_f32_16x16x32_bf16 v[126:129], v[152:155], v[184:187], v[126:129]
	v_mfma_f32_16x16x32_bf16 v[122:125], v[160:163], v[184:187], v[122:125]
	v_mfma_f32_16x16x32_bf16 v[110:113], v[152:155], v[204:207], v[110:113]
	v_mfma_f32_16x16x32_bf16 v[106:109], v[160:163], v[204:207], v[106:109]
	v_mfma_f32_16x16x32_bf16 v[94:97], v[152:155], v[212:215], v[94:97]
	v_mfma_f32_16x16x32_bf16 v[90:93], v[160:163], v[212:215], v[90:93]
	v_mfma_f32_16x16x32_bf16 v[78:81], v[152:155], v[220:223], v[78:81]
	v_mfma_f32_16x16x32_bf16 v[74:77], v[160:163], v[220:223], v[74:77]
	s_setprio 0
	s_setprio 1
	v_mfma_f32_16x16x32_bf16 v[118:121], v[164:167], v[180:183], v[118:121]
	v_mfma_f32_16x16x32_bf16 v[114:117], v[172:175], v[180:183], v[114:117]
	v_mfma_f32_16x16x32_bf16 v[102:105], v[164:167], v[188:191], v[102:105]
	v_mfma_f32_16x16x32_bf16 v[98:101], v[172:175], v[188:191], v[98:101]
	v_mfma_f32_16x16x32_bf16 v[86:89], v[164:167], v[208:211], v[86:89]
	v_mfma_f32_16x16x32_bf16 v[82:85], v[172:175], v[208:211], v[82:85]
	v_mfma_f32_16x16x32_bf16 v[70:73], v[164:167], v[216:219], v[70:73]
	v_mfma_f32_16x16x32_bf16 v[66:69], v[172:175], v[216:219], v[66:69]
	v_mfma_f32_16x16x32_bf16 v[118:121], v[168:171], v[184:187], v[118:121]
	v_mfma_f32_16x16x32_bf16 v[114:117], v[176:179], v[184:187], v[114:117]
	v_mfma_f32_16x16x32_bf16 v[102:105], v[168:171], v[204:207], v[102:105]
	v_mfma_f32_16x16x32_bf16 v[98:101], v[176:179], v[204:207], v[98:101]
	v_mfma_f32_16x16x32_bf16 v[86:89], v[168:171], v[212:215], v[86:89]
	v_mfma_f32_16x16x32_bf16 v[82:85], v[176:179], v[212:215], v[82:85]
	v_mfma_f32_16x16x32_bf16 v[70:73], v[168:171], v[220:223], v[70:73]
	v_mfma_f32_16x16x32_bf16 v[66:69], v[176:179], v[220:223], v[66:69]
	s_setprio 0
	s_barrier
	s_add_i32 s36, s36, s52
	s_mov_b32 m0, s36
	ds_read_b128 v[180:183], v146 offset:16384
	ds_read_b128 v[184:187], v146 offset:17408
	ds_read_b128 v[188:191], v146 offset:18432
	ds_read_b128 v[204:207], v146 offset:19456
	ds_read_b128 v[208:211], v146 offset:20480
	ds_read_b128 v[212:215], v146 offset:21504
	ds_read_b128 v[216:219], v146 offset:22528
	ds_read_b128 v[220:223], v146 offset:23552
	global_load_lds_dwordx4 v134, s[24:25]
	s_add_i32 m0, s36, 0x2000
	s_add_u32 s78, s24, 0x4000
	s_addc_u32 s79, s25, 0
	s_add_i32 s36, s37, s52
	global_load_lds_dwordx4 v130, s[24:25]
	s_mov_b32 m0, s36
	s_nop 0
	global_load_lds_dwordx4 v134, s[78:79]
	s_add_i32 m0, s36, 0x2000
	s_nop 0
	global_load_lds_dwordx4 v130, s[78:79]
	s_mov_b32 m0, s19
	s_nop 0
	global_load_lds_dwordx4 v136, s[26:27]
	s_mov_b32 m0, s54
	s_nop 0
	global_load_lds_dwordx4 v132, s[26:27]
	s_waitcnt vmcnt(8)
	s_waitcnt lgkmcnt(0)
	s_barrier
	s_setprio 1
	s_waitcnt lgkmcnt(0)
	v_mfma_f32_16x16x32_bf16 v[62:65], v[148:151], v[180:183], v[62:65]
	v_mfma_f32_16x16x32_bf16 v[58:61], v[156:159], v[180:183], v[58:61]
	v_mfma_f32_16x16x32_bf16 v[46:49], v[148:151], v[188:191], v[46:49]
	v_mfma_f32_16x16x32_bf16 v[42:45], v[156:159], v[188:191], v[42:45]
	v_mfma_f32_16x16x32_bf16 v[30:33], v[148:151], v[208:211], v[30:33]
	v_mfma_f32_16x16x32_bf16 v[26:29], v[156:159], v[208:211], v[26:29]
	v_mfma_f32_16x16x32_bf16 v[14:17], v[148:151], v[216:219], v[14:17]
	v_mfma_f32_16x16x32_bf16 v[10:13], v[156:159], v[216:219], v[10:13]
	v_mfma_f32_16x16x32_bf16 v[62:65], v[152:155], v[184:187], v[62:65]
	v_mfma_f32_16x16x32_bf16 v[58:61], v[160:163], v[184:187], v[58:61]
	v_mfma_f32_16x16x32_bf16 v[46:49], v[152:155], v[204:207], v[46:49]
	v_mfma_f32_16x16x32_bf16 v[42:45], v[160:163], v[204:207], v[42:45]
	v_mfma_f32_16x16x32_bf16 v[30:33], v[152:155], v[212:215], v[30:33]
	v_mfma_f32_16x16x32_bf16 v[26:29], v[160:163], v[212:215], v[26:29]
	v_mfma_f32_16x16x32_bf16 v[14:17], v[152:155], v[220:223], v[14:17]
	v_mfma_f32_16x16x32_bf16 v[10:13], v[160:163], v[220:223], v[10:13]
	s_setprio 0
	s_setprio 1
	v_mfma_f32_16x16x32_bf16 v[54:57], v[164:167], v[180:183], v[54:57]
	v_mfma_f32_16x16x32_bf16 v[50:53], v[172:175], v[180:183], v[50:53]
	v_mfma_f32_16x16x32_bf16 v[38:41], v[164:167], v[188:191], v[38:41]
	v_mfma_f32_16x16x32_bf16 v[34:37], v[172:175], v[188:191], v[34:37]
	v_mfma_f32_16x16x32_bf16 v[22:25], v[164:167], v[208:211], v[22:25]
	v_mfma_f32_16x16x32_bf16 v[18:21], v[172:175], v[208:211], v[18:21]
	v_mfma_f32_16x16x32_bf16 v[6:9], v[164:167], v[216:219], v[6:9]
	v_mfma_f32_16x16x32_bf16 v[2:5], v[172:175], v[216:219], v[2:5]
	v_mfma_f32_16x16x32_bf16 v[54:57], v[168:171], v[184:187], v[54:57]
	v_mfma_f32_16x16x32_bf16 v[50:53], v[176:179], v[184:187], v[50:53]
	v_mfma_f32_16x16x32_bf16 v[38:41], v[168:171], v[204:207], v[38:41]
	v_mfma_f32_16x16x32_bf16 v[34:37], v[176:179], v[204:207], v[34:37]
	v_mfma_f32_16x16x32_bf16 v[22:25], v[168:171], v[212:215], v[22:25]
	v_mfma_f32_16x16x32_bf16 v[18:21], v[176:179], v[212:215], v[18:21]
	v_mfma_f32_16x16x32_bf16 v[6:9], v[168:171], v[220:223], v[6:9]
	v_mfma_f32_16x16x32_bf16 v[2:5], v[176:179], v[220:223], v[2:5]
	s_setprio 0
	s_barrier
; #define PG8_STAGE(bufoff, gbase, voff) do { _Pragma("unroll") for (int _i = 0; _i < 2; ++_i) \
;         __builtin_amdgcn_global_load_lds((const unsigned*)((const char*)(gbase) + (voff)[_i]), (LAS unsigned*)(lds + (bufoff) + ldsw + _i * 8192), 16, 0, 0); } while (0)
; #define PG8_LDA(dst, b, h) do { _Pragma("unroll") for (int m = 0; m < 4; ++m) _Pragma("unroll") for (int k = 0; k < 2; ++k) dst[m][k] = *(const LAS bf16x8*)(lds + PG8_SA(b, h) + aoff + m * 2048 + k * 1024); } while (0)
; #define PG8_LDB(dst, b, h) do { _Pragma("unroll") for (int n = 0; n < 2; ++n) _Pragma("unroll") for (int k = 0; k < 2; ++k) dst[n][k] = *(const LAS bf16x8*)(lds + PG8_SB(b, h) + boff + n * 2048 + k * 1024); } while (0)
; #define PG8_MMA(ai, bj, At, Bt) do { __builtin_amdgcn_s_setprio(1); _Pragma("unroll") for (int m = 0; m < 4; ++m) _Pragma("unroll") for (int n = 0; n < 2; ++n) _Pragma("unroll") for (int k = 0; k < 2; ++k) \
;         acc[ai][bj][m][n] = __builtin_amdgcn_mfma_f32_16x16x32_bf16(Bt[n][k], At[m][k], acc[ai][bj][m][n], 0, 0, 0); __builtin_amdgcn_s_setprio(0); } while (0)
; #define PG8_WAIT_V(n) asm volatile("s_waitcnt vmcnt(" #n ")" ::: "memory")
; #define PG8_WAIT_L(n) asm volatile("s_waitcnt lgkmcnt(" #n ")" ::: "memory")
; #define PG8_BAR __builtin_amdgcn_s_barrier()
; #define PG8_SCHED __builtin_amdgcn_sched_barrier(0)
; template <class Epi, class Sched>
; __device__ __forceinline__ void gemm_phase(const int tid, LAS unsigned char* lds, const Gemm g, const Sched& S, const Epi& E) {
;     ...
;             PG8_LDB(B0, 1, 0); PG8_LDB(B1, 1, 1); PG8_SCHED; PG8_LDA(At, 1, 0); PG8_STAGE(PG8_SA(0, 1), a2 + hstepA, voffA);
;             PG8_WAIT_V(8); PG8_WAIT_L(0); PG8_BAR; PG8_MMA(0, 0, At, B0); PG8_MMA(0, 1, At, B1); PG8_BAR; PG8_SCHED;
;             PG8_LDA(At, 1, 1); PG8_STAGE(PG8_SB(1, 0), b3, voffB); PG8_STAGE(PG8_SB(1, 1), b3 + hstepB, voffB); PG8_STAGE(PG8_SA(1, 0), a3, voffA);
;             PG8_WAIT_V(8); PG8_WAIT_L(0); PG8_BAR; PG8_MMA(1, 0, At, B0); PG8_MMA(1, 1, At, B1); PG8_BAR; PG8_SCHED;
;         }
;         if (wr == 0) PG8_BAR;
	s_add_i32 s36, 16, 0x18000
	v_add_u32_e32 v0, s36, v145
	s_add_i32 s37, 16, 0x1c000
	ds_read_b128 v[148:151], v0
	ds_read_b128 v[152:155], v0 offset:1024
	ds_read_b128 v[156:159], v0 offset:2048
	ds_read_b128 v[160:163], v0 offset:3072
	v_add_u32_e32 v0, s37, v145
	ds_read_b128 v[164:167], v0
	ds_read_b128 v[168:171], v0 offset:1024
	ds_read_b128 v[172:175], v0 offset:2048
	ds_read_b128 v[176:179], v0 offset:3072
	s_add_u32 s26, s26, 0x4000
	s_addc_u32 s27, s27, 0
	s_mov_b32 m0, s55
	ds_read_b128 v[180:183], v146 offset:32768
	ds_read_b128 v[184:187], v146 offset:33792
	ds_read_b128 v[188:191], v146 offset:34816
	ds_read_b128 v[204:207], v146 offset:35840
	ds_read_b128 v[208:211], v146 offset:36864
	ds_read_b128 v[212:215], v146 offset:37888
	ds_read_b128 v[216:219], v146 offset:38912
	ds_read_b128 v[220:223], v146 offset:39936
	global_load_lds_dwordx4 v136, s[26:27]
	s_mov_b32 m0, s56
	s_nop 0
	global_load_lds_dwordx4 v132, s[26:27]
	s_waitcnt vmcnt(8)
	s_waitcnt lgkmcnt(0)
	s_barrier
	s_setprio 1
	s_waitcnt lgkmcnt(0)
	v_mfma_f32_16x16x32_bf16 v[126:129], v[148:151], v[180:183], v[126:129]
	v_mfma_f32_16x16x32_bf16 v[122:125], v[156:159], v[180:183], v[122:125]
	v_mfma_f32_16x16x32_bf16 v[110:113], v[148:151], v[188:191], v[110:113]
	v_mfma_f32_16x16x32_bf16 v[106:109], v[156:159], v[188:191], v[106:109]
	v_mfma_f32_16x16x32_bf16 v[94:97], v[148:151], v[208:211], v[94:97]
	v_mfma_f32_16x16x32_bf16 v[90:93], v[156:159], v[208:211], v[90:93]
	v_mfma_f32_16x16x32_bf16 v[78:81], v[148:151], v[216:219], v[78:81]
	v_mfma_f32_16x16x32_bf16 v[74:77], v[156:159], v[216:219], v[74:77]
	v_mfma_f32_16x16x32_bf16 v[126:129], v[152:155], v[184:187], v[126:129]
	v_mfma_f32_16x16x32_bf16 v[122:125], v[160:163], v[184:187], v[122:125]
	v_mfma_f32_16x16x32_bf16 v[110:113], v[152:155], v[204:207], v[110:113]
	v_mfma_f32_16x16x32_bf16 v[106:109], v[160:163], v[204:207], v[106:109]
	v_mfma_f32_16x16x32_bf16 v[94:97], v[152:155], v[212:215], v[94:97]
	v_mfma_f32_16x16x32_bf16 v[90:93], v[160:163], v[212:215], v[90:93]
	v_mfma_f32_16x16x32_bf16 v[78:81], v[152:155], v[220:223], v[78:81]
	v_mfma_f32_16x16x32_bf16 v[74:77], v[160:163], v[220:223], v[74:77]
	s_setprio 0
	s_setprio 1
	v_mfma_f32_16x16x32_bf16 v[118:121], v[164:167], v[180:183], v[118:121]
	v_mfma_f32_16x16x32_bf16 v[114:117], v[172:175], v[180:183], v[114:117]
	v_mfma_f32_16x16x32_bf16 v[102:105], v[164:167], v[188:191], v[102:105]
	v_mfma_f32_16x16x32_bf16 v[98:101], v[172:175], v[188:191], v[98:101]
	v_mfma_f32_16x16x32_bf16 v[86:89], v[164:167], v[208:211], v[86:89]
	v_mfma_f32_16x16x32_bf16 v[82:85], v[172:175], v[208:211], v[82:85]
	v_mfma_f32_16x16x32_bf16 v[70:73], v[164:167], v[216:219], v[70:73]
	v_mfma_f32_16x16x32_bf16 v[66:69], v[172:175], v[216:219], v[66:69]
	v_mfma_f32_16x16x32_bf16 v[118:121], v[168:171], v[184:187], v[118:121]
	v_mfma_f32_16x16x32_bf16 v[114:117], v[176:179], v[184:187], v[114:117]
	v_mfma_f32_16x16x32_bf16 v[102:105], v[168:171], v[204:207], v[102:105]
	v_mfma_f32_16x16x32_bf16 v[98:101], v[176:179], v[204:207], v[98:101]
	v_mfma_f32_16x16x32_bf16 v[86:89], v[168:171], v[212:215], v[86:89]
	v_mfma_f32_16x16x32_bf16 v[82:85], v[176:179], v[212:215], v[82:85]
	v_mfma_f32_16x16x32_bf16 v[70:73], v[168:171], v[220:223], v[70:73]
	v_mfma_f32_16x16x32_bf16 v[66:69], v[176:179], v[220:223], v[66:69]
	s_setprio 0
	s_barrier
	s_add_u32 s26, s24, 0x8000
	s_addc_u32 s27, s25, 0
	s_add_i32 s36, s36, s52
	s_mov_b32 m0, s36
	ds_read_b128 v[180:183], v146 offset:49152
	ds_read_b128 v[184:187], v146 offset:50176
	ds_read_b128 v[188:191], v146 offset:51200
	ds_read_b128 v[204:207], v146 offset:52224
	ds_read_b128 v[208:211], v146 offset:53248
	ds_read_b128 v[212:215], v146 offset:54272
	ds_read_b128 v[216:219], v146 offset:55296
	ds_read_b128 v[220:223], v146 offset:56320
	global_load_lds_dwordx4 v134, s[26:27]
	s_add_i32 m0, s36, 0x2000
	s_add_u32 s24, s24, 0xc000
	s_addc_u32 s25, s25, 0
	global_load_lds_dwordx4 v130, s[26:27]
	s_add_i32 s26, s37, s52
	s_mov_b32 m0, s26
	s_nop 0
	global_load_lds_dwordx4 v134, s[24:25]
	s_add_i32 m0, s26, 0x2000
	s_nop 0
	global_load_lds_dwordx4 v130, s[24:25]
	s_mov_b32 m0, s59
	s_nop 0
	global_load_lds_dwordx4 v136, s[22:23]
	s_mov_b32 m0, s60
	s_nop 0
	global_load_lds_dwordx4 v132, s[22:23]
	s_waitcnt vmcnt(8)
	s_waitcnt lgkmcnt(0)
	s_barrier
	s_setprio 1
	s_waitcnt lgkmcnt(0)
	v_mfma_f32_16x16x32_bf16 v[62:65], v[148:151], v[180:183], v[62:65]
	v_mfma_f32_16x16x32_bf16 v[58:61], v[156:159], v[180:183], v[58:61]
	v_mfma_f32_16x16x32_bf16 v[46:49], v[148:151], v[188:191], v[46:49]
	v_mfma_f32_16x16x32_bf16 v[42:45], v[156:159], v[188:191], v[42:45]
	v_mfma_f32_16x16x32_bf16 v[30:33], v[148:151], v[208:211], v[30:33]
	v_mfma_f32_16x16x32_bf16 v[26:29], v[156:159], v[208:211], v[26:29]
	v_mfma_f32_16x16x32_bf16 v[14:17], v[148:151], v[216:219], v[14:17]
	v_mfma_f32_16x16x32_bf16 v[10:13], v[156:159], v[216:219], v[10:13]
	v_mfma_f32_16x16x32_bf16 v[62:65], v[152:155], v[184:187], v[62:65]
	v_mfma_f32_16x16x32_bf16 v[58:61], v[160:163], v[184:187], v[58:61]
	v_mfma_f32_16x16x32_bf16 v[46:49], v[152:155], v[204:207], v[46:49]
	v_mfma_f32_16x16x32_bf16 v[42:45], v[160:163], v[204:207], v[42:45]
	v_mfma_f32_16x16x32_bf16 v[30:33], v[152:155], v[212:215], v[30:33]
	v_mfma_f32_16x16x32_bf16 v[26:29], v[160:163], v[212:215], v[26:29]
	v_mfma_f32_16x16x32_bf16 v[14:17], v[152:155], v[220:223], v[14:17]
	v_mfma_f32_16x16x32_bf16 v[10:13], v[160:163], v[220:223], v[10:13]
	s_setprio 0
	s_setprio 1
	v_mfma_f32_16x16x32_bf16 v[54:57], v[164:167], v[180:183], v[54:57]
	v_mfma_f32_16x16x32_bf16 v[50:53], v[172:175], v[180:183], v[50:53]
	v_mfma_f32_16x16x32_bf16 v[38:41], v[164:167], v[188:191], v[38:41]
	v_mfma_f32_16x16x32_bf16 v[34:37], v[172:175], v[188:191], v[34:37]
	v_mfma_f32_16x16x32_bf16 v[22:25], v[164:167], v[208:211], v[22:25]
	v_mfma_f32_16x16x32_bf16 v[18:21], v[172:175], v[208:211], v[18:21]
	v_mfma_f32_16x16x32_bf16 v[6:9], v[164:167], v[216:219], v[6:9]
	v_mfma_f32_16x16x32_bf16 v[2:5], v[172:175], v[216:219], v[2:5]
	v_mfma_f32_16x16x32_bf16 v[54:57], v[168:171], v[184:187], v[54:57]
	v_mfma_f32_16x16x32_bf16 v[50:53], v[176:179], v[184:187], v[50:53]
	v_mfma_f32_16x16x32_bf16 v[38:41], v[168:171], v[204:207], v[38:41]
	v_mfma_f32_16x16x32_bf16 v[34:37], v[176:179], v[204:207], v[34:37]
	v_mfma_f32_16x16x32_bf16 v[22:25], v[168:171], v[212:215], v[22:25]
	v_mfma_f32_16x16x32_bf16 v[18:21], v[176:179], v[212:215], v[18:21]
	v_mfma_f32_16x16x32_bf16 v[6:9], v[168:171], v[220:223], v[6:9]
	v_mfma_f32_16x16x32_bf16 v[2:5], v[176:179], v[220:223], v[2:5]
	s_setprio 0
	s_barrier
	s_add_i32 s76, s76, 2
	s_add_u32 s66, s66, 0x10000
	s_addc_u32 s67, s67, 0
	s_add_u32 s20, s20, 0x10000
	s_addc_u32 s21, s21, 0
	s_cmp_gt_u32 s76, 29
	s_cbranch_scc0 .LBB0_1100
	s_and_b64 vcc, exec, s[6:7]
	s_cbranch_vccz .LBB0_1103
	s_barrier

; #define PG8_STAGE(bufoff, gbase, voff) do { _Pragma("unroll") for (int _i = 0; _i < 2; ++_i) \
;         __builtin_amdgcn_global_load_lds((const unsigned*)((const char*)(gbase) + (voff)[_i]), (LAS unsigned*)(lds + (bufoff) + ldsw + _i * 8192), 16, 0, 0); } while (0)
; #define PG8_LDA(dst, b, h) do { _Pragma("unroll") for (int m = 0; m < 4; ++m) _Pragma("unroll") for (int k = 0; k < 2; ++k) dst[m][k] = *(const LAS bf16x8*)(lds + PG8_SA(b, h) + aoff + m * 2048 + k * 1024); } while (0)
; #define PG8_LDB(dst, b, h) do { _Pragma("unroll") for (int n = 0; n < 2; ++n) _Pragma("unroll") for (int k = 0; k < 2; ++k) dst[n][k] = *(const LAS bf16x8*)(lds + PG8_SB(b, h) + boff + n * 2048 + k * 1024); } while (0)
; #define PG8_MMA(ai, bj, At, Bt) do { __builtin_amdgcn_s_setprio(1); _Pragma("unroll") for (int m = 0; m < 4; ++m) _Pragma("unroll") for (int n = 0; n < 2; ++n) _Pragma("unroll") for (int k = 0; k < 2; ++k) \
;         acc[ai][bj][m][n] = __builtin_amdgcn_mfma_f32_16x16x32_bf16(Bt[n][k], At[m][k], acc[ai][bj][m][n], 0, 0, 0); __builtin_amdgcn_s_setprio(0); } while (0)
; #define PG8_WAIT_V(n) asm volatile("s_waitcnt vmcnt(" #n ")" ::: "memory")
; #define PG8_WAIT_L(n) asm volatile("s_waitcnt lgkmcnt(" #n ")" ::: "memory")
; #define PG8_BAR __builtin_amdgcn_s_barrier()
; #define PG8_SCHED __builtin_amdgcn_sched_barrier(0)
; template <class Epi, class Sched>
; __device__ __forceinline__ void gemm_phase(const int tid, LAS unsigned char* lds, const Gemm g, const Sched& S, const Epi& E) {
;     ...
;         for (int t = 0; t < nt; t += 2) {
;             const bool last = (t == nt - 2);
;             const char* a1 = cA + (size_t)(t + 1) * kstepA;
;             const char* a2 = last ? nA : cA + (size_t)(t + 2) * kstepA; const char* b2 = last ? nB : cB + (size_t)(t + 2) * kstepB;
;             const char* a3 = a2 + kstepA; const char* b3 = b2 + kstepB;
;             PG8_LDB(B0, 0, 0); PG8_LDB(B1, 0, 1); PG8_SCHED; PG8_LDA(At, 0, 0); PG8_STAGE(PG8_SA(1, 1), a1 + hstepA, voffA);
;             PG8_WAIT_V(8); PG8_WAIT_L(0); PG8_BAR; PG8_MMA(0, 0, At, B0); PG8_MMA(0, 1, At, B1); PG8_BAR; PG8_SCHED;
;             PG8_LDA(At, 0, 1); PG8_STAGE(PG8_SB(0, 0), b2, voffB); PG8_STAGE(PG8_SB(0, 1), b2 + hstepB, voffB); PG8_STAGE(PG8_SA(0, 0), a2, voffA);
;             PG8_WAIT_V(8); PG8_WAIT_L(0); PG8_BAR; PG8_MMA(1, 0, At, B0); PG8_MMA(1, 1, At, B1); PG8_BAR; PG8_SCHED;
.LBB0_1171:
	s_add_u32 s16, s14, 0x4000
	s_addc_u32 s17, s15, 0
	s_cmpk_eq_i32 s62, 0x54
	s_cselect_b32 s20, s6, s16
	s_cselect_b32 s21, s7, s17
	s_cselect_b32 s18, s12, s60
	s_cselect_b32 s19, s13, s61
	s_add_u32 s16, s20, 0x8000
	s_addc_u32 s17, s21, 0
	s_add_i32 s36, 16, 0x10000
	s_add_i32 s37, 16, 0x14000
	v_add_u32_e32 v148, s36, v157
	v_add_u32_e32 v168, s37, v157
	ds_read_b128 v[130:133], v148
	ds_read_b128 v[134:137], v148 offset:1024
	ds_read_b128 v[138:141], v148 offset:2048
	ds_read_b128 v[148:151], v148 offset:3072
	ds_read_b128 v[152:155], v168
	ds_read_b128 v[160:163], v168 offset:1024
	ds_read_b128 v[164:167], v168 offset:2048
	ds_read_b128 v[168:171], v168 offset:3072
	s_add_i32 m0, s30, 0xc000
	ds_read_b128 v[172:175], v159
	ds_read_b128 v[176:179], v159 offset:1024
	ds_read_b128 v[180:183], v159 offset:2048
	ds_read_b128 v[184:187], v159 offset:3072
	ds_read_b128 v[188:191], v159 offset:4096
	ds_read_b128 v[204:207], v159 offset:5120
	ds_read_b128 v[208:211], v159 offset:6144
	ds_read_b128 v[212:215], v159 offset:7168
	global_load_lds_dwordx4 v146, s[14:15]
	s_add_i32 m0, s30, 0xe000
	s_nop 0
	global_load_lds_dwordx4 v144, s[14:15]
	s_waitcnt vmcnt(8)
	s_waitcnt lgkmcnt(0)
	s_barrier
	s_setprio 1
	s_waitcnt lgkmcnt(0)
	v_mfma_f32_16x16x32_bf16 v[126:129], v[130:133], v[172:175], v[126:129]
	v_mfma_f32_16x16x32_bf16 v[122:125], v[138:141], v[172:175], v[122:125]
	v_mfma_f32_16x16x32_bf16 v[118:121], v[130:133], v[180:183], v[118:121]
	v_mfma_f32_16x16x32_bf16 v[106:109], v[138:141], v[180:183], v[106:109]
	v_mfma_f32_16x16x32_bf16 v[102:105], v[130:133], v[188:191], v[102:105]
	v_mfma_f32_16x16x32_bf16 v[90:93], v[138:141], v[188:191], v[90:93]
	v_mfma_f32_16x16x32_bf16 v[86:89], v[130:133], v[208:211], v[86:89]
	v_mfma_f32_16x16x32_bf16 v[74:77], v[138:141], v[208:211], v[74:77]
	v_mfma_f32_16x16x32_bf16 v[126:129], v[134:137], v[176:179], v[126:129]
	v_mfma_f32_16x16x32_bf16 v[122:125], v[148:151], v[176:179], v[122:125]
	v_mfma_f32_16x16x32_bf16 v[118:121], v[134:137], v[184:187], v[118:121]
	v_mfma_f32_16x16x32_bf16 v[106:109], v[148:151], v[184:187], v[106:109]
	v_mfma_f32_16x16x32_bf16 v[102:105], v[134:137], v[204:207], v[102:105]
	v_mfma_f32_16x16x32_bf16 v[90:93], v[148:151], v[204:207], v[90:93]
	v_mfma_f32_16x16x32_bf16 v[86:89], v[134:137], v[212:215], v[86:89]
	v_mfma_f32_16x16x32_bf16 v[74:77], v[148:151], v[212:215], v[74:77]
	s_setprio 0
	s_setprio 1
	v_mfma_f32_16x16x32_bf16 v[114:117], v[152:155], v[172:175], v[114:117]
	v_mfma_f32_16x16x32_bf16 v[110:113], v[164:167], v[172:175], v[110:113]
	v_mfma_f32_16x16x32_bf16 v[98:101], v[152:155], v[180:183], v[98:101]
	v_mfma_f32_16x16x32_bf16 v[94:97], v[164:167], v[180:183], v[94:97]
	v_mfma_f32_16x16x32_bf16 v[82:85], v[152:155], v[188:191], v[82:85]
	v_mfma_f32_16x16x32_bf16 v[78:81], v[164:167], v[188:191], v[78:81]
	v_mfma_f32_16x16x32_bf16 v[70:73], v[152:155], v[208:211], v[70:73]
	v_mfma_f32_16x16x32_bf16 v[66:69], v[164:167], v[208:211], v[66:69]
	v_mfma_f32_16x16x32_bf16 v[114:117], v[160:163], v[176:179], v[114:117]
	v_mfma_f32_16x16x32_bf16 v[110:113], v[168:171], v[176:179], v[110:113]
	v_mfma_f32_16x16x32_bf16 v[98:101], v[160:163], v[184:187], v[98:101]
	v_mfma_f32_16x16x32_bf16 v[94:97], v[168:171], v[184:187], v[94:97]
	v_mfma_f32_16x16x32_bf16 v[82:85], v[160:163], v[204:207], v[82:85]
	v_mfma_f32_16x16x32_bf16 v[78:81], v[168:171], v[204:207], v[78:81]
	v_mfma_f32_16x16x32_bf16 v[70:73], v[160:163], v[212:215], v[70:73]
	v_mfma_f32_16x16x32_bf16 v[66:69], v[168:171], v[212:215], v[66:69]
	s_setprio 0
	s_barrier
	s_add_i32 s36, s36, s29
	s_mov_b32 m0, s36
	ds_read_b128 v[172:175], v159 offset:16384
	ds_read_b128 v[176:179], v159 offset:17408
	ds_read_b128 v[180:183], v159 offset:18432
	ds_read_b128 v[184:187], v159 offset:19456
	ds_read_b128 v[188:191], v159 offset:20480
	ds_read_b128 v[204:207], v159 offset:21504
	ds_read_b128 v[208:211], v159 offset:22528
	ds_read_b128 v[212:215], v159 offset:23552
	global_load_lds_dwordx4 v0, s[18:19]
	s_add_i32 m0, s36, 0x2000
	s_add_u32 s64, s18, 0x4000
	s_addc_u32 s65, s19, 0
	s_add_i32 s36, s37, s29
	global_load_lds_dwordx4 v142, s[18:19]
	s_mov_b32 m0, s36
	s_nop 0
	global_load_lds_dwordx4 v0, s[64:65]
	s_add_i32 m0, s36, 0x2000
	s_nop 0
	global_load_lds_dwordx4 v142, s[64:65]
	s_mov_b32 m0, s30
	s_nop 0
	global_load_lds_dwordx4 v0, s[20:21]
	s_mov_b32 m0, s31
	s_nop 0
	global_load_lds_dwordx4 v142, s[20:21]
	s_waitcnt vmcnt(8)
	s_waitcnt lgkmcnt(0)
	s_barrier
	s_setprio 1
	s_waitcnt lgkmcnt(0)
	v_mfma_f32_16x16x32_bf16 v[62:65], v[130:133], v[172:175], v[62:65]
	v_mfma_f32_16x16x32_bf16 v[58:61], v[138:141], v[172:175], v[58:61]
	v_mfma_f32_16x16x32_bf16 v[54:57], v[130:133], v[180:183], v[54:57]
	v_mfma_f32_16x16x32_bf16 v[42:45], v[138:141], v[180:183], v[42:45]
	v_mfma_f32_16x16x32_bf16 v[38:41], v[130:133], v[188:191], v[38:41]
	v_mfma_f32_16x16x32_bf16 v[26:29], v[138:141], v[188:191], v[26:29]
	v_mfma_f32_16x16x32_bf16 v[22:25], v[130:133], v[208:211], v[22:25]
	v_mfma_f32_16x16x32_bf16 v[10:13], v[138:141], v[208:211], v[10:13]
	v_mfma_f32_16x16x32_bf16 v[62:65], v[134:137], v[176:179], v[62:65]
	v_mfma_f32_16x16x32_bf16 v[58:61], v[148:151], v[176:179], v[58:61]
	v_mfma_f32_16x16x32_bf16 v[54:57], v[134:137], v[184:187], v[54:57]
	v_mfma_f32_16x16x32_bf16 v[42:45], v[148:151], v[184:187], v[42:45]
	v_mfma_f32_16x16x32_bf16 v[38:41], v[134:137], v[204:207], v[38:41]
	v_mfma_f32_16x16x32_bf16 v[26:29], v[148:151], v[204:207], v[26:29]
	v_mfma_f32_16x16x32_bf16 v[22:25], v[134:137], v[212:215], v[22:25]
	v_mfma_f32_16x16x32_bf16 v[10:13], v[148:151], v[212:215], v[10:13]
	s_setprio 0
	s_setprio 1
	v_mfma_f32_16x16x32_bf16 v[50:53], v[152:155], v[172:175], v[50:53]
	v_mfma_f32_16x16x32_bf16 v[46:49], v[164:167], v[172:175], v[46:49]
	v_mfma_f32_16x16x32_bf16 v[34:37], v[152:155], v[180:183], v[34:37]
	v_mfma_f32_16x16x32_bf16 v[30:33], v[164:167], v[180:183], v[30:33]
	v_mfma_f32_16x16x32_bf16 v[18:21], v[152:155], v[188:191], v[18:21]
	v_mfma_f32_16x16x32_bf16 v[14:17], v[164:167], v[188:191], v[14:17]
	v_mfma_f32_16x16x32_bf16 v[6:9], v[152:155], v[208:211], v[6:9]
	v_mfma_f32_16x16x32_bf16 v[2:5], v[164:167], v[208:211], v[2:5]
	v_mfma_f32_16x16x32_bf16 v[50:53], v[160:163], v[176:179], v[50:53]
	v_mfma_f32_16x16x32_bf16 v[46:49], v[168:171], v[176:179], v[46:49]
	v_mfma_f32_16x16x32_bf16 v[34:37], v[160:163], v[184:187], v[34:37]
	v_mfma_f32_16x16x32_bf16 v[30:33], v[168:171], v[184:187], v[30:33]
	v_mfma_f32_16x16x32_bf16 v[18:21], v[160:163], v[204:207], v[18:21]
	v_mfma_f32_16x16x32_bf16 v[14:17], v[168:171], v[204:207], v[14:17]
	v_mfma_f32_16x16x32_bf16 v[6:9], v[160:163], v[212:215], v[6:9]
	v_mfma_f32_16x16x32_bf16 v[2:5], v[168:171], v[212:215], v[2:5]
	s_setprio 0
	s_barrier
; #define PG8_STAGE(bufoff, gbase, voff) do { _Pragma("unroll") for (int _i = 0; _i < 2; ++_i) \
;         __builtin_amdgcn_global_load_lds((const unsigned*)((const char*)(gbase) + (voff)[_i]), (LAS unsigned*)(lds + (bufoff) + ldsw + _i * 8192), 16, 0, 0); } while (0)
; #define PG8_LDA(dst, b, h) do { _Pragma("unroll") for (int m = 0; m < 4; ++m) _Pragma("unroll") for (int k = 0; k < 2; ++k) dst[m][k] = *(const LAS bf16x8*)(lds + PG8_SA(b, h) + aoff + m * 2048 + k * 1024); } while (0)
; #define PG8_LDB(dst, b, h) do { _Pragma("unroll") for (int n = 0; n < 2; ++n) _Pragma("unroll") for (int k = 0; k < 2; ++k) dst[n][k] = *(const LAS bf16x8*)(lds + PG8_SB(b, h) + boff + n * 2048 + k * 1024); } while (0)
; #define PG8_MMA(ai, bj, At, Bt) do { __builtin_amdgcn_s_setprio(1); _Pragma("unroll") for (int m = 0; m < 4; ++m) _Pragma("unroll") for (int n = 0; n < 2; ++n) _Pragma("unroll") for (int k = 0; k < 2; ++k) \
;         acc[ai][bj][m][n] = __builtin_amdgcn_mfma_f32_16x16x32_bf16(Bt[n][k], At[m][k], acc[ai][bj][m][n], 0, 0, 0); __builtin_amdgcn_s_setprio(0); } while (0)
; #define PG8_WAIT_V(n) asm volatile("s_waitcnt vmcnt(" #n ")" ::: "memory")
; #define PG8_WAIT_L(n) asm volatile("s_waitcnt lgkmcnt(" #n ")" ::: "memory")
; #define PG8_BAR __builtin_amdgcn_s_barrier()
; #define PG8_SCHED __builtin_amdgcn_sched_barrier(0)
; template <class Epi, class Sched>
; __device__ __forceinline__ void gemm_phase(const int tid, LAS unsigned char* lds, const Gemm g, const Sched& S, const Epi& E) {
;     ...
;             PG8_LDB(B0, 1, 0); PG8_LDB(B1, 1, 1); PG8_SCHED; PG8_LDA(At, 1, 0); PG8_STAGE(PG8_SA(0, 1), a2 + hstepA, voffA);
;             PG8_WAIT_V(8); PG8_WAIT_L(0); PG8_BAR; PG8_MMA(0, 0, At, B0); PG8_MMA(0, 1, At, B1); PG8_BAR; PG8_SCHED;
;             PG8_LDA(At, 1, 1); PG8_STAGE(PG8_SB(1, 0), b3, voffB); PG8_STAGE(PG8_SB(1, 1), b3 + hstepB, voffB); PG8_STAGE(PG8_SA(1, 0), a3, voffA);
;             PG8_WAIT_V(8); PG8_WAIT_L(0); PG8_BAR; PG8_MMA(1, 0, At, B0); PG8_MMA(1, 1, At, B1); PG8_BAR; PG8_SCHED;
;         }
;         if (wr == 0) PG8_BAR;
	s_add_i32 s36, 16, 0x18000
	s_add_i32 s37, 16, 0x1c000
	v_add_u32_e32 v148, s36, v157
	v_add_u32_e32 v168, s37, v157
	ds_read_b128 v[130:133], v148
	ds_read_b128 v[134:137], v148 offset:1024
	ds_read_b128 v[138:141], v148 offset:2048
	ds_read_b128 v[148:151], v148 offset:3072
	ds_read_b128 v[152:155], v168
	ds_read_b128 v[160:163], v168 offset:1024
	ds_read_b128 v[164:167], v168 offset:2048
	ds_read_b128 v[168:171], v168 offset:3072
	s_add_u32 s20, s20, 0x4000
	s_addc_u32 s21, s21, 0
	s_mov_b32 m0, s34
	ds_read_b128 v[172:175], v159 offset:32768
	ds_read_b128 v[176:179], v159 offset:33792
	ds_read_b128 v[180:183], v159 offset:34816
	ds_read_b128 v[184:187], v159 offset:35840
	ds_read_b128 v[188:191], v159 offset:36864
	ds_read_b128 v[204:207], v159 offset:37888
	ds_read_b128 v[208:211], v159 offset:38912
	ds_read_b128 v[212:215], v159 offset:39936
	global_load_lds_dwordx4 v0, s[20:21]
	s_mov_b32 m0, s35
	s_nop 0
	global_load_lds_dwordx4 v142, s[20:21]
	s_waitcnt vmcnt(8)
	s_waitcnt lgkmcnt(0)
	s_barrier
	s_setprio 1
	s_waitcnt lgkmcnt(0)
	v_mfma_f32_16x16x32_bf16 v[126:129], v[130:133], v[172:175], v[126:129]
	v_mfma_f32_16x16x32_bf16 v[122:125], v[138:141], v[172:175], v[122:125]
	v_mfma_f32_16x16x32_bf16 v[118:121], v[130:133], v[180:183], v[118:121]
	v_mfma_f32_16x16x32_bf16 v[106:109], v[138:141], v[180:183], v[106:109]
	v_mfma_f32_16x16x32_bf16 v[102:105], v[130:133], v[188:191], v[102:105]
	v_mfma_f32_16x16x32_bf16 v[90:93], v[138:141], v[188:191], v[90:93]
	v_mfma_f32_16x16x32_bf16 v[86:89], v[130:133], v[208:211], v[86:89]
	v_mfma_f32_16x16x32_bf16 v[74:77], v[138:141], v[208:211], v[74:77]
	v_mfma_f32_16x16x32_bf16 v[126:129], v[134:137], v[176:179], v[126:129]
	v_mfma_f32_16x16x32_bf16 v[122:125], v[148:151], v[176:179], v[122:125]
	v_mfma_f32_16x16x32_bf16 v[118:121], v[134:137], v[184:187], v[118:121]
	v_mfma_f32_16x16x32_bf16 v[106:109], v[148:151], v[184:187], v[106:109]
	v_mfma_f32_16x16x32_bf16 v[102:105], v[134:137], v[204:207], v[102:105]
	v_mfma_f32_16x16x32_bf16 v[90:93], v[148:151], v[204:207], v[90:93]
	v_mfma_f32_16x16x32_bf16 v[86:89], v[134:137], v[212:215], v[86:89]
	v_mfma_f32_16x16x32_bf16 v[74:77], v[148:151], v[212:215], v[74:77]
	s_setprio 0
	s_setprio 1
	v_mfma_f32_16x16x32_bf16 v[114:117], v[152:155], v[172:175], v[114:117]
	v_mfma_f32_16x16x32_bf16 v[110:113], v[164:167], v[172:175], v[110:113]
	v_mfma_f32_16x16x32_bf16 v[98:101], v[152:155], v[180:183], v[98:101]
	v_mfma_f32_16x16x32_bf16 v[94:97], v[164:167], v[180:183], v[94:97]
	v_mfma_f32_16x16x32_bf16 v[82:85], v[152:155], v[188:191], v[82:85]
	v_mfma_f32_16x16x32_bf16 v[78:81], v[164:167], v[188:191], v[78:81]
	v_mfma_f32_16x16x32_bf16 v[70:73], v[152:155], v[208:211], v[70:73]
	v_mfma_f32_16x16x32_bf16 v[66:69], v[164:167], v[208:211], v[66:69]
	v_mfma_f32_16x16x32_bf16 v[114:117], v[160:163], v[176:179], v[114:117]
	v_mfma_f32_16x16x32_bf16 v[110:113], v[168:171], v[176:179], v[110:113]
	v_mfma_f32_16x16x32_bf16 v[98:101], v[160:163], v[184:187], v[98:101]
	v_mfma_f32_16x16x32_bf16 v[94:97], v[168:171], v[184:187], v[94:97]
	v_mfma_f32_16x16x32_bf16 v[82:85], v[160:163], v[204:207], v[82:85]
	v_mfma_f32_16x16x32_bf16 v[78:81], v[168:171], v[204:207], v[78:81]
	v_mfma_f32_16x16x32_bf16 v[70:73], v[160:163], v[212:215], v[70:73]
	v_mfma_f32_16x16x32_bf16 v[66:69], v[168:171], v[212:215], v[66:69]
	s_setprio 0
	s_barrier
	s_add_u32 s20, s18, 0x8000
	s_addc_u32 s21, s19, 0
	s_add_i32 s36, s36, s29
	s_mov_b32 m0, s36
	ds_read_b128 v[172:175], v159 offset:49152
	ds_read_b128 v[176:179], v159 offset:50176
	ds_read_b128 v[180:183], v159 offset:51200
	ds_read_b128 v[184:187], v159 offset:52224
	ds_read_b128 v[188:191], v159 offset:53248
	ds_read_b128 v[204:207], v159 offset:54272
	ds_read_b128 v[208:211], v159 offset:55296
	ds_read_b128 v[212:215], v159 offset:56320
	global_load_lds_dwordx4 v0, s[20:21]
	s_add_i32 m0, s36, 0x2000
	s_add_u32 s18, s18, 0xc000
	s_addc_u32 s19, s19, 0
	global_load_lds_dwordx4 v142, s[20:21]
	s_add_i32 s20, s37, s29
	s_mov_b32 m0, s20
	s_nop 0
	global_load_lds_dwordx4 v0, s[18:19]
	s_add_i32 m0, s20, 0x2000
	s_nop 0
	global_load_lds_dwordx4 v142, s[18:19]
	s_mov_b32 m0, s53
	s_nop 0
	global_load_lds_dwordx4 v0, s[16:17]
	s_mov_b32 m0, s54
	s_nop 0
	global_load_lds_dwordx4 v142, s[16:17]
	s_waitcnt vmcnt(8)
	s_waitcnt lgkmcnt(0)
	s_barrier
	s_setprio 1
	s_waitcnt lgkmcnt(0)
	v_mfma_f32_16x16x32_bf16 v[62:65], v[130:133], v[172:175], v[62:65]
	v_mfma_f32_16x16x32_bf16 v[58:61], v[138:141], v[172:175], v[58:61]
	v_mfma_f32_16x16x32_bf16 v[54:57], v[130:133], v[180:183], v[54:57]
	v_mfma_f32_16x16x32_bf16 v[42:45], v[138:141], v[180:183], v[42:45]
	v_mfma_f32_16x16x32_bf16 v[38:41], v[130:133], v[188:191], v[38:41]
	v_mfma_f32_16x16x32_bf16 v[26:29], v[138:141], v[188:191], v[26:29]
	v_mfma_f32_16x16x32_bf16 v[22:25], v[130:133], v[208:211], v[22:25]
	v_mfma_f32_16x16x32_bf16 v[10:13], v[138:141], v[208:211], v[10:13]
	v_mfma_f32_16x16x32_bf16 v[62:65], v[134:137], v[176:179], v[62:65]
	v_mfma_f32_16x16x32_bf16 v[58:61], v[148:151], v[176:179], v[58:61]
	v_mfma_f32_16x16x32_bf16 v[54:57], v[134:137], v[184:187], v[54:57]
	v_mfma_f32_16x16x32_bf16 v[42:45], v[148:151], v[184:187], v[42:45]
	v_mfma_f32_16x16x32_bf16 v[38:41], v[134:137], v[204:207], v[38:41]
	v_mfma_f32_16x16x32_bf16 v[26:29], v[148:151], v[204:207], v[26:29]
	v_mfma_f32_16x16x32_bf16 v[22:25], v[134:137], v[212:215], v[22:25]
	v_mfma_f32_16x16x32_bf16 v[10:13], v[148:151], v[212:215], v[10:13]
	s_setprio 0
	s_setprio 1
	v_mfma_f32_16x16x32_bf16 v[50:53], v[152:155], v[172:175], v[50:53]
	v_mfma_f32_16x16x32_bf16 v[46:49], v[164:167], v[172:175], v[46:49]
	v_mfma_f32_16x16x32_bf16 v[34:37], v[152:155], v[180:183], v[34:37]
	v_mfma_f32_16x16x32_bf16 v[30:33], v[164:167], v[180:183], v[30:33]
	v_mfma_f32_16x16x32_bf16 v[18:21], v[152:155], v[188:191], v[18:21]
	v_mfma_f32_16x16x32_bf16 v[14:17], v[164:167], v[188:191], v[14:17]
	v_mfma_f32_16x16x32_bf16 v[6:9], v[152:155], v[208:211], v[6:9]
	v_mfma_f32_16x16x32_bf16 v[2:5], v[164:167], v[208:211], v[2:5]
	v_mfma_f32_16x16x32_bf16 v[50:53], v[160:163], v[176:179], v[50:53]
	v_mfma_f32_16x16x32_bf16 v[46:49], v[168:171], v[176:179], v[46:49]
	v_mfma_f32_16x16x32_bf16 v[34:37], v[160:163], v[184:187], v[34:37]
	v_mfma_f32_16x16x32_bf16 v[30:33], v[168:171], v[184:187], v[30:33]
	v_mfma_f32_16x16x32_bf16 v[18:21], v[160:163], v[204:207], v[18:21]
	v_mfma_f32_16x16x32_bf16 v[14:17], v[168:171], v[204:207], v[14:17]
	v_mfma_f32_16x16x32_bf16 v[6:9], v[160:163], v[212:215], v[6:9]
	v_mfma_f32_16x16x32_bf16 v[2:5], v[168:171], v[212:215], v[2:5]
	s_setprio 0
	s_barrier
	s_add_i32 s62, s62, 2
	s_add_u32 s60, s60, 0x10000
	s_addc_u32 s61, s61, 0
	s_add_u32 s14, s14, 0x10000
	s_addc_u32 s15, s15, 0
	s_cmpk_gt_u32 s62, 0x55
	s_cbranch_scc0 .LBB0_1171
	s_and_b64 vcc, exec, s[10:11]
	s_cbranch_vccz .LBB0_1174
	s_barrier
